# RG-LRU gate clusters without s_setprio (phase is VALU-issue bound; test whether the MFMA-wave priority still helps)
# baseline (speedup 1.0000x reference)
.LBB0_263:
.LBB0_264:
	s_and_b32 s65, s96, 63
	s_ashr_i32 s64, s20, 6
	s_lshl_b32 s4, s65, 8
	s_lshl_b32 s5, s64, 5
	v_and_b32_e32 v93, 31, v90
	s_add_i32 s12, s5, s4
	v_or_b32_e32 v9, s12, v93
	v_add_u32_e32 v0, -2, v9
	v_cmp_gt_u32_e32 vcc, s84, v0
	v_bfe_u32 v92, v90, 5, 1
	s_lshl_b32 s20, s73, 1
	v_cndmask_b32_e32 v2, v9, v0, vcc
	v_mov_b64_e32 v[0:1], s[52:53]
	v_mad_i64_i32 v[2:3], s[4:5], v2, s85, v[0:1]
	v_lshl_add_u64 v[2:3], v[2:3], 0, s[20:21]
	v_lshlrev_b32_e32 v88, 4, v92
	v_lshl_add_u64 v[4:5], v[2:3], 0, v[88:89]
	v_add_co_u32_e64 v2, s[4:5], s86, v4
	s_waitcnt lgkmcnt(0)
	s_nop 0
	v_addc_co_u32_e64 v3, s[4:5], 0, v5, s[4:5]
	s_barrier
	global_load_dwordx4 v[10:13], v[2:3], off offset:1024
	global_load_dwordx4 v[178:181], v[2:3], off offset:1056
	global_load_dwordx4 v[194:197], v[2:3], off offset:1088
	global_load_dwordx4 v[210:213], v[2:3], off offset:1120
	global_load_dwordx4 v[226:229], v[2:3], off offset:1152
	global_load_dwordx4 v[242:245], v[2:3], off offset:1184
	v_add_u32_e32 v2, -1, v9
	v_cmp_gt_u32_e64 s[4:5], s84, v2
	v_add_u32_e32 v18, 1, v9
	s_cmpk_lt_u32 s12, 0x4000
	v_cndmask_b32_e64 v2, v9, v2, s[4:5]
	v_mad_i64_i32 v[2:3], s[6:7], v2, s85, v[0:1]
	v_lshl_add_u64 v[2:3], v[2:3], 0, s[20:21]
	v_lshl_add_u64 v[2:3], v[2:3], 0, v[88:89]
	v_add_co_u32_e64 v6, s[6:7], s86, v2
	v_lshlrev_b32_e32 v91, 8, v93
	s_nop 0
	v_addc_co_u32_e64 v7, s[6:7], 0, v3, s[6:7]
	global_load_dwordx4 v[14:17], v[6:7], off offset:1024
	global_load_dwordx4 v[182:185], v[6:7], off offset:1056
	global_load_dwordx4 v[198:201], v[6:7], off offset:1088
	global_load_dwordx4 v[214:217], v[6:7], off offset:1120
	global_load_dwordx4 v[230:233], v[6:7], off offset:1152
	global_load_dwordx4 v[246:249], v[6:7], off offset:1184
	v_mad_i64_i32 v[6:7], s[6:7], v9, s85, v[0:1]
	v_cmp_gt_u32_e64 s[6:7], s84, v18
	v_lshl_add_u64 v[6:7], v[6:7], 0, s[20:21]
	v_lshl_add_u64 v[52:53], v[6:7], 0, v[88:89]
	v_cndmask_b32_e64 v9, v9, v18, s[6:7]
	v_mad_i64_i32 v[0:1], s[8:9], v9, s85, v[0:1]
	v_add_co_u32_e64 v6, s[8:9], s86, v52
	v_lshl_add_u64 v[0:1], v[0:1], 0, s[20:21]
	s_nop 0
	v_addc_co_u32_e64 v7, s[8:9], 0, v53, s[8:9]
	global_load_dwordx4 v[18:21], v[6:7], off offset:1024
	global_load_dwordx4 v[186:189], v[6:7], off offset:1056
	global_load_dwordx4 v[202:205], v[6:7], off offset:1088
	global_load_dwordx4 v[218:221], v[6:7], off offset:1120
	global_load_dwordx4 v[234:237], v[6:7], off offset:1152
	global_load_dwordx4 v[252:255], v[6:7], off offset:1184
	v_lshl_add_u64 v[6:7], v[0:1], 0, v[88:89]
	v_add_co_u32_e64 v0, s[8:9], s86, v6
	v_lshl_add_u32 v9, v92, 5, 16
	s_nop 0
	v_addc_co_u32_e64 v1, s[8:9], 0, v7, s[8:9]
	global_load_dwordx4 v[22:25], v[0:1], off offset:1024
	global_load_dwordx4 v[190:193], v[0:1], off offset:1056
	global_load_dwordx4 v[206:209], v[0:1], off offset:1088
	global_load_dwordx4 v[222:225], v[0:1], off offset:1120
	global_load_dwordx4 v[238:241], v[0:1], off offset:1152
	global_load_dwordx4 v[168:171], v[0:1], off offset:1184
	s_waitcnt vmcnt(26)
	s_waitcnt lgkmcnt(4)
	v_lshl_add_u64 v[0:1], v[4:5], 0, s[38:39]
	s_cselect_b64 s[8:9], -1, 0
	v_lshl_add_u64 v[6:7], v[6:7], 0, s[38:39]
	v_or_b32_e32 v138, s73, v93
	v_and_b32_e32 v8, 0x70, v8
	v_add_u32_e32 v94, 16, v91
	s_waitcnt vmcnt(23)
	s_waitcnt vmcnt(17)
	s_waitcnt lgkmcnt(3)
	s_waitcnt lgkmcnt(1)
	s_waitcnt lgkmcnt(0)
	s_waitcnt vmcnt(11)
	s_waitcnt vmcnt(5)
	ds_read_b128 v[26:29], v9 offset:10240
	ds_read_b128 v[30:33], v9 offset:10256
	ds_read_b128 v[34:37], v9 offset:8192
	ds_read_b128 v[38:41], v9 offset:8208
	ds_read_b128 v[42:45], v9 offset:8704
	ds_read_b128 v[80:83], v9 offset:8720
	s_mov_b64 exec, vcc
	v_lshlrev_b32_e32 v4, 16, v10
	v_and_b32_e32 v5, 0xffff0000, v10
	v_lshlrev_b32_e32 v46, 16, v11
	v_and_b32_e32 v47, 0xffff0000, v11
	s_waitcnt lgkmcnt(2)
	v_pk_fma_f32 v[26:27], v[34:35], v[4:5], v[26:27]
	v_pk_fma_f32 v[28:29], v[36:37], v[46:47], v[28:29]
	v_lshlrev_b32_e32 v84, 16, v12
	v_and_b32_e32 v85, 0xffff0000, v12
	v_lshlrev_b32_e32 v86, 16, v13
	v_and_b32_e32 v87, 0xffff0000, v13
	v_pk_fma_f32 v[30:31], v[38:39], v[84:85], v[30:31]
	v_pk_fma_f32 v[32:33], v[40:41], v[86:87], v[32:33]
	s_mov_b64 exec, -1
	ds_read_b128 v[34:37], v9 offset:9216
	ds_read_b128 v[38:41], v9 offset:9232
	s_mov_b64 exec, s[4:5]
	v_lshlrev_b32_e32 v4, 16, v14
	v_and_b32_e32 v5, 0xffff0000, v14
	v_lshlrev_b32_e32 v46, 16, v15
	v_and_b32_e32 v47, 0xffff0000, v15
	s_waitcnt lgkmcnt(2)
	v_pk_fma_f32 v[26:27], v[42:43], v[4:5], v[26:27]
	v_pk_fma_f32 v[28:29], v[44:45], v[46:47], v[28:29]
	v_lshlrev_b32_e32 v84, 16, v16
	v_and_b32_e32 v85, 0xffff0000, v16
	v_lshlrev_b32_e32 v86, 16, v17
	v_and_b32_e32 v87, 0xffff0000, v17
	v_pk_fma_f32 v[30:31], v[80:81], v[84:85], v[30:31]
	v_pk_fma_f32 v[32:33], v[82:83], v[86:87], v[32:33]
	s_mov_b64 exec, -1
	ds_read_b128 v[42:45], v9 offset:9728
	ds_read_b128 v[80:83], v9 offset:9744
	v_lshlrev_b32_e32 v4, 16, v18
	v_and_b32_e32 v5, 0xffff0000, v18
	v_lshlrev_b32_e32 v46, 16, v19
	v_and_b32_e32 v47, 0xffff0000, v19
	s_waitcnt lgkmcnt(2)
	v_pk_fma_f32 v[26:27], v[34:35], v[4:5], v[26:27]
	v_pk_fma_f32 v[28:29], v[36:37], v[46:47], v[28:29]
	v_lshlrev_b32_e32 v84, 16, v20
	v_and_b32_e32 v85, 0xffff0000, v20
	v_lshlrev_b32_e32 v86, 16, v21
	v_and_b32_e32 v87, 0xffff0000, v21
	v_pk_fma_f32 v[30:31], v[38:39], v[84:85], v[30:31]
	v_pk_fma_f32 v[32:33], v[40:41], v[86:87], v[32:33]
	s_mov_b64 exec, s[6:7]
	v_lshlrev_b32_e32 v4, 16, v22
	v_and_b32_e32 v5, 0xffff0000, v22
	v_lshlrev_b32_e32 v46, 16, v23
	v_and_b32_e32 v47, 0xffff0000, v23
	s_waitcnt lgkmcnt(0)
	v_pk_fma_f32 v[26:27], v[42:43], v[4:5], v[26:27]
	v_pk_fma_f32 v[28:29], v[44:45], v[46:47], v[28:29]
	v_lshlrev_b32_e32 v84, 16, v24
	v_and_b32_e32 v85, 0xffff0000, v24
	v_lshlrev_b32_e32 v86, 16, v25
	v_and_b32_e32 v87, 0xffff0000, v25
	v_pk_fma_f32 v[30:31], v[80:81], v[84:85], v[30:31]
	v_pk_fma_f32 v[32:33], v[82:83], v[86:87], v[32:33]
	s_mov_b64 exec, -1
	v_cvt_pk_bf16_f32 v48, v26, v27
	v_cvt_pk_bf16_f32 v49, v28, v29
	v_cvt_pk_bf16_f32 v50, v30, v31
	v_cvt_pk_bf16_f32 v51, v32, v33
	s_waitcnt lgkmcnt(3)
	s_waitcnt lgkmcnt(1)
	s_waitcnt lgkmcnt(0)
	s_nop 0
	v_lshl_add_u64 v[4:5], v[2:3], 0, s[38:39]
	v_lshl_add_u64 v[2:3], v[52:53], 0, s[38:39]
	s_waitcnt vmcnt(4)
	s_waitcnt vmcnt(4)
	s_waitcnt lgkmcnt(3)
	s_waitcnt lgkmcnt(1)
	s_waitcnt lgkmcnt(0)
	s_waitcnt vmcnt(4)
	ds_read_b128 v[26:29], v9 offset:10304
	ds_read_b128 v[30:33], v9 offset:10320
	ds_read_b128 v[34:37], v9 offset:8256
	ds_read_b128 v[38:41], v9 offset:8272
	ds_read_b128 v[42:45], v9 offset:8768
	ds_read_b128 v[80:83], v9 offset:8784
	s_mov_b64 exec, vcc
	v_lshlrev_b32_e32 v46, 16, v178
	v_and_b32_e32 v47, 0xffff0000, v178
	v_lshlrev_b32_e32 v84, 16, v179
	v_and_b32_e32 v85, 0xffff0000, v179
	s_waitcnt lgkmcnt(2)
	v_pk_fma_f32 v[26:27], v[34:35], v[46:47], v[26:27]
	v_pk_fma_f32 v[28:29], v[36:37], v[84:85], v[28:29]
	v_lshlrev_b32_e32 v86, 16, v180
	v_and_b32_e32 v87, 0xffff0000, v180
	v_lshlrev_b32_e32 v96, 16, v181
	v_and_b32_e32 v97, 0xffff0000, v181
	v_pk_fma_f32 v[30:31], v[38:39], v[86:87], v[30:31]
	v_pk_fma_f32 v[32:33], v[40:41], v[96:97], v[32:33]
	s_mov_b64 exec, -1
	ds_read_b128 v[34:37], v9 offset:9280
	ds_read_b128 v[38:41], v9 offset:9296
	s_mov_b64 exec, s[4:5]
	v_lshlrev_b32_e32 v46, 16, v182
	v_and_b32_e32 v47, 0xffff0000, v182
	v_lshlrev_b32_e32 v84, 16, v183
	v_and_b32_e32 v85, 0xffff0000, v183
	s_waitcnt lgkmcnt(2)
	v_pk_fma_f32 v[26:27], v[42:43], v[46:47], v[26:27]
	v_pk_fma_f32 v[28:29], v[44:45], v[84:85], v[28:29]
	v_lshlrev_b32_e32 v86, 16, v184
	v_and_b32_e32 v87, 0xffff0000, v184
	v_lshlrev_b32_e32 v96, 16, v185
	v_and_b32_e32 v97, 0xffff0000, v185
	v_pk_fma_f32 v[30:31], v[80:81], v[86:87], v[30:31]
	v_pk_fma_f32 v[32:33], v[82:83], v[96:97], v[32:33]
	s_mov_b64 exec, -1
	ds_read_b128 v[42:45], v9 offset:9792
	ds_read_b128 v[80:83], v9 offset:9808
	v_lshlrev_b32_e32 v46, 16, v186
	v_and_b32_e32 v47, 0xffff0000, v186
	v_lshlrev_b32_e32 v84, 16, v187
	v_and_b32_e32 v85, 0xffff0000, v187
	s_waitcnt lgkmcnt(2)
	v_pk_fma_f32 v[26:27], v[34:35], v[46:47], v[26:27]
	v_pk_fma_f32 v[28:29], v[36:37], v[84:85], v[28:29]
	v_lshlrev_b32_e32 v86, 16, v188
	v_and_b32_e32 v87, 0xffff0000, v188
	v_lshlrev_b32_e32 v96, 16, v189
	v_and_b32_e32 v97, 0xffff0000, v189
	v_pk_fma_f32 v[30:31], v[38:39], v[86:87], v[30:31]
	v_pk_fma_f32 v[32:33], v[40:41], v[96:97], v[32:33]
	s_mov_b64 exec, s[6:7]
	v_lshlrev_b32_e32 v46, 16, v190
	v_and_b32_e32 v47, 0xffff0000, v190
	v_lshlrev_b32_e32 v84, 16, v191
	v_and_b32_e32 v85, 0xffff0000, v191
	s_waitcnt lgkmcnt(0)
	v_pk_fma_f32 v[26:27], v[42:43], v[46:47], v[26:27]
	v_pk_fma_f32 v[28:29], v[44:45], v[84:85], v[28:29]
	v_lshlrev_b32_e32 v86, 16, v192
	v_and_b32_e32 v87, 0xffff0000, v192
	v_lshlrev_b32_e32 v96, 16, v193
	v_and_b32_e32 v97, 0xffff0000, v193
	v_pk_fma_f32 v[30:31], v[80:81], v[86:87], v[30:31]
	v_pk_fma_f32 v[32:33], v[82:83], v[96:97], v[32:33]
	s_mov_b64 exec, -1
	v_cvt_pk_bf16_f32 v52, v26, v27
	v_cvt_pk_bf16_f32 v53, v28, v29
	v_cvt_pk_bf16_f32 v54, v30, v31
	v_cvt_pk_bf16_f32 v55, v32, v33
	s_waitcnt lgkmcnt(3)
	s_waitcnt lgkmcnt(1)
	s_waitcnt lgkmcnt(0)
	s_nop 0
	global_load_dwordx4 v[178:181], v[0:1], off offset:192
	global_load_dwordx4 v[182:185], v[4:5], off offset:192
	global_load_dwordx4 v[186:189], v[2:3], off offset:192
	global_load_dwordx4 v[190:193], v[6:7], off offset:192
	s_waitcnt vmcnt(7)
	s_waitcnt vmcnt(7)
	s_waitcnt lgkmcnt(3)
	s_waitcnt lgkmcnt(1)
	s_waitcnt lgkmcnt(0)
	s_waitcnt vmcnt(7)
	s_waitcnt vmcnt(7)
	ds_read_b128 v[26:29], v9 offset:10368
	ds_read_b128 v[30:33], v9 offset:10384
	ds_read_b128 v[34:37], v9 offset:8320
	ds_read_b128 v[38:41], v9 offset:8336
	ds_read_b128 v[42:45], v9 offset:8832
	ds_read_b128 v[80:83], v9 offset:8848
	s_mov_b64 exec, vcc
	v_lshlrev_b32_e32 v46, 16, v194
	v_and_b32_e32 v47, 0xffff0000, v194
	v_lshlrev_b32_e32 v84, 16, v195
	v_and_b32_e32 v85, 0xffff0000, v195
	s_waitcnt lgkmcnt(2)
	v_pk_fma_f32 v[26:27], v[34:35], v[46:47], v[26:27]
	v_pk_fma_f32 v[28:29], v[36:37], v[84:85], v[28:29]
	v_lshlrev_b32_e32 v86, 16, v196
	v_and_b32_e32 v87, 0xffff0000, v196
	v_lshlrev_b32_e32 v96, 16, v197
	v_and_b32_e32 v97, 0xffff0000, v197
	v_pk_fma_f32 v[30:31], v[38:39], v[86:87], v[30:31]
	v_pk_fma_f32 v[32:33], v[40:41], v[96:97], v[32:33]
	s_mov_b64 exec, -1
	ds_read_b128 v[34:37], v9 offset:9344
	ds_read_b128 v[38:41], v9 offset:9360
	s_mov_b64 exec, s[4:5]
	v_lshlrev_b32_e32 v46, 16, v198
	v_and_b32_e32 v47, 0xffff0000, v198
	v_lshlrev_b32_e32 v84, 16, v199
	v_and_b32_e32 v85, 0xffff0000, v199
	s_waitcnt lgkmcnt(2)
	v_pk_fma_f32 v[26:27], v[42:43], v[46:47], v[26:27]
	v_pk_fma_f32 v[28:29], v[44:45], v[84:85], v[28:29]
	v_lshlrev_b32_e32 v86, 16, v200
	v_and_b32_e32 v87, 0xffff0000, v200
	v_lshlrev_b32_e32 v96, 16, v201
	v_and_b32_e32 v97, 0xffff0000, v201
	v_pk_fma_f32 v[30:31], v[80:81], v[86:87], v[30:31]
	v_pk_fma_f32 v[32:33], v[82:83], v[96:97], v[32:33]
	s_mov_b64 exec, -1
	ds_read_b128 v[42:45], v9 offset:9856
	ds_read_b128 v[80:83], v9 offset:9872
	v_lshlrev_b32_e32 v46, 16, v202
	v_and_b32_e32 v47, 0xffff0000, v202
	v_lshlrev_b32_e32 v84, 16, v203
	v_and_b32_e32 v85, 0xffff0000, v203
	s_waitcnt lgkmcnt(2)
	v_pk_fma_f32 v[26:27], v[34:35], v[46:47], v[26:27]
	v_pk_fma_f32 v[28:29], v[36:37], v[84:85], v[28:29]
	v_lshlrev_b32_e32 v86, 16, v204
	v_and_b32_e32 v87, 0xffff0000, v204
	v_lshlrev_b32_e32 v96, 16, v205
	v_and_b32_e32 v97, 0xffff0000, v205
	v_pk_fma_f32 v[30:31], v[38:39], v[86:87], v[30:31]
	v_pk_fma_f32 v[32:33], v[40:41], v[96:97], v[32:33]
	s_mov_b64 exec, s[6:7]
	v_lshlrev_b32_e32 v46, 16, v206
	v_and_b32_e32 v47, 0xffff0000, v206
	v_lshlrev_b32_e32 v84, 16, v207
	v_and_b32_e32 v85, 0xffff0000, v207
	s_waitcnt lgkmcnt(0)
	v_pk_fma_f32 v[26:27], v[42:43], v[46:47], v[26:27]
	v_pk_fma_f32 v[28:29], v[44:45], v[84:85], v[28:29]
	v_lshlrev_b32_e32 v86, 16, v208
	v_and_b32_e32 v87, 0xffff0000, v208
	v_lshlrev_b32_e32 v96, 16, v209
	v_and_b32_e32 v97, 0xffff0000, v209
	v_pk_fma_f32 v[30:31], v[80:81], v[86:87], v[30:31]
	v_pk_fma_f32 v[32:33], v[82:83], v[96:97], v[32:33]
	s_mov_b64 exec, -1
	v_cvt_pk_bf16_f32 v56, v26, v27
	v_cvt_pk_bf16_f32 v57, v28, v29
	v_cvt_pk_bf16_f32 v58, v30, v31
	v_cvt_pk_bf16_f32 v59, v32, v33
	s_waitcnt lgkmcnt(3)
	s_waitcnt lgkmcnt(1)
	s_waitcnt lgkmcnt(0)
	s_nop 0
	global_load_dwordx4 v[194:197], v[0:1], off offset:224
	global_load_dwordx4 v[198:201], v[4:5], off offset:224
	global_load_dwordx4 v[202:205], v[2:3], off offset:224
	global_load_dwordx4 v[206:209], v[6:7], off offset:224
	s_waitcnt vmcnt(10)
	s_waitcnt vmcnt(10)
	s_waitcnt lgkmcnt(3)
	s_waitcnt lgkmcnt(1)
	s_waitcnt lgkmcnt(0)
	s_waitcnt vmcnt(10)
	s_waitcnt vmcnt(10)
	ds_read_b128 v[0:3], v9 offset:10432
	ds_read_b128 v[4:7], v9 offset:10448
	ds_read_b128 v[26:29], v9 offset:8384
	ds_read_b128 v[30:33], v9 offset:8400
	ds_read_b128 v[34:37], v9 offset:8896
	ds_read_b128 v[38:41], v9 offset:8912
	s_mov_b64 exec, vcc
	v_lshlrev_b32_e32 v42, 16, v210
	v_and_b32_e32 v43, 0xffff0000, v210
	v_lshlrev_b32_e32 v44, 16, v211
	v_and_b32_e32 v45, 0xffff0000, v211
	s_waitcnt lgkmcnt(2)
	v_pk_fma_f32 v[0:1], v[26:27], v[42:43], v[0:1]
	v_pk_fma_f32 v[2:3], v[28:29], v[44:45], v[2:3]
	v_lshlrev_b32_e32 v46, 16, v212
	v_and_b32_e32 v47, 0xffff0000, v212
	v_lshlrev_b32_e32 v80, 16, v213
	v_and_b32_e32 v81, 0xffff0000, v213
	v_pk_fma_f32 v[4:5], v[30:31], v[46:47], v[4:5]
	v_pk_fma_f32 v[6:7], v[32:33], v[80:81], v[6:7]
	s_mov_b64 exec, -1
	ds_read_b128 v[26:29], v9 offset:9408
	ds_read_b128 v[30:33], v9 offset:9424
	s_mov_b64 exec, s[4:5]
	v_lshlrev_b32_e32 v42, 16, v214
	v_and_b32_e32 v43, 0xffff0000, v214
	v_lshlrev_b32_e32 v44, 16, v215
	v_and_b32_e32 v45, 0xffff0000, v215
	s_waitcnt lgkmcnt(2)
	v_pk_fma_f32 v[0:1], v[34:35], v[42:43], v[0:1]
	v_pk_fma_f32 v[2:3], v[36:37], v[44:45], v[2:3]
	v_lshlrev_b32_e32 v46, 16, v216
	v_and_b32_e32 v47, 0xffff0000, v216
	v_lshlrev_b32_e32 v80, 16, v217
	v_and_b32_e32 v81, 0xffff0000, v217
	v_pk_fma_f32 v[4:5], v[38:39], v[46:47], v[4:5]
	v_pk_fma_f32 v[6:7], v[40:41], v[80:81], v[6:7]
	s_mov_b64 exec, -1
	ds_read_b128 v[34:37], v9 offset:9920
	ds_read_b128 v[38:41], v9 offset:9936
	v_lshlrev_b32_e32 v42, 16, v218
	v_and_b32_e32 v43, 0xffff0000, v218
	v_lshlrev_b32_e32 v44, 16, v219
	v_and_b32_e32 v45, 0xffff0000, v219
	s_waitcnt lgkmcnt(2)
	v_pk_fma_f32 v[0:1], v[26:27], v[42:43], v[0:1]
	v_pk_fma_f32 v[2:3], v[28:29], v[44:45], v[2:3]
	v_lshlrev_b32_e32 v46, 16, v220
	v_and_b32_e32 v47, 0xffff0000, v220
	v_lshlrev_b32_e32 v80, 16, v221
	v_and_b32_e32 v81, 0xffff0000, v221
	v_pk_fma_f32 v[4:5], v[30:31], v[46:47], v[4:5]
	v_pk_fma_f32 v[6:7], v[32:33], v[80:81], v[6:7]
	s_mov_b64 exec, s[6:7]
	v_lshlrev_b32_e32 v42, 16, v222
	v_and_b32_e32 v43, 0xffff0000, v222
	v_lshlrev_b32_e32 v44, 16, v223
	v_and_b32_e32 v45, 0xffff0000, v223
	s_waitcnt lgkmcnt(0)
	v_pk_fma_f32 v[0:1], v[34:35], v[42:43], v[0:1]
	v_pk_fma_f32 v[2:3], v[36:37], v[44:45], v[2:3]
	v_lshlrev_b32_e32 v46, 16, v224
	v_and_b32_e32 v47, 0xffff0000, v224
	v_lshlrev_b32_e32 v80, 16, v225
	v_and_b32_e32 v81, 0xffff0000, v225
	v_pk_fma_f32 v[4:5], v[38:39], v[46:47], v[4:5]
	v_pk_fma_f32 v[6:7], v[40:41], v[80:81], v[6:7]
	s_mov_b64 exec, -1
	v_cvt_pk_bf16_f32 v60, v0, v1
	v_cvt_pk_bf16_f32 v61, v2, v3
	v_cvt_pk_bf16_f32 v62, v4, v5
	v_cvt_pk_bf16_f32 v63, v6, v7
	s_waitcnt lgkmcnt(3)
	s_waitcnt lgkmcnt(1)
	s_waitcnt lgkmcnt(0)
	s_nop 0
	s_waitcnt vmcnt(9)
	s_waitcnt vmcnt(9)
	s_waitcnt lgkmcnt(3)
	s_waitcnt lgkmcnt(1)
	s_waitcnt lgkmcnt(0)
	s_waitcnt vmcnt(9)
	s_waitcnt vmcnt(9)
	ds_read_b128 v[0:3], v9 offset:10496
	ds_read_b128 v[4:7], v9 offset:10512
	ds_read_b128 v[26:29], v9 offset:8448
	ds_read_b128 v[30:33], v9 offset:8464
	ds_read_b128 v[34:37], v9 offset:8960
	ds_read_b128 v[38:41], v9 offset:8976
	s_mov_b64 exec, vcc
	v_lshlrev_b32_e32 v42, 16, v226
	v_and_b32_e32 v43, 0xffff0000, v226
	v_lshlrev_b32_e32 v44, 16, v227
	v_and_b32_e32 v45, 0xffff0000, v227
	s_waitcnt lgkmcnt(2)
	v_pk_fma_f32 v[0:1], v[26:27], v[42:43], v[0:1]
	v_pk_fma_f32 v[2:3], v[28:29], v[44:45], v[2:3]
	v_lshlrev_b32_e32 v46, 16, v228
	v_and_b32_e32 v47, 0xffff0000, v228
	v_lshlrev_b32_e32 v80, 16, v229
	v_and_b32_e32 v81, 0xffff0000, v229
	v_pk_fma_f32 v[4:5], v[30:31], v[46:47], v[4:5]
	v_pk_fma_f32 v[6:7], v[32:33], v[80:81], v[6:7]
	s_mov_b64 exec, -1
	ds_read_b128 v[26:29], v9 offset:9472
	ds_read_b128 v[30:33], v9 offset:9488
	s_mov_b64 exec, s[4:5]
	v_lshlrev_b32_e32 v42, 16, v230
	v_and_b32_e32 v43, 0xffff0000, v230
	v_lshlrev_b32_e32 v44, 16, v231
	v_and_b32_e32 v45, 0xffff0000, v231
	s_waitcnt lgkmcnt(2)
	v_pk_fma_f32 v[0:1], v[34:35], v[42:43], v[0:1]
	v_pk_fma_f32 v[2:3], v[36:37], v[44:45], v[2:3]
	v_lshlrev_b32_e32 v46, 16, v232
	v_and_b32_e32 v47, 0xffff0000, v232
	v_lshlrev_b32_e32 v80, 16, v233
	v_and_b32_e32 v81, 0xffff0000, v233
	v_pk_fma_f32 v[4:5], v[38:39], v[46:47], v[4:5]
	v_pk_fma_f32 v[6:7], v[40:41], v[80:81], v[6:7]
	s_mov_b64 exec, -1
	ds_read_b128 v[34:37], v9 offset:9984
	ds_read_b128 v[38:41], v9 offset:10000
	v_lshlrev_b32_e32 v42, 16, v234
	v_and_b32_e32 v43, 0xffff0000, v234
	v_lshlrev_b32_e32 v44, 16, v235
	v_and_b32_e32 v45, 0xffff0000, v235
	s_waitcnt lgkmcnt(2)
	v_pk_fma_f32 v[0:1], v[26:27], v[42:43], v[0:1]
	v_pk_fma_f32 v[2:3], v[28:29], v[44:45], v[2:3]
	v_lshlrev_b32_e32 v46, 16, v236
	v_and_b32_e32 v47, 0xffff0000, v236
	v_lshlrev_b32_e32 v80, 16, v237
	v_and_b32_e32 v81, 0xffff0000, v237
	v_pk_fma_f32 v[4:5], v[30:31], v[46:47], v[4:5]
	v_pk_fma_f32 v[6:7], v[32:33], v[80:81], v[6:7]
	s_mov_b64 exec, s[6:7]
	v_lshlrev_b32_e32 v42, 16, v238
	v_and_b32_e32 v43, 0xffff0000, v238
	v_lshlrev_b32_e32 v44, 16, v239
	v_and_b32_e32 v45, 0xffff0000, v239
	s_waitcnt lgkmcnt(0)
	v_pk_fma_f32 v[0:1], v[34:35], v[42:43], v[0:1]
	v_pk_fma_f32 v[2:3], v[36:37], v[44:45], v[2:3]
	v_lshlrev_b32_e32 v46, 16, v240
	v_and_b32_e32 v47, 0xffff0000, v240
	v_lshlrev_b32_e32 v80, 16, v241
	v_and_b32_e32 v81, 0xffff0000, v241
	v_pk_fma_f32 v[4:5], v[38:39], v[46:47], v[4:5]
	v_pk_fma_f32 v[6:7], v[40:41], v[80:81], v[6:7]
	s_mov_b64 exec, -1
	v_cvt_pk_bf16_f32 v64, v0, v1
	v_cvt_pk_bf16_f32 v65, v2, v3
	v_cvt_pk_bf16_f32 v66, v4, v5
	v_cvt_pk_bf16_f32 v67, v6, v7
	s_waitcnt lgkmcnt(3)
	s_waitcnt lgkmcnt(1)
	s_waitcnt lgkmcnt(0)
	s_nop 0
	s_waitcnt vmcnt(8)
	s_waitcnt vmcnt(8)
	s_waitcnt lgkmcnt(3)
	s_waitcnt lgkmcnt(1)
	s_waitcnt lgkmcnt(0)
	s_waitcnt vmcnt(8)
	s_waitcnt vmcnt(8)
	ds_read_b128 v[0:3], v9 offset:10560
	ds_read_b128 v[4:7], v9 offset:10576
	ds_read_b128 v[26:29], v9 offset:8512
	ds_read_b128 v[30:33], v9 offset:8528
	ds_read_b128 v[34:37], v9 offset:9024
	ds_read_b128 v[38:41], v9 offset:9040
	s_mov_b64 exec, vcc
	v_lshlrev_b32_e32 v42, 16, v242
	v_and_b32_e32 v43, 0xffff0000, v242
	v_lshlrev_b32_e32 v44, 16, v243
	v_and_b32_e32 v45, 0xffff0000, v243
	s_waitcnt lgkmcnt(2)
	v_pk_fma_f32 v[0:1], v[26:27], v[42:43], v[0:1]
	v_pk_fma_f32 v[2:3], v[28:29], v[44:45], v[2:3]
	v_lshlrev_b32_e32 v46, 16, v244
	v_and_b32_e32 v47, 0xffff0000, v244
	v_lshlrev_b32_e32 v80, 16, v245
	v_and_b32_e32 v81, 0xffff0000, v245
	v_pk_fma_f32 v[4:5], v[30:31], v[46:47], v[4:5]
	v_pk_fma_f32 v[6:7], v[32:33], v[80:81], v[6:7]
	s_mov_b64 exec, -1
	ds_read_b128 v[26:29], v9 offset:9536
	ds_read_b128 v[30:33], v9 offset:9552
	s_mov_b64 exec, s[4:5]
	v_lshlrev_b32_e32 v42, 16, v246
	v_and_b32_e32 v43, 0xffff0000, v246
	v_lshlrev_b32_e32 v44, 16, v247
	v_and_b32_e32 v45, 0xffff0000, v247
	s_waitcnt lgkmcnt(2)
	v_pk_fma_f32 v[0:1], v[34:35], v[42:43], v[0:1]
	v_pk_fma_f32 v[2:3], v[36:37], v[44:45], v[2:3]
	v_lshlrev_b32_e32 v46, 16, v248
	v_and_b32_e32 v47, 0xffff0000, v248
	v_lshlrev_b32_e32 v80, 16, v249
	v_and_b32_e32 v81, 0xffff0000, v249
	v_pk_fma_f32 v[4:5], v[38:39], v[46:47], v[4:5]
	v_pk_fma_f32 v[6:7], v[40:41], v[80:81], v[6:7]
	s_mov_b64 exec, -1
	ds_read_b128 v[34:37], v9 offset:10048
	ds_read_b128 v[38:41], v9 offset:10064
	v_lshlrev_b32_e32 v42, 16, v252
	v_and_b32_e32 v43, 0xffff0000, v252
	v_lshlrev_b32_e32 v44, 16, v253
	v_and_b32_e32 v45, 0xffff0000, v253
	s_waitcnt lgkmcnt(2)
	v_pk_fma_f32 v[0:1], v[26:27], v[42:43], v[0:1]
	v_pk_fma_f32 v[2:3], v[28:29], v[44:45], v[2:3]
	v_lshlrev_b32_e32 v46, 16, v254
	v_and_b32_e32 v47, 0xffff0000, v254
	v_lshlrev_b32_e32 v80, 16, v255
	v_and_b32_e32 v81, 0xffff0000, v255
	v_pk_fma_f32 v[4:5], v[30:31], v[46:47], v[4:5]
	v_pk_fma_f32 v[6:7], v[32:33], v[80:81], v[6:7]
	s_mov_b64 exec, s[6:7]
	v_lshlrev_b32_e32 v42, 16, v168
	v_and_b32_e32 v43, 0xffff0000, v168
	v_lshlrev_b32_e32 v44, 16, v169
	v_and_b32_e32 v45, 0xffff0000, v169
	s_waitcnt lgkmcnt(0)
	v_pk_fma_f32 v[0:1], v[34:35], v[42:43], v[0:1]
	v_pk_fma_f32 v[2:3], v[36:37], v[44:45], v[2:3]
	v_lshlrev_b32_e32 v46, 16, v170
	v_and_b32_e32 v47, 0xffff0000, v170
	v_lshlrev_b32_e32 v80, 16, v171
	v_and_b32_e32 v81, 0xffff0000, v171
	v_pk_fma_f32 v[4:5], v[38:39], v[46:47], v[4:5]
	v_pk_fma_f32 v[6:7], v[40:41], v[80:81], v[6:7]
	s_mov_b64 exec, -1
	v_cvt_pk_bf16_f32 v68, v0, v1
	v_cvt_pk_bf16_f32 v69, v2, v3
	v_cvt_pk_bf16_f32 v70, v4, v5
	v_cvt_pk_bf16_f32 v71, v6, v7
	s_waitcnt lgkmcnt(3)
	s_waitcnt lgkmcnt(1)
	s_waitcnt lgkmcnt(0)
	s_nop 0
	s_waitcnt vmcnt(4)
	s_waitcnt vmcnt(4)
	s_waitcnt lgkmcnt(3)
	s_waitcnt lgkmcnt(1)
	s_waitcnt lgkmcnt(0)
	s_waitcnt vmcnt(4)
	s_waitcnt vmcnt(4)
	ds_read_b128 v[0:3], v9 offset:10624
	ds_read_b128 v[4:7], v9 offset:10640
	ds_read_b128 v[26:29], v9 offset:8576
	ds_read_b128 v[30:33], v9 offset:8592
	ds_read_b128 v[34:37], v9 offset:9088
	ds_read_b128 v[38:41], v9 offset:9104
	s_mov_b64 exec, vcc
	v_lshlrev_b32_e32 v42, 16, v178
	v_and_b32_e32 v43, 0xffff0000, v178
	v_lshlrev_b32_e32 v44, 16, v179
	v_and_b32_e32 v45, 0xffff0000, v179
	s_waitcnt lgkmcnt(2)
	v_pk_fma_f32 v[0:1], v[26:27], v[42:43], v[0:1]
	v_pk_fma_f32 v[2:3], v[28:29], v[44:45], v[2:3]
	v_lshlrev_b32_e32 v46, 16, v180
	v_and_b32_e32 v47, 0xffff0000, v180
	v_lshlrev_b32_e32 v80, 16, v181
	v_and_b32_e32 v81, 0xffff0000, v181
	v_pk_fma_f32 v[4:5], v[30:31], v[46:47], v[4:5]
	v_pk_fma_f32 v[6:7], v[32:33], v[80:81], v[6:7]
	s_mov_b64 exec, -1
	ds_read_b128 v[26:29], v9 offset:9600
	ds_read_b128 v[30:33], v9 offset:9616
	s_mov_b64 exec, s[4:5]
	v_lshlrev_b32_e32 v42, 16, v182
	v_and_b32_e32 v43, 0xffff0000, v182
	v_lshlrev_b32_e32 v44, 16, v183
	v_and_b32_e32 v45, 0xffff0000, v183
	s_waitcnt lgkmcnt(2)
	v_pk_fma_f32 v[0:1], v[34:35], v[42:43], v[0:1]
	v_pk_fma_f32 v[2:3], v[36:37], v[44:45], v[2:3]
	v_lshlrev_b32_e32 v46, 16, v184
	v_and_b32_e32 v47, 0xffff0000, v184
	v_lshlrev_b32_e32 v80, 16, v185
	v_and_b32_e32 v81, 0xffff0000, v185
	v_pk_fma_f32 v[4:5], v[38:39], v[46:47], v[4:5]
	v_pk_fma_f32 v[6:7], v[40:41], v[80:81], v[6:7]
	s_mov_b64 exec, -1
	ds_read_b128 v[34:37], v9 offset:10112
	ds_read_b128 v[38:41], v9 offset:10128
	v_lshlrev_b32_e32 v42, 16, v186
	v_and_b32_e32 v43, 0xffff0000, v186
	v_lshlrev_b32_e32 v44, 16, v187
	v_and_b32_e32 v45, 0xffff0000, v187
	s_waitcnt lgkmcnt(2)
	v_pk_fma_f32 v[0:1], v[26:27], v[42:43], v[0:1]
	v_pk_fma_f32 v[2:3], v[28:29], v[44:45], v[2:3]
	v_lshlrev_b32_e32 v46, 16, v188
	v_and_b32_e32 v47, 0xffff0000, v188
	v_lshlrev_b32_e32 v80, 16, v189
	v_and_b32_e32 v81, 0xffff0000, v189
	v_pk_fma_f32 v[4:5], v[30:31], v[46:47], v[4:5]
	v_pk_fma_f32 v[6:7], v[32:33], v[80:81], v[6:7]
	s_mov_b64 exec, s[6:7]
	v_lshlrev_b32_e32 v42, 16, v190
	v_and_b32_e32 v43, 0xffff0000, v190
	v_lshlrev_b32_e32 v44, 16, v191
	v_and_b32_e32 v45, 0xffff0000, v191
	s_waitcnt lgkmcnt(0)
	v_pk_fma_f32 v[0:1], v[34:35], v[42:43], v[0:1]
	v_pk_fma_f32 v[2:3], v[36:37], v[44:45], v[2:3]
	v_lshlrev_b32_e32 v46, 16, v192
	v_and_b32_e32 v47, 0xffff0000, v192
	v_lshlrev_b32_e32 v80, 16, v193
	v_and_b32_e32 v81, 0xffff0000, v193
	v_pk_fma_f32 v[4:5], v[38:39], v[46:47], v[4:5]
	v_pk_fma_f32 v[6:7], v[40:41], v[80:81], v[6:7]
	s_mov_b64 exec, -1
	v_cvt_pk_bf16_f32 v72, v0, v1
	v_cvt_pk_bf16_f32 v73, v2, v3
	v_cvt_pk_bf16_f32 v74, v4, v5
	v_cvt_pk_bf16_f32 v75, v6, v7
	s_waitcnt lgkmcnt(3)
	s_waitcnt lgkmcnt(1)
	s_waitcnt lgkmcnt(0)
	v_lshlrev_b32_e32 v38, 3, v92
	s_nop 0
	s_nop 0
	v_or_b32_e32 v39, 16, v38
	s_waitcnt vmcnt(0)
	s_waitcnt vmcnt(0)
	s_waitcnt lgkmcnt(3)
	s_waitcnt lgkmcnt(1)
	s_waitcnt lgkmcnt(0)
	s_waitcnt vmcnt(0)
	s_waitcnt vmcnt(0)
	ds_read_b128 v[0:3], v9 offset:10688
	ds_read_b128 v[4:7], v9 offset:10704
	ds_read_b128 v[26:29], v9 offset:8640
	ds_read_b128 v[30:33], v9 offset:8656
	ds_read_b128 v[34:37], v9 offset:9152
	ds_read_b128 v[40:43], v9 offset:9168
	s_mov_b64 exec, vcc
	v_lshlrev_b32_e32 v44, 16, v194
	v_and_b32_e32 v45, 0xffff0000, v194
	v_lshlrev_b32_e32 v46, 16, v195
	v_and_b32_e32 v47, 0xffff0000, v195
	s_waitcnt lgkmcnt(2)
	v_pk_fma_f32 v[0:1], v[26:27], v[44:45], v[0:1]
	v_pk_fma_f32 v[2:3], v[28:29], v[46:47], v[2:3]
	v_lshlrev_b32_e32 v80, 16, v196
	v_and_b32_e32 v81, 0xffff0000, v196
	v_lshlrev_b32_e32 v82, 16, v197
	v_and_b32_e32 v83, 0xffff0000, v197
	v_pk_fma_f32 v[4:5], v[30:31], v[80:81], v[4:5]
	v_pk_fma_f32 v[6:7], v[32:33], v[82:83], v[6:7]
	s_mov_b64 exec, -1
	ds_read_b128 v[26:29], v9 offset:9664
	ds_read_b128 v[30:33], v9 offset:9680
	s_mov_b64 exec, s[4:5]
	v_lshlrev_b32_e32 v44, 16, v198
	v_and_b32_e32 v45, 0xffff0000, v198
	v_lshlrev_b32_e32 v46, 16, v199
	v_and_b32_e32 v47, 0xffff0000, v199
	s_waitcnt lgkmcnt(2)
	v_pk_fma_f32 v[0:1], v[34:35], v[44:45], v[0:1]
	v_pk_fma_f32 v[2:3], v[36:37], v[46:47], v[2:3]
	v_lshlrev_b32_e32 v80, 16, v200
	v_and_b32_e32 v81, 0xffff0000, v200
	v_lshlrev_b32_e32 v82, 16, v201
	v_and_b32_e32 v83, 0xffff0000, v201
	v_pk_fma_f32 v[4:5], v[40:41], v[80:81], v[4:5]
	v_pk_fma_f32 v[6:7], v[42:43], v[82:83], v[6:7]
	s_mov_b64 exec, -1
	ds_read_b128 v[34:37], v9 offset:10176
	ds_read_b128 v[40:43], v9 offset:10192
	v_lshlrev_b32_e32 v44, 16, v202
	v_and_b32_e32 v45, 0xffff0000, v202
	v_lshlrev_b32_e32 v46, 16, v203
	v_and_b32_e32 v47, 0xffff0000, v203
	s_waitcnt lgkmcnt(2)
	v_pk_fma_f32 v[0:1], v[26:27], v[44:45], v[0:1]
	v_pk_fma_f32 v[2:3], v[28:29], v[46:47], v[2:3]
	v_lshlrev_b32_e32 v80, 16, v204
	v_and_b32_e32 v81, 0xffff0000, v204
	v_lshlrev_b32_e32 v82, 16, v205
	v_and_b32_e32 v83, 0xffff0000, v205
	v_pk_fma_f32 v[4:5], v[30:31], v[80:81], v[4:5]
	v_pk_fma_f32 v[6:7], v[32:33], v[82:83], v[6:7]
	s_mov_b64 exec, s[6:7]
	v_lshlrev_b32_e32 v44, 16, v206
	v_and_b32_e32 v45, 0xffff0000, v206
	v_lshlrev_b32_e32 v46, 16, v207
	v_and_b32_e32 v47, 0xffff0000, v207
	s_waitcnt lgkmcnt(0)
	v_pk_fma_f32 v[0:1], v[34:35], v[44:45], v[0:1]
	v_pk_fma_f32 v[2:3], v[36:37], v[46:47], v[2:3]
	v_lshlrev_b32_e32 v80, 16, v208
	v_and_b32_e32 v81, 0xffff0000, v208
	v_lshlrev_b32_e32 v82, 16, v209
	v_and_b32_e32 v83, 0xffff0000, v209
	v_pk_fma_f32 v[4:5], v[40:41], v[80:81], v[4:5]
	v_pk_fma_f32 v[6:7], v[42:43], v[82:83], v[6:7]
	s_mov_b64 exec, -1
	v_cvt_pk_bf16_f32 v76, v0, v1
	v_cvt_pk_bf16_f32 v77, v2, v3
	v_cvt_pk_bf16_f32 v78, v4, v5
	v_cvt_pk_bf16_f32 v79, v6, v7
	s_waitcnt lgkmcnt(3)
	s_waitcnt lgkmcnt(1)
	s_waitcnt lgkmcnt(0)
	v_cmp_eq_u32_e32 vcc, v38, v93
	v_or_b32_e32 v2, 1, v38
	v_cndmask_b32_e32 v0, 0, v128, vcc
	v_or_b32_e32 v1, 2, v38
	v_cmp_eq_u32_e32 vcc, v2, v93
	v_or_b32_e32 v4, 3, v38
	v_or_b32_e32 v3, 4, v38
	v_cndmask_b32_e32 v2, 0, v128, vcc
	v_cmp_eq_u32_e32 vcc, v1, v93
	v_or_b32_e32 v5, 6, v38
	v_or_b32_e32 v6, 5, v38
	v_cndmask_b32_e32 v1, 0, v128, vcc
	v_cmp_eq_u32_e32 vcc, v4, v93
	v_or_b32_e32 v7, 7, v38
	v_or_b32_e32 v11, 17, v38
	v_cndmask_b32_e32 v4, 0, v128, vcc
	v_cmp_eq_u32_e32 vcc, v3, v93
	v_or_b32_e32 v10, 18, v38
	v_or_b32_e32 v13, 19, v38
	v_cndmask_b32_e32 v3, 0, v128, vcc
	v_cmp_eq_u32_e32 vcc, v5, v93
	v_or_b32_e32 v12, 20, v38
	v_or_b32_e32 v14, 22, v38
	v_cndmask_b32_e32 v5, 0, v128, vcc
	v_cmp_eq_u32_e32 vcc, v6, v93
	v_or_b32_e32 v15, 21, v38
	v_or_b32_e32 v16, 23, v38
	v_cndmask_b32_e32 v6, 0, v128, vcc
	v_cmp_eq_u32_e32 vcc, v7, v93
	v_and_b32_e32 v18, 64, v126
	v_xor_b32_e32 v17, 32, v126
	v_cndmask_b32_e32 v7, 0, v128, vcc
	v_cmp_eq_u32_e32 vcc, v39, v93
	v_add_u32_e32 v18, 64, v18
	s_lshl_b32 s6, s64, 8
	v_cndmask_b32_e32 v9, 0, v128, vcc
	v_cmp_eq_u32_e32 vcc, v11, v93
	s_add_i32 s6, s6, 16
	v_cmp_eq_u32_e64 s[4:5], 0, v92
	v_cndmask_b32_e32 v11, 0, v128, vcc
	v_cmp_eq_u32_e32 vcc, v10, v93
	v_lshl_add_u32 v136, v93, 3, s6
	v_perm_b32 v82, v6, v3, s87
	v_cndmask_b32_e32 v10, 0, v128, vcc
	v_cmp_eq_u32_e32 vcc, v13, v93
	v_perm_b32 v81, v4, v1, s87
	v_perm_b32 v83, v7, v5, s87
	v_cndmask_b32_e32 v13, 0, v128, vcc
	v_cmp_eq_u32_e32 vcc, v12, v93
	v_perm_b32 v80, v2, v0, s87
	v_perm_b32 v85, v13, v10, s87
	v_cndmask_b32_e32 v12, 0, v128, vcc
	v_cmp_eq_u32_e32 vcc, v14, v93
	v_perm_b32 v84, v11, v9, s87
	s_nop 0
	v_cndmask_b32_e32 v14, 0, v128, vcc
	v_cmp_eq_u32_e32 vcc, v15, v93
	s_nop 1
	v_cndmask_b32_e32 v15, 0, v128, vcc
	v_cmp_eq_u32_e32 vcc, v16, v93
	v_perm_b32 v86, v15, v12, s87
	s_nop 0
	v_cndmask_b32_e32 v16, 0, v128, vcc
	v_cmp_lt_i32_e32 vcc, v17, v18
	v_perm_b32 v87, v16, v14, s87
	s_nop 0
	v_cndmask_b32_e32 v17, v126, v17, vcc
	v_lshlrev_b32_e32 v137, 2, v17
	v_lshl_or_b32 v175, v138, 2, v129
	global_load_dword v172, v175, s[42:43]
	global_load_dword v173, v175, s[36:37]
	global_load_dword v174, v175, s[40:41]
	v_xad_u32 v145, v88, v8, v94
	ds_read_b128 v[0:3], v145 offset:16384
	ds_read_b128 v[4:7], v145 offset:49152
	s_waitcnt lgkmcnt(1)
	v_mfma_f32_32x32x16_bf16 v[32:47], v[48:51], v[0:3], 0
	v_or_b32_e32 v0, 32, v88
	v_xad_u32 v147, v0, v8, v94
	s_waitcnt lgkmcnt(0)
	v_mfma_f32_32x32x16_bf16 v[16:31], v[48:51], v[4:7], 0
	ds_read_b128 v[0:3], v147 offset:16384
	ds_read_b128 v[4:7], v147 offset:49152
	s_waitcnt lgkmcnt(1)
	v_mfma_f32_32x32x16_bf16 v[32:47], v[52:55], v[0:3], v[32:47]
	v_or_b32_e32 v0, 64, v88
	v_xad_u32 v142, v0, v8, v94
	s_waitcnt lgkmcnt(0)
	v_mfma_f32_32x32x16_bf16 v[16:31], v[52:55], v[4:7], v[16:31]
	ds_read_b128 v[0:3], v142 offset:16384
	ds_read_b128 v[4:7], v142 offset:49152
	s_waitcnt lgkmcnt(1)
	v_mfma_f32_32x32x16_bf16 v[32:47], v[56:59], v[0:3], v[32:47]
	v_or_b32_e32 v0, 0x60, v88
	v_xad_u32 v146, v0, v8, v94
	s_waitcnt lgkmcnt(0)
	v_mfma_f32_32x32x16_bf16 v[16:31], v[56:59], v[4:7], v[16:31]
	ds_read_b128 v[0:3], v146 offset:16384
	ds_read_b128 v[4:7], v146 offset:49152
	s_waitcnt lgkmcnt(1)
	v_mfma_f32_32x32x16_bf16 v[32:47], v[60:63], v[0:3], v[32:47]
	v_or_b32_e32 v0, 0x80, v88
	v_xad_u32 v141, v0, v8, v94
	s_waitcnt lgkmcnt(0)
	v_mfma_f32_32x32x16_bf16 v[16:31], v[60:63], v[4:7], v[16:31]
	ds_read_b128 v[0:3], v141 offset:16384
	ds_read_b128 v[4:7], v141 offset:49152
	s_waitcnt lgkmcnt(1)
	v_mfma_f32_32x32x16_bf16 v[32:47], v[64:67], v[0:3], v[32:47]
	v_or_b32_e32 v0, 0xa0, v88
	v_xad_u32 v144, v0, v8, v94
	s_waitcnt lgkmcnt(0)
	v_mfma_f32_32x32x16_bf16 v[16:31], v[64:67], v[4:7], v[16:31]
	ds_read_b128 v[0:3], v144 offset:16384
	ds_read_b128 v[4:7], v144 offset:49152
	s_waitcnt lgkmcnt(1)
	v_mfma_f32_32x32x16_bf16 v[32:47], v[68:71], v[0:3], v[32:47]
	v_or_b32_e32 v0, 0xc0, v88
	v_xad_u32 v139, v0, v8, v94
	s_waitcnt lgkmcnt(0)
	v_mfma_f32_32x32x16_bf16 v[16:31], v[68:71], v[4:7], v[16:31]
	ds_read_b128 v[0:3], v139 offset:16384
	ds_read_b128 v[4:7], v139 offset:49152
	s_waitcnt lgkmcnt(1)
	v_mfma_f32_32x32x16_bf16 v[32:47], v[72:75], v[0:3], v[32:47]
	v_or_b32_e32 v0, 0xe0, v88
	v_xad_u32 v143, v0, v8, v94
	s_waitcnt lgkmcnt(0)
	v_mfma_f32_32x32x16_bf16 v[16:31], v[72:75], v[4:7], v[16:31]
	ds_read_b128 v[0:3], v143 offset:16384
	ds_read_b128 v[4:7], v143 offset:49152
	s_waitcnt lgkmcnt(1)
	v_mfma_f32_32x32x16_bf16 v[32:47], v[76:79], v[0:3], v[32:47]
	s_waitcnt lgkmcnt(0)
	v_mfma_f32_32x32x16_bf16 v[16:31], v[76:79], v[4:7], v[16:31]
	v_mfma_f32_32x32x16_bf16 v[0:15], v[48:51], v[80:83], 0
	v_mfma_f32_32x32x16_bf16 v[0:15], v[52:55], v[84:87], v[0:15]
	v_lshl_or_b32 v88, v138, 2, v129
	s_waitcnt vmcnt(0)
	ds_read_b32 v251, v167
	v_mul_f32_e32 v94, 0xbfb8aa3b, v173
	v_mul_f32_e32 v88, 0xbfb8aa3b, v174
	v_fmamk_f32 v32, v32, 0xbfb8aa3b, v94
	v_fmamk_f32 v16, v16, 0xbfb8aa3b, v88
	v_exp_f32_e32 v32, v32
	v_exp_f32_e32 v96, v16
	v_fmamk_f32 v17, v17, 0xbfb8aa3b, v88
	v_exp_f32_e32 v97, v17
	v_add_f32_e32 v32, 1.0, v32
	v_add_f32_e32 v96, 1.0, v96
	v_rcp_f32_e32 v17, v32
	v_rcp_f32_e32 v32, v96
	v_fmamk_f32 v33, v33, 0xbfb8aa3b, v94
	v_fmamk_f32 v34, v34, 0xbfb8aa3b, v94
	v_exp_f32_e32 v33, v33
	v_exp_f32_e32 v34, v34
	v_add_f32_e32 v33, 1.0, v33
	v_add_f32_e32 v34, 1.0, v34
	v_rcp_f32_e32 v33, v33
	v_rcp_f32_e32 v34, v34
	v_fmamk_f32 v18, v18, 0xbfb8aa3b, v88
	v_fmamk_f32 v19, v19, 0xbfb8aa3b, v88
	v_exp_f32_e32 v18, v18
	s_waitcnt lgkmcnt(0)
	v_mul_f32_e32 v95, 0x3fb8aa3b, v251
	v_mul_f32_e32 v16, v17, v95
	v_mul_f32_e32 v17, v33, v95
	v_exp_f32_e32 v33, v16
	v_mul_f32_e32 v16, v34, v95
	v_exp_f32_e32 v98, v16
	v_fmamk_f32 v16, v35, 0xbfb8aa3b, v94
	v_exp_f32_e32 v16, v16
	v_exp_f32_e32 v96, v17
	v_add_f32_e32 v16, 1.0, v16
	v_rcp_f32_e32 v16, v16
	v_exp_f32_e32 v19, v19
	v_add_f32_e32 v97, 1.0, v97
	v_add_f32_e32 v18, 1.0, v18
	v_mul_f32_e32 v16, v16, v95
	v_exp_f32_e32 v16, v16
	v_fma_f32 v35, -v98, v98, 1.0
	v_rcp_f32_e32 v17, v97
	v_fma_f32 v34, -v33, v33, 1.0
	v_fma_f32 v97, -v96, v96, 1.0
	v_rcp_f32_e32 v18, v18
	v_sqrt_f32_e32 v35, v35
	v_add_f32_e32 v19, 1.0, v19
	v_fma_f32 v99, -v16, v16, 1.0
	v_sqrt_f32_e32 v34, v34
	v_sqrt_f32_e32 v97, v97
	v_rcp_f32_e32 v19, v19
	v_sqrt_f32_e32 v99, v99
	v_mul_f32_e32 v35, v18, v35
	v_fmamk_f32 v18, v36, 0xbfb8aa3b, v94
	v_mul_f32_e32 v32, v32, v34
	v_mul_f32_e32 v34, v17, v97
	v_mul_f32_e32 v17, v19, v99
	v_fmamk_f32 v19, v20, 0xbfb8aa3b, v88
	v_exp_f32_e32 v18, v18
	v_exp_f32_e32 v19, v19
	v_mul_f32_e32 v3, v3, v17
	v_add_f32_e32 v17, 1.0, v18
	v_rcp_f32_e32 v17, v17
	v_add_f32_e32 v18, 1.0, v19
	v_fmamk_f32 v19, v37, 0xbfb8aa3b, v94
	v_exp_f32_e32 v19, v19
	v_mul_f32_e32 v17, v17, v95
	v_exp_f32_e32 v36, v17
	v_add_f32_e32 v17, 1.0, v19
	v_rcp_f32_e32 v17, v17
	v_fmamk_f32 v19, v21, 0xbfb8aa3b, v88
	v_exp_f32_e32 v19, v19
	v_mul_f32_e32 v17, v17, v95
	v_exp_f32_e32 v37, v17
	v_fmamk_f32 v17, v38, 0xbfb8aa3b, v94
	v_exp_f32_e32 v17, v17
	v_fmamk_f32 v23, v23, 0xbfb8aa3b, v88
	v_add_f32_e32 v19, 1.0, v19
	v_fma_f32 v21, -v37, v37, 1.0
	v_add_f32_e32 v17, 1.0, v17
	v_rcp_f32_e32 v17, v17
	v_rcp_f32_e32 v19, v19
	v_sqrt_f32_e32 v21, v21
	v_mul_f32_e32 v17, v17, v95
	v_exp_f32_e32 v38, v17
	v_fmamk_f32 v17, v39, 0xbfb8aa3b, v94
	v_exp_f32_e32 v17, v17
	v_exp_f32_e32 v23, v23
	v_fma_f32 v20, -v36, v36, 1.0
	v_mul_f32_e32 v100, v19, v21
	v_add_f32_e32 v17, 1.0, v17
	v_rcp_f32_e32 v17, v17
	v_add_f32_e32 v23, 1.0, v23
	v_fmamk_f32 v19, v40, 0xbfb8aa3b, v94
	v_rcp_f32_e32 v18, v18
	v_mul_f32_e32 v17, v17, v95
	v_exp_f32_e32 v17, v17
	v_sqrt_f32_e32 v20, v20
	v_rcp_f32_e32 v23, v23
	v_fma_f32 v97, -v17, v17, 1.0
	v_sqrt_f32_e32 v97, v97
	v_fmamk_f32 v21, v24, 0xbfb8aa3b, v88
	v_fmamk_f32 v22, v22, 0xbfb8aa3b, v88
	v_exp_f32_e32 v19, v19
	v_exp_f32_e32 v21, v21
	v_exp_f32_e32 v22, v22
	v_mul_f32_e32 v99, v18, v20
	v_mul_f32_e32 v18, v23, v97
	v_mul_f32_e32 v7, v7, v18
	v_add_f32_e32 v18, 1.0, v19
	v_rcp_f32_e32 v18, v18
	v_add_f32_e32 v19, 1.0, v21
	v_fmamk_f32 v21, v41, 0xbfb8aa3b, v94
	v_add_f32_e32 v22, 1.0, v22
	v_fma_f32 v39, -v38, v38, 1.0
	v_rcp_f32_e32 v22, v22
	v_sqrt_f32_e32 v39, v39
	v_exp_f32_e32 v21, v21
	v_mul_f32_e32 v18, v18, v95
	v_mul_f32_e32 v20, v22, v39
	v_exp_f32_e32 v39, v18
	v_add_f32_e32 v18, 1.0, v21
	v_rcp_f32_e32 v18, v18
	v_fmamk_f32 v21, v25, 0xbfb8aa3b, v88
	v_exp_f32_e32 v21, v21
	v_mul_f32_e32 v18, v18, v95
	v_exp_f32_e32 v40, v18
	v_fmamk_f32 v18, v42, 0xbfb8aa3b, v94
	v_exp_f32_e32 v18, v18
	v_fmamk_f32 v24, v26, 0xbfb8aa3b, v88
	v_fmamk_f32 v26, v27, 0xbfb8aa3b, v88
	v_add_f32_e32 v21, 1.0, v21
	v_add_f32_e32 v18, 1.0, v18
	v_rcp_f32_e32 v18, v18
	v_fma_f32 v23, -v40, v40, 1.0
	v_fma_f32 v22, -v39, v39, 1.0
	v_mul_f32_e32 v18, v18, v95
	v_exp_f32_e32 v41, v18
	v_fmamk_f32 v18, v43, 0xbfb8aa3b, v94
	v_exp_f32_e32 v18, v18
	v_rcp_f32_e32 v21, v21
	v_sqrt_f32_e32 v23, v23
	v_exp_f32_e32 v26, v26
	v_add_f32_e32 v18, 1.0, v18
	v_rcp_f32_e32 v18, v18
	v_rcp_f32_e32 v19, v19
	v_sqrt_f32_e32 v22, v22
	v_add_f32_e32 v26, 1.0, v26
	v_mul_f32_e32 v18, v18, v95
	v_exp_f32_e32 v18, v18
	v_mul_f32_e32 v43, v21, v23
	v_fmamk_f32 v21, v44, 0xbfb8aa3b, v94
	v_rcp_f32_e32 v26, v26
	v_fma_f32 v27, -v18, v18, 1.0
	v_sqrt_f32_e32 v27, v27
	v_mul_f32_e32 v42, v19, v22
	v_fmamk_f32 v22, v28, 0xbfb8aa3b, v88
	v_exp_f32_e32 v21, v21
	v_exp_f32_e32 v22, v22
	v_mul_f32_e32 v19, v26, v27
	v_mul_f32_e32 v11, v11, v19
	v_add_f32_e32 v19, 1.0, v21
	v_rcp_f32_e32 v19, v19
	v_add_f32_e32 v21, 1.0, v22
	v_fmamk_f32 v22, v45, 0xbfb8aa3b, v94
	v_exp_f32_e32 v22, v22
	v_mul_f32_e32 v19, v19, v95
	v_exp_f32_e32 v44, v19
	v_add_f32_e32 v19, 1.0, v22
	v_rcp_f32_e32 v19, v19
	v_exp_f32_e32 v24, v24
	v_fma_f32 v25, -v41, v41, 1.0
	v_mul_f32_e32 v19, v19, v95
	v_exp_f32_e32 v45, v19
	v_fmamk_f32 v19, v46, 0xbfb8aa3b, v94
	v_exp_f32_e32 v19, v19
	v_add_f32_e32 v24, 1.0, v24
	v_rcp_f32_e32 v24, v24
	v_sqrt_f32_e32 v25, v25
	v_add_f32_e32 v19, 1.0, v19
	v_rcp_f32_e32 v19, v19
	v_fmamk_f32 v22, v29, 0xbfb8aa3b, v88
	v_mul_f32_e32 v97, v24, v25
	v_fma_f32 v24, -v45, v45, 1.0
	v_mul_f32_e32 v19, v19, v95
	v_exp_f32_e32 v46, v19
	v_fmamk_f32 v19, v47, 0xbfb8aa3b, v94
	v_exp_f32_e32 v19, v19
	v_sqrt_f32_e32 v25, v24
	v_fmamk_f32 v24, v30, 0xbfb8aa3b, v88
	v_exp_f32_e32 v24, v24
	v_add_f32_e32 v19, 1.0, v19
	v_rcp_f32_e32 v19, v19
	v_fma_f32 v27, -v46, v46, 1.0
	v_add_f32_e32 v24, 1.0, v24
	v_rcp_f32_e32 v26, v24
	v_fmamk_f32 v24, v31, 0xbfb8aa3b, v88
	v_mul_f32_e32 v19, v19, v95
	v_exp_f32_e32 v28, v24
	v_exp_f32_e32 v24, v19
	v_sqrt_f32_e32 v19, v27
	v_add_f32_e32 v27, 1.0, v28
	v_fma_f32 v28, -v24, v24, 1.0
	v_exp_f32_e32 v22, v22
	v_rcp_f32_e32 v27, v27
	v_sqrt_f32_e32 v28, v28
	v_fma_f32 v23, -v44, v44, 1.0
	v_rcp_f32_e32 v21, v21
	v_sqrt_f32_e32 v23, v23
	v_add_f32_e32 v22, 1.0, v22
	v_mul_f32_e32 v94, v26, v19
	v_mul_f32_e32 v19, v27, v28
	v_fmac_f32_e32 v7, 0, v17
	v_rcp_f32_e32 v22, v22
	v_mul_f32_e32 v15, v15, v19
	v_mul_f32_e32 v19, v38, v7
	v_fmac_f32_e32 v3, 0, v16
	v_fmac_f32_e32 v19, v6, v20
	v_mul_f32_e32 v47, v21, v23
	v_mul_f32_e32 v21, v98, v3
	v_mul_f32_e32 v20, v37, v19
	v_fmac_f32_e32 v15, 0, v24
	v_fmac_f32_e32 v21, v2, v35
	v_fmac_f32_e32 v20, v5, v100
	v_mul_f32_e32 v2, v46, v15
	v_mul_f32_e32 v88, v22, v25
	v_mul_f32_e32 v22, v36, v20
	v_fmac_f32_e32 v2, v14, v94
	v_fmac_f32_e32 v22, v4, v99
	v_mul_f32_e32 v4, v45, v2
	v_mul_f32_e32 v23, v96, v21
	v_fmac_f32_e32 v4, v13, v88
	v_fmac_f32_e32 v23, v1, v34
	v_fmac_f32_e32 v11, 0, v18
	v_mul_f32_e32 v14, v24, v46
	v_mul_f32_e32 v6, v44, v4
	v_mul_f32_e32 v25, v33, v23
	v_mul_f32_e32 v5, v41, v11
	v_mul_f32_e32 v13, v45, v14
	v_fmac_f32_e32 v6, v12, v47
	v_fmac_f32_e32 v25, v0, v32
	v_fmac_f32_e32 v5, v10, v97
	v_mul_f32_e32 v12, v44, v13
	ds_bpermute_b32 v0, v137, v6
	v_mul_f32_e32 v10, v40, v5
	ds_bpermute_b32 v35, v137, v12
	v_mul_f32_e32 v28, v18, v41
	v_fmac_f32_e32 v10, v9, v43
	v_mul_f32_e32 v26, v16, v98
	v_mul_f32_e32 v27, v17, v38
	v_mul_f32_e32 v31, v40, v28
	v_mul_f32_e32 v9, v39, v10
	v_mul_f32_e32 v29, v96, v26
	v_mul_f32_e32 v30, v37, v27
	v_fmac_f32_e32 v9, v8, v42
	v_mul_f32_e32 v34, v39, v31
	v_mul_f32_e32 v32, v33, v29
	v_mul_f32_e32 v33, v36, v30
	s_waitcnt lgkmcnt(1)
	v_cndmask_b32_e64 v36, v0, v6, s[4:5]
	v_cndmask_b32_e64 v37, v6, v0, s[4:5]
	ds_bpermute_b32 v0, v137, v34
	ds_bpermute_b32 v40, v137, v9
	s_waitcnt lgkmcnt(2)
	v_cndmask_b32_e64 v8, v12, v35, s[4:5]
	v_fmac_f32_e32 v37, 0, v8
	ds_bpermute_b32 v8, v137, v33
	v_cndmask_b32_e64 v1, v35, v12, s[4:5]
	v_mul_f32_e32 v38, v12, v35
	v_fmac_f32_e32 v36, v1, v37
	s_waitcnt lgkmcnt(2)
	v_cndmask_b32_e64 v1, v0, v34, s[4:5]
	s_waitcnt lgkmcnt(1)
	v_cndmask_b32_e64 v39, v40, v9, s[4:5]
	v_cndmask_b32_e64 v0, v34, v0, s[4:5]
	v_cndmask_b32_e64 v40, v9, v40, s[4:5]
	ds_bpermute_b32 v44, v137, v22
	v_mul_f32_e32 v41, v38, v0
	v_fmac_f32_e32 v40, v0, v36
	v_mul_f32_e32 v42, v1, v41
	v_fmac_f32_e32 v39, v1, v40
	s_waitcnt lgkmcnt(1)
	v_cndmask_b32_e64 v0, v8, v33, s[4:5]
	v_cndmask_b32_e64 v1, v33, v8, s[4:5]
	ds_bpermute_b32 v8, v137, v32
	ds_bpermute_b32 v47, v137, v25
	s_waitcnt lgkmcnt(2)
	v_cndmask_b32_e64 v43, v44, v22, s[4:5]
	v_cndmask_b32_e64 v44, v22, v44, s[4:5]
	v_mul_f32_e32 v45, v1, v42
	v_fmac_f32_e32 v44, v1, v39
	v_mul_f32_e32 v46, v0, v45
	v_fmac_f32_e32 v43, v0, v44
	s_waitcnt lgkmcnt(1)
	v_cndmask_b32_e64 v0, v32, v8, s[4:5]
	s_waitcnt lgkmcnt(0)
	v_cndmask_b32_e64 v47, v25, v47, s[4:5]
	v_mul_f32_e32 v88, v0, v46
	v_fmac_f32_e32 v47, v0, v43
	s_and_saveexec_b64 s[6:7], s[4:5]
	v_mul_f32_e32 v0, v32, v88
	v_fma_f32 v1, v32, v47, v25
	ds_write_b64 v136, v[0:1]
	s_or_b64 exec, exec, s[6:7]
	s_cmp_lt_i32 s64, 7
	s_cselect_b64 s[14:15], -1, 0
	s_cmp_gt_i32 s64, 6
	v_mul_i32_i24_e32 v140, 0xffffff08, v93
	s_waitcnt lgkmcnt(0)
	s_barrier
	s_cbranch_scc1 .LBB0_269
	v_add3_u32 v94, v140, v91, s92
	v_mov_b32_e32 v8, 1.0
	v_mov_b32_e32 v1, 0
	s_mov_b32 s6, 7

.LBB0_272:
	s_or_b64 exec, exec, s[8:9]
	ds_read_b128 v[0:3], v145 offset:24576
	ds_read_b128 v[4:7], v145 offset:57344
	s_waitcnt lgkmcnt(1)
	v_mfma_f32_32x32x16_bf16 v[32:47], v[48:51], v[0:3], 0
	s_waitcnt lgkmcnt(0)
	v_mfma_f32_32x32x16_bf16 v[16:31], v[48:51], v[4:7], 0
	ds_read_b128 v[0:3], v147 offset:24576
	ds_read_b128 v[4:7], v147 offset:57344
	s_waitcnt lgkmcnt(1)
	v_mfma_f32_32x32x16_bf16 v[32:47], v[52:55], v[0:3], v[32:47]
	s_waitcnt lgkmcnt(0)
	v_mfma_f32_32x32x16_bf16 v[16:31], v[52:55], v[4:7], v[16:31]
	ds_read_b128 v[0:3], v142 offset:24576
	ds_read_b128 v[4:7], v142 offset:57344
	s_waitcnt lgkmcnt(1)
	v_mfma_f32_32x32x16_bf16 v[32:47], v[56:59], v[0:3], v[32:47]
	s_waitcnt lgkmcnt(0)
	v_mfma_f32_32x32x16_bf16 v[16:31], v[56:59], v[4:7], v[16:31]
	ds_read_b128 v[0:3], v146 offset:24576
	ds_read_b128 v[4:7], v146 offset:57344
	s_waitcnt lgkmcnt(1)
	v_mfma_f32_32x32x16_bf16 v[32:47], v[60:63], v[0:3], v[32:47]
	s_waitcnt lgkmcnt(0)
	v_mfma_f32_32x32x16_bf16 v[16:31], v[60:63], v[4:7], v[16:31]
	ds_read_b128 v[0:3], v141 offset:24576
	ds_read_b128 v[4:7], v141 offset:57344
	s_waitcnt lgkmcnt(1)
	v_mfma_f32_32x32x16_bf16 v[32:47], v[64:67], v[0:3], v[32:47]
	s_waitcnt lgkmcnt(0)
	v_mfma_f32_32x32x16_bf16 v[16:31], v[64:67], v[4:7], v[16:31]
	ds_read_b128 v[0:3], v144 offset:24576
	ds_read_b128 v[4:7], v144 offset:57344
	s_waitcnt lgkmcnt(1)
	v_mfma_f32_32x32x16_bf16 v[32:47], v[68:71], v[0:3], v[32:47]
	s_waitcnt lgkmcnt(0)
	v_mfma_f32_32x32x16_bf16 v[16:31], v[68:71], v[4:7], v[16:31]
	ds_read_b128 v[0:3], v139 offset:24576
	ds_read_b128 v[4:7], v139 offset:57344
	s_waitcnt lgkmcnt(1)
	v_mfma_f32_32x32x16_bf16 v[32:47], v[72:75], v[0:3], v[32:47]
	s_waitcnt lgkmcnt(0)
	v_mfma_f32_32x32x16_bf16 v[16:31], v[72:75], v[4:7], v[16:31]
	ds_read_b128 v[0:3], v143 offset:24576
	ds_read_b128 v[4:7], v143 offset:57344
	s_waitcnt lgkmcnt(1)
	v_mfma_f32_32x32x16_bf16 v[32:47], v[76:79], v[0:3], v[32:47]
	s_waitcnt lgkmcnt(0)
	v_mfma_f32_32x32x16_bf16 v[16:31], v[76:79], v[4:7], v[16:31]
	v_mfma_f32_32x32x16_bf16 v[0:15], v[56:59], v[80:83], 0
	v_mfma_f32_32x32x16_bf16 v[0:15], v[60:63], v[84:87], v[0:15]
	v_lshl_or_b32 v93, v138, 2, v133
	s_waitcnt vmcnt(16)
	ds_read_b32 v251, v167 offset:128
	v_mul_f32_e32 v148, 0xbfb8aa3b, v173
	v_mul_f32_e32 v93, 0xbfb8aa3b, v174
	v_fmamk_f32 v32, v32, 0xbfb8aa3b, v148
	v_fmamk_f32 v16, v16, 0xbfb8aa3b, v93
	v_exp_f32_e32 v32, v32
	v_exp_f32_e32 v150, v16
	v_fmamk_f32 v17, v17, 0xbfb8aa3b, v93
	v_exp_f32_e32 v151, v17
	v_add_f32_e32 v32, 1.0, v32
	v_add_f32_e32 v150, 1.0, v150
	v_rcp_f32_e32 v17, v32
	v_rcp_f32_e32 v32, v150
	v_fmamk_f32 v33, v33, 0xbfb8aa3b, v148
	v_fmamk_f32 v34, v34, 0xbfb8aa3b, v148
	v_exp_f32_e32 v33, v33
	v_exp_f32_e32 v34, v34
	v_add_f32_e32 v33, 1.0, v33
	v_add_f32_e32 v34, 1.0, v34
	v_rcp_f32_e32 v33, v33
	v_rcp_f32_e32 v34, v34
	v_fmamk_f32 v18, v18, 0xbfb8aa3b, v93
	v_fmamk_f32 v19, v19, 0xbfb8aa3b, v93
	v_exp_f32_e32 v18, v18
	s_waitcnt lgkmcnt(0)
	v_mul_f32_e32 v149, 0x3fb8aa3b, v251
	v_mul_f32_e32 v16, v17, v149
	v_mul_f32_e32 v17, v33, v149
	v_exp_f32_e32 v33, v16
	v_mul_f32_e32 v16, v34, v149
	v_exp_f32_e32 v152, v16
	v_fmamk_f32 v16, v35, 0xbfb8aa3b, v148
	v_exp_f32_e32 v16, v16
	v_exp_f32_e32 v150, v17
	v_add_f32_e32 v16, 1.0, v16
	v_rcp_f32_e32 v16, v16
	v_exp_f32_e32 v19, v19
	v_add_f32_e32 v151, 1.0, v151
	v_add_f32_e32 v18, 1.0, v18
	v_mul_f32_e32 v16, v16, v149
	v_exp_f32_e32 v16, v16
	v_fma_f32 v35, -v152, v152, 1.0
	v_rcp_f32_e32 v17, v151
	v_fma_f32 v34, -v33, v33, 1.0
	v_fma_f32 v151, -v150, v150, 1.0
	v_rcp_f32_e32 v18, v18
	v_sqrt_f32_e32 v35, v35
	v_add_f32_e32 v19, 1.0, v19
	v_fma_f32 v153, -v16, v16, 1.0
	v_sqrt_f32_e32 v34, v34
	v_sqrt_f32_e32 v151, v151
	v_rcp_f32_e32 v19, v19
	v_sqrt_f32_e32 v153, v153
	v_mul_f32_e32 v35, v18, v35
	v_fmamk_f32 v18, v36, 0xbfb8aa3b, v148
	v_mul_f32_e32 v32, v32, v34
	v_mul_f32_e32 v34, v17, v151
	v_mul_f32_e32 v17, v19, v153
	v_fmamk_f32 v19, v20, 0xbfb8aa3b, v93
	v_exp_f32_e32 v18, v18
	v_exp_f32_e32 v19, v19
	v_mul_f32_e32 v3, v3, v17
	v_add_f32_e32 v17, 1.0, v18
	v_rcp_f32_e32 v17, v17
	v_add_f32_e32 v18, 1.0, v19
	v_fmamk_f32 v19, v37, 0xbfb8aa3b, v148
	v_exp_f32_e32 v19, v19
	v_mul_f32_e32 v17, v17, v149
	v_exp_f32_e32 v36, v17
	v_add_f32_e32 v17, 1.0, v19
	v_rcp_f32_e32 v17, v17
	v_fmamk_f32 v19, v21, 0xbfb8aa3b, v93
	v_exp_f32_e32 v19, v19
	v_mul_f32_e32 v17, v17, v149
	v_exp_f32_e32 v37, v17
	v_fmamk_f32 v17, v38, 0xbfb8aa3b, v148
	v_exp_f32_e32 v17, v17
	v_fmamk_f32 v23, v23, 0xbfb8aa3b, v93
	v_add_f32_e32 v19, 1.0, v19
	v_fma_f32 v21, -v37, v37, 1.0
	v_add_f32_e32 v17, 1.0, v17
	v_rcp_f32_e32 v17, v17
	v_fma_f32 v20, -v36, v36, 1.0
	v_rcp_f32_e32 v19, v19
	v_mul_f32_e32 v17, v17, v149
	v_exp_f32_e32 v38, v17
	v_fmamk_f32 v17, v39, 0xbfb8aa3b, v148
	v_exp_f32_e32 v17, v17
	v_sqrt_f32_e32 v21, v21
	v_exp_f32_e32 v23, v23
	v_rcp_f32_e32 v18, v18
	v_add_f32_e32 v17, 1.0, v17
	v_rcp_f32_e32 v17, v17
	v_sqrt_f32_e32 v20, v20
	v_add_f32_e32 v23, 1.0, v23
	v_mul_f32_e32 v154, v19, v21
	v_mul_f32_e32 v17, v17, v149
	v_exp_f32_e32 v17, v17
	v_fmamk_f32 v19, v40, 0xbfb8aa3b, v148
	v_rcp_f32_e32 v23, v23
	v_mul_f32_e32 v153, v18, v20
	v_fma_f32 v151, -v17, v17, 1.0
	v_sqrt_f32_e32 v151, v151
	v_fmamk_f32 v20, v24, 0xbfb8aa3b, v93
	v_fmamk_f32 v22, v22, 0xbfb8aa3b, v93
	v_exp_f32_e32 v19, v19
	v_exp_f32_e32 v20, v20
	v_exp_f32_e32 v22, v22
	v_mul_f32_e32 v18, v23, v151
	v_mul_f32_e32 v7, v7, v18
	v_add_f32_e32 v18, 1.0, v19
	v_rcp_f32_e32 v18, v18
	v_add_f32_e32 v19, 1.0, v20
	v_fmamk_f32 v20, v41, 0xbfb8aa3b, v148
	v_add_f32_e32 v22, 1.0, v22
	v_fma_f32 v39, -v38, v38, 1.0
	v_rcp_f32_e32 v22, v22
	v_sqrt_f32_e32 v39, v39
	v_exp_f32_e32 v20, v20
	v_mul_f32_e32 v18, v18, v149
	v_mul_f32_e32 v21, v22, v39
	v_exp_f32_e32 v39, v18
	v_add_f32_e32 v18, 1.0, v20
	v_rcp_f32_e32 v18, v18
	v_fmamk_f32 v20, v25, 0xbfb8aa3b, v93
	v_exp_f32_e32 v20, v20
	v_mul_f32_e32 v18, v18, v149
	v_exp_f32_e32 v40, v18
	v_fmamk_f32 v18, v42, 0xbfb8aa3b, v148
	v_exp_f32_e32 v18, v18
	v_fmamk_f32 v24, v26, 0xbfb8aa3b, v93
	v_fmamk_f32 v26, v27, 0xbfb8aa3b, v93
	v_add_f32_e32 v20, 1.0, v20
	v_add_f32_e32 v18, 1.0, v18
	v_rcp_f32_e32 v18, v18
	v_fma_f32 v23, -v40, v40, 1.0
	v_fma_f32 v22, -v39, v39, 1.0
	v_mul_f32_e32 v18, v18, v149
	v_exp_f32_e32 v41, v18
	v_fmamk_f32 v18, v43, 0xbfb8aa3b, v148
	v_exp_f32_e32 v18, v18
	v_rcp_f32_e32 v20, v20
	v_sqrt_f32_e32 v23, v23
	v_exp_f32_e32 v26, v26
	v_add_f32_e32 v18, 1.0, v18
	v_rcp_f32_e32 v18, v18
	v_rcp_f32_e32 v19, v19
	v_sqrt_f32_e32 v22, v22
	v_add_f32_e32 v26, 1.0, v26
	v_mul_f32_e32 v18, v18, v149
	v_exp_f32_e32 v18, v18
	v_mul_f32_e32 v43, v20, v23
	v_fmamk_f32 v20, v44, 0xbfb8aa3b, v148
	v_rcp_f32_e32 v26, v26
	v_fma_f32 v27, -v18, v18, 1.0
	v_sqrt_f32_e32 v27, v27
	v_mul_f32_e32 v42, v19, v22
	v_fmamk_f32 v22, v28, 0xbfb8aa3b, v93
	v_exp_f32_e32 v20, v20
	v_exp_f32_e32 v22, v22
	v_mul_f32_e32 v19, v26, v27
	v_mul_f32_e32 v11, v11, v19
	v_add_f32_e32 v19, 1.0, v20
	v_rcp_f32_e32 v19, v19
	v_add_f32_e32 v20, 1.0, v22
	v_fmamk_f32 v22, v45, 0xbfb8aa3b, v148
	v_exp_f32_e32 v22, v22
	v_mul_f32_e32 v19, v19, v149
	v_exp_f32_e32 v44, v19
	v_add_f32_e32 v19, 1.0, v22
	v_rcp_f32_e32 v19, v19
	v_exp_f32_e32 v24, v24
	v_fmamk_f32 v22, v29, 0xbfb8aa3b, v93
	v_mul_f32_e32 v19, v19, v149
	v_exp_f32_e32 v45, v19
	v_fmamk_f32 v19, v46, 0xbfb8aa3b, v148
	v_exp_f32_e32 v19, v19
	v_add_f32_e32 v24, 1.0, v24
	v_fma_f32 v25, -v41, v41, 1.0
	v_add_f32_e32 v19, 1.0, v19
	v_rcp_f32_e32 v19, v19
	v_exp_f32_e32 v22, v22
	v_rcp_f32_e32 v24, v24
	v_sqrt_f32_e32 v25, v25
	v_mul_f32_e32 v19, v19, v149
	v_exp_f32_e32 v46, v19
	v_fmamk_f32 v19, v47, 0xbfb8aa3b, v148
	v_add_f32_e32 v22, 1.0, v22
	v_exp_f32_e32 v19, v19
	v_mul_f32_e32 v151, v24, v25
	v_rcp_f32_e32 v24, v22
	v_fma_f32 v22, -v45, v45, 1.0
	v_sqrt_f32_e32 v25, v22
	v_fmamk_f32 v22, v30, 0xbfb8aa3b, v93
	v_exp_f32_e32 v22, v22
	v_add_f32_e32 v19, 1.0, v19
	v_rcp_f32_e32 v19, v19
	v_fma_f32 v27, -v46, v46, 1.0
	v_add_f32_e32 v22, 1.0, v22
	v_rcp_f32_e32 v26, v22
	v_fmamk_f32 v22, v31, 0xbfb8aa3b, v93
	v_mul_f32_e32 v19, v19, v149
	v_exp_f32_e32 v28, v22
	v_exp_f32_e32 v22, v19
	v_sqrt_f32_e32 v19, v27
	v_fma_f32 v23, -v44, v44, 1.0
	v_add_f32_e32 v27, 1.0, v28
	v_fma_f32 v28, -v22, v22, 1.0
	v_rcp_f32_e32 v27, v27
	v_sqrt_f32_e32 v28, v28
	v_rcp_f32_e32 v20, v20
	v_sqrt_f32_e32 v23, v23
	v_mul_f32_e32 v148, v26, v19
	v_mul_f32_e32 v19, v27, v28
	v_fmac_f32_e32 v7, 0, v17
	v_mul_f32_e32 v15, v15, v19
	v_mul_f32_e32 v19, v38, v7
	v_fmac_f32_e32 v19, v6, v21
	v_fmac_f32_e32 v3, 0, v16
	v_mul_f32_e32 v21, v37, v19
	v_mul_f32_e32 v47, v20, v23
	v_mul_f32_e32 v20, v152, v3
	v_fmac_f32_e32 v21, v5, v154
	v_fmac_f32_e32 v15, 0, v22
	v_mul_f32_e32 v93, v24, v25
	v_fmac_f32_e32 v20, v2, v35
	v_mul_f32_e32 v24, v36, v21
	v_fmac_f32_e32 v11, 0, v18
	v_mul_f32_e32 v2, v46, v15
	v_fmac_f32_e32 v24, v4, v153
	v_mul_f32_e32 v4, v41, v11
	v_fmac_f32_e32 v2, v14, v148
	v_fmac_f32_e32 v4, v10, v151
	v_mul_f32_e32 v5, v45, v2
	v_mul_f32_e32 v23, v150, v20
	v_mul_f32_e32 v6, v40, v4
	v_fmac_f32_e32 v5, v13, v93
	v_fmac_f32_e32 v23, v1, v34
	v_fmac_f32_e32 v6, v9, v43
	v_mul_f32_e32 v14, v22, v46
	v_mul_f32_e32 v9, v44, v5
	v_mul_f32_e32 v25, v33, v23
	v_mul_f32_e32 v13, v45, v14
	v_fmac_f32_e32 v9, v12, v47
	v_fmac_f32_e32 v25, v0, v32
	v_mul_f32_e32 v12, v44, v13
	ds_bpermute_b32 v0, v137, v9
	ds_bpermute_b32 v35, v137, v12
	v_mul_f32_e32 v28, v18, v41
	v_mul_f32_e32 v26, v16, v152
	v_mul_f32_e32 v27, v17, v38
	v_mul_f32_e32 v31, v40, v28
	v_mul_f32_e32 v10, v39, v6
	v_mul_f32_e32 v29, v150, v26
	v_mul_f32_e32 v30, v37, v27
	v_fmac_f32_e32 v10, v8, v42
	v_mul_f32_e32 v34, v39, v31
	v_mul_f32_e32 v32, v33, v29
	v_mul_f32_e32 v33, v36, v30
	s_waitcnt lgkmcnt(1)
	v_cndmask_b32_e64 v36, v0, v9, s[4:5]
	v_cndmask_b32_e64 v37, v9, v0, s[4:5]
	ds_bpermute_b32 v0, v137, v34
	ds_bpermute_b32 v40, v137, v10
	s_waitcnt lgkmcnt(2)
	v_cndmask_b32_e64 v8, v12, v35, s[4:5]
	v_fmac_f32_e32 v37, 0, v8
	ds_bpermute_b32 v8, v137, v33
	v_cndmask_b32_e64 v1, v35, v12, s[4:5]
	v_mul_f32_e32 v38, v12, v35
	v_fmac_f32_e32 v36, v1, v37
	s_waitcnt lgkmcnt(2)
	v_cndmask_b32_e64 v1, v0, v34, s[4:5]
	s_waitcnt lgkmcnt(1)
	v_cndmask_b32_e64 v39, v40, v10, s[4:5]
	v_cndmask_b32_e64 v0, v34, v0, s[4:5]
	v_cndmask_b32_e64 v40, v10, v40, s[4:5]
	ds_bpermute_b32 v44, v137, v24
	v_mul_f32_e32 v41, v38, v0
	v_fmac_f32_e32 v40, v0, v36
	v_mul_f32_e32 v42, v1, v41
	v_fmac_f32_e32 v39, v1, v40
	s_waitcnt lgkmcnt(1)
	v_cndmask_b32_e64 v0, v8, v33, s[4:5]
	v_cndmask_b32_e64 v1, v33, v8, s[4:5]
	ds_bpermute_b32 v8, v137, v32
	ds_bpermute_b32 v47, v137, v25
	s_waitcnt lgkmcnt(2)
	v_cndmask_b32_e64 v43, v44, v24, s[4:5]
	v_cndmask_b32_e64 v44, v24, v44, s[4:5]
	v_mul_f32_e32 v45, v1, v42
	v_fmac_f32_e32 v44, v1, v39
	v_mul_f32_e32 v46, v0, v45
	v_fmac_f32_e32 v43, v0, v44
	s_waitcnt lgkmcnt(1)
	v_cndmask_b32_e64 v0, v32, v8, s[4:5]
	s_waitcnt lgkmcnt(0)
	v_cndmask_b32_e64 v47, v25, v47, s[4:5]
	v_mul_f32_e32 v93, v0, v46
	v_fmac_f32_e32 v47, v0, v43
	s_and_saveexec_b64 s[8:9], s[4:5]
	v_mul_f32_e32 v0, v32, v93
	v_fma_f32 v1, v32, v47, v25
	ds_write_b64 v136, v[0:1] offset:2048
	s_or_b64 exec, exec, s[8:9]
	v_cndmask_b32_e64 v0, 0, 1, s[14:15]
	v_cmp_ne_u32_e64 s[8:9], 1, v0
	s_andn2_b64 vcc, exec, s[14:15]
	s_waitcnt lgkmcnt(0)
	s_barrier
	s_cbranch_vccnz .LBB0_277
	v_add3_u32 v148, v140, v91, s93
	v_mov_b32_e32 v8, 1.0
	v_mov_b32_e32 v1, 0
	s_mov_b32 s12, 7

.LBB0_280:
	s_or_b64 exec, exec, s[12:13]
	ds_read_b128 v[0:3], v145 offset:32768
	ds_read_b128 v[4:7], v147 offset:32768
	v_add_u32_e32 v8, 0x8000, v147
	s_waitcnt lgkmcnt(1)
	v_mfma_f32_32x32x16_bf16 v[32:47], v[48:51], v[0:3], 0
	v_add_u32_e32 v0, 0x8000, v145
	ds_read_b128 v[0:3], v0 offset:32768
	ds_read_b128 v[8:11], v8 offset:32768
	s_waitcnt lgkmcnt(1)
	v_mfma_f32_32x32x16_bf16 v[16:31], v[48:51], v[0:3], 0
	v_mfma_f32_32x32x16_bf16 v[32:47], v[52:55], v[4:7], v[32:47]
	ds_read_b128 v[0:3], v142 offset:32768
	ds_read_b128 v[4:7], v146 offset:32768
	s_waitcnt lgkmcnt(2)
	v_mfma_f32_32x32x16_bf16 v[16:31], v[52:55], v[8:11], v[16:31]
	v_add_u32_e32 v8, 0x8000, v146
	ds_read_b128 v[8:11], v8 offset:32768
	s_waitcnt lgkmcnt(2)
	v_mfma_f32_32x32x16_bf16 v[32:47], v[56:59], v[0:3], v[32:47]
	v_add_u32_e32 v0, 0x8000, v142
	ds_read_b128 v[0:3], v0 offset:32768
	s_waitcnt lgkmcnt(0)
	v_mfma_f32_32x32x16_bf16 v[16:31], v[56:59], v[0:3], v[16:31]
	v_mfma_f32_32x32x16_bf16 v[32:47], v[60:63], v[4:7], v[32:47]
	ds_read_b128 v[0:3], v141 offset:32768
	ds_read_b128 v[4:7], v144 offset:32768
	v_mfma_f32_32x32x16_bf16 v[16:31], v[60:63], v[8:11], v[16:31]
	v_add_u32_e32 v8, 0x8000, v144
	ds_read_b128 v[8:11], v8 offset:32768
	s_waitcnt lgkmcnt(2)
	v_mfma_f32_32x32x16_bf16 v[32:47], v[64:67], v[0:3], v[32:47]
	v_add_u32_e32 v0, 0x8000, v141
	ds_read_b128 v[0:3], v0 offset:32768
	s_waitcnt lgkmcnt(0)
	v_mfma_f32_32x32x16_bf16 v[16:31], v[64:67], v[0:3], v[16:31]
	v_mfma_f32_32x32x16_bf16 v[32:47], v[68:71], v[4:7], v[32:47]
	ds_read_b128 v[0:3], v139 offset:32768
	ds_read_b128 v[4:7], v143 offset:32768
	v_mfma_f32_32x32x16_bf16 v[16:31], v[68:71], v[8:11], v[16:31]
	v_add_u32_e32 v8, 0x8000, v143
	ds_read_b128 v[8:11], v8 offset:32768
	s_waitcnt lgkmcnt(2)
	v_mfma_f32_32x32x16_bf16 v[32:47], v[72:75], v[0:3], v[32:47]
	v_add_u32_e32 v0, 0x8000, v139
	ds_read_b128 v[0:3], v0 offset:32768
	s_waitcnt lgkmcnt(0)
	v_mfma_f32_32x32x16_bf16 v[16:31], v[72:75], v[0:3], v[16:31]
	v_mfma_f32_32x32x16_bf16 v[32:47], v[76:79], v[4:7], v[32:47]
	v_mfma_f32_32x32x16_bf16 v[16:31], v[76:79], v[8:11], v[16:31]
	v_mfma_f32_32x32x16_bf16 v[0:15], v[64:67], v[80:83], 0
	v_mfma_f32_32x32x16_bf16 v[0:15], v[68:71], v[84:87], v[0:15]
	v_lshl_or_b32 v93, v138, 2, v134
	s_waitcnt vmcnt(16)
	ds_read_b32 v251, v167 offset:256
	v_mul_f32_e32 v148, 0xbfb8aa3b, v173
	v_mul_f32_e32 v93, 0xbfb8aa3b, v174
	v_fmamk_f32 v32, v32, 0xbfb8aa3b, v148
	v_fmamk_f32 v16, v16, 0xbfb8aa3b, v93
	v_exp_f32_e32 v32, v32
	v_exp_f32_e32 v150, v16
	v_fmamk_f32 v17, v17, 0xbfb8aa3b, v93
	v_exp_f32_e32 v151, v17
	v_add_f32_e32 v32, 1.0, v32
	v_add_f32_e32 v150, 1.0, v150
	v_rcp_f32_e32 v17, v32
	v_rcp_f32_e32 v32, v150
	v_fmamk_f32 v33, v33, 0xbfb8aa3b, v148
	v_fmamk_f32 v34, v34, 0xbfb8aa3b, v148
	v_exp_f32_e32 v33, v33
	v_exp_f32_e32 v34, v34
	v_add_f32_e32 v33, 1.0, v33
	v_add_f32_e32 v34, 1.0, v34
	v_rcp_f32_e32 v33, v33
	v_rcp_f32_e32 v34, v34
	v_fmamk_f32 v18, v18, 0xbfb8aa3b, v93
	v_fmamk_f32 v19, v19, 0xbfb8aa3b, v93
	v_exp_f32_e32 v18, v18
	s_waitcnt lgkmcnt(0)
	v_mul_f32_e32 v149, 0x3fb8aa3b, v251
	v_mul_f32_e32 v16, v17, v149
	v_mul_f32_e32 v17, v33, v149
	v_exp_f32_e32 v33, v16
	v_mul_f32_e32 v16, v34, v149
	v_exp_f32_e32 v152, v16
	v_fmamk_f32 v16, v35, 0xbfb8aa3b, v148
	v_exp_f32_e32 v16, v16
	v_exp_f32_e32 v150, v17
	v_add_f32_e32 v16, 1.0, v16
	v_rcp_f32_e32 v16, v16
	v_exp_f32_e32 v19, v19
	v_add_f32_e32 v151, 1.0, v151
	v_add_f32_e32 v18, 1.0, v18
	v_mul_f32_e32 v16, v16, v149
	v_exp_f32_e32 v16, v16
	v_fma_f32 v35, -v152, v152, 1.0
	v_rcp_f32_e32 v17, v151
	v_fma_f32 v34, -v33, v33, 1.0
	v_fma_f32 v151, -v150, v150, 1.0
	v_rcp_f32_e32 v18, v18
	v_sqrt_f32_e32 v35, v35
	v_add_f32_e32 v19, 1.0, v19
	v_fma_f32 v153, -v16, v16, 1.0
	v_sqrt_f32_e32 v34, v34
	v_sqrt_f32_e32 v151, v151
	v_rcp_f32_e32 v19, v19
	v_sqrt_f32_e32 v153, v153
	v_mul_f32_e32 v35, v18, v35
	v_fmamk_f32 v18, v36, 0xbfb8aa3b, v148
	v_mul_f32_e32 v32, v32, v34
	v_mul_f32_e32 v34, v17, v151
	v_mul_f32_e32 v17, v19, v153
	v_fmamk_f32 v19, v20, 0xbfb8aa3b, v93
	v_exp_f32_e32 v18, v18
	v_exp_f32_e32 v19, v19
	v_mul_f32_e32 v3, v3, v17
	v_add_f32_e32 v17, 1.0, v18
	v_rcp_f32_e32 v17, v17
	v_add_f32_e32 v18, 1.0, v19
	v_fmamk_f32 v19, v37, 0xbfb8aa3b, v148
	v_exp_f32_e32 v19, v19
	v_mul_f32_e32 v17, v17, v149
	v_exp_f32_e32 v36, v17
	v_add_f32_e32 v17, 1.0, v19
	v_rcp_f32_e32 v17, v17
	v_fmamk_f32 v19, v21, 0xbfb8aa3b, v93
	v_exp_f32_e32 v19, v19
	v_mul_f32_e32 v17, v17, v149
	v_exp_f32_e32 v37, v17
	v_fmamk_f32 v17, v38, 0xbfb8aa3b, v148
	v_exp_f32_e32 v17, v17
	v_fmamk_f32 v23, v23, 0xbfb8aa3b, v93
	v_add_f32_e32 v19, 1.0, v19
	v_fma_f32 v21, -v37, v37, 1.0
	v_add_f32_e32 v17, 1.0, v17
	v_rcp_f32_e32 v17, v17
	v_fma_f32 v20, -v36, v36, 1.0
	v_rcp_f32_e32 v19, v19
	v_mul_f32_e32 v17, v17, v149
	v_exp_f32_e32 v38, v17
	v_fmamk_f32 v17, v39, 0xbfb8aa3b, v148
	v_exp_f32_e32 v17, v17
	v_sqrt_f32_e32 v21, v21
	v_exp_f32_e32 v23, v23
	v_rcp_f32_e32 v18, v18
	v_add_f32_e32 v17, 1.0, v17
	v_rcp_f32_e32 v17, v17
	v_sqrt_f32_e32 v20, v20
	v_add_f32_e32 v23, 1.0, v23
	v_mul_f32_e32 v154, v19, v21
	v_mul_f32_e32 v17, v17, v149
	v_exp_f32_e32 v17, v17
	v_fmamk_f32 v19, v40, 0xbfb8aa3b, v148
	v_rcp_f32_e32 v23, v23
	v_mul_f32_e32 v153, v18, v20
	v_fma_f32 v151, -v17, v17, 1.0
	v_sqrt_f32_e32 v151, v151
	v_fmamk_f32 v20, v24, 0xbfb8aa3b, v93
	v_fmamk_f32 v22, v22, 0xbfb8aa3b, v93
	v_exp_f32_e32 v19, v19
	v_exp_f32_e32 v20, v20
	v_exp_f32_e32 v22, v22
	v_mul_f32_e32 v18, v23, v151
	v_mul_f32_e32 v7, v7, v18
	v_add_f32_e32 v18, 1.0, v19
	v_rcp_f32_e32 v18, v18
	v_add_f32_e32 v19, 1.0, v20
	v_fmamk_f32 v20, v41, 0xbfb8aa3b, v148
	v_add_f32_e32 v22, 1.0, v22
	v_fma_f32 v39, -v38, v38, 1.0
	v_rcp_f32_e32 v22, v22
	v_sqrt_f32_e32 v39, v39
	v_exp_f32_e32 v20, v20
	v_mul_f32_e32 v18, v18, v149
	v_mul_f32_e32 v21, v22, v39
	v_exp_f32_e32 v39, v18
	v_add_f32_e32 v18, 1.0, v20
	v_rcp_f32_e32 v18, v18
	v_fmamk_f32 v20, v25, 0xbfb8aa3b, v93
	v_exp_f32_e32 v20, v20
	v_mul_f32_e32 v18, v18, v149
	v_exp_f32_e32 v40, v18
	v_fmamk_f32 v18, v42, 0xbfb8aa3b, v148
	v_exp_f32_e32 v18, v18
	v_fmamk_f32 v24, v26, 0xbfb8aa3b, v93
	v_fmamk_f32 v26, v27, 0xbfb8aa3b, v93
	v_add_f32_e32 v20, 1.0, v20
	v_add_f32_e32 v18, 1.0, v18
	v_rcp_f32_e32 v18, v18
	v_fma_f32 v23, -v40, v40, 1.0
	v_fma_f32 v22, -v39, v39, 1.0
	v_mul_f32_e32 v18, v18, v149
	v_exp_f32_e32 v41, v18
	v_fmamk_f32 v18, v43, 0xbfb8aa3b, v148
	v_exp_f32_e32 v18, v18
	v_rcp_f32_e32 v20, v20
	v_sqrt_f32_e32 v23, v23
	v_exp_f32_e32 v26, v26
	v_add_f32_e32 v18, 1.0, v18
	v_rcp_f32_e32 v18, v18
	v_rcp_f32_e32 v19, v19
	v_sqrt_f32_e32 v22, v22
	v_add_f32_e32 v26, 1.0, v26
	v_mul_f32_e32 v18, v18, v149
	v_exp_f32_e32 v18, v18
	v_mul_f32_e32 v43, v20, v23
	v_fmamk_f32 v20, v44, 0xbfb8aa3b, v148
	v_rcp_f32_e32 v26, v26
	v_fma_f32 v27, -v18, v18, 1.0
	v_sqrt_f32_e32 v27, v27
	v_mul_f32_e32 v42, v19, v22
	v_fmamk_f32 v22, v28, 0xbfb8aa3b, v93
	v_exp_f32_e32 v20, v20
	v_exp_f32_e32 v22, v22
	v_mul_f32_e32 v19, v26, v27
	v_mul_f32_e32 v11, v11, v19
	v_add_f32_e32 v19, 1.0, v20
	v_rcp_f32_e32 v19, v19
	v_add_f32_e32 v20, 1.0, v22
	v_fmamk_f32 v22, v45, 0xbfb8aa3b, v148
	v_exp_f32_e32 v22, v22
	v_mul_f32_e32 v19, v19, v149
	v_exp_f32_e32 v44, v19
	v_add_f32_e32 v19, 1.0, v22
	v_rcp_f32_e32 v19, v19
	v_exp_f32_e32 v24, v24
	v_fmamk_f32 v22, v29, 0xbfb8aa3b, v93
	v_mul_f32_e32 v19, v19, v149
	v_exp_f32_e32 v45, v19
	v_fmamk_f32 v19, v46, 0xbfb8aa3b, v148
	v_exp_f32_e32 v19, v19
	v_add_f32_e32 v24, 1.0, v24
	v_fma_f32 v25, -v41, v41, 1.0
	v_add_f32_e32 v19, 1.0, v19
	v_rcp_f32_e32 v19, v19
	v_exp_f32_e32 v22, v22
	v_rcp_f32_e32 v24, v24
	v_sqrt_f32_e32 v25, v25
	v_mul_f32_e32 v19, v19, v149
	v_exp_f32_e32 v46, v19
	v_fmamk_f32 v19, v47, 0xbfb8aa3b, v148
	v_add_f32_e32 v22, 1.0, v22
	v_exp_f32_e32 v19, v19
	v_mul_f32_e32 v151, v24, v25
	v_rcp_f32_e32 v24, v22
	v_fma_f32 v22, -v45, v45, 1.0
	v_sqrt_f32_e32 v25, v22
	v_fmamk_f32 v22, v30, 0xbfb8aa3b, v93
	v_exp_f32_e32 v22, v22
	v_add_f32_e32 v19, 1.0, v19
	v_rcp_f32_e32 v19, v19
	v_fma_f32 v27, -v46, v46, 1.0
	v_add_f32_e32 v22, 1.0, v22
	v_rcp_f32_e32 v26, v22
	v_fmamk_f32 v22, v31, 0xbfb8aa3b, v93
	v_mul_f32_e32 v19, v19, v149
	v_exp_f32_e32 v28, v22
	v_exp_f32_e32 v22, v19
	v_sqrt_f32_e32 v19, v27
	v_fma_f32 v23, -v44, v44, 1.0
	v_add_f32_e32 v27, 1.0, v28
	v_fma_f32 v28, -v22, v22, 1.0
	v_rcp_f32_e32 v27, v27
	v_sqrt_f32_e32 v28, v28
	v_rcp_f32_e32 v20, v20
	v_sqrt_f32_e32 v23, v23
	v_mul_f32_e32 v148, v26, v19
	v_mul_f32_e32 v19, v27, v28
	v_fmac_f32_e32 v7, 0, v17
	v_mul_f32_e32 v15, v15, v19
	v_mul_f32_e32 v19, v38, v7
	v_fmac_f32_e32 v19, v6, v21
	v_fmac_f32_e32 v3, 0, v16
	v_mul_f32_e32 v21, v37, v19
	v_mul_f32_e32 v47, v20, v23
	v_mul_f32_e32 v20, v152, v3
	v_fmac_f32_e32 v21, v5, v154
	v_fmac_f32_e32 v15, 0, v22
	v_mul_f32_e32 v93, v24, v25
	v_fmac_f32_e32 v20, v2, v35
	v_mul_f32_e32 v24, v36, v21
	v_fmac_f32_e32 v11, 0, v18
	v_mul_f32_e32 v2, v46, v15
	v_fmac_f32_e32 v24, v4, v153
	v_mul_f32_e32 v4, v41, v11
	v_fmac_f32_e32 v2, v14, v148
	v_fmac_f32_e32 v4, v10, v151
	v_mul_f32_e32 v5, v45, v2
	v_mul_f32_e32 v23, v150, v20
	v_mul_f32_e32 v6, v40, v4
	v_fmac_f32_e32 v5, v13, v93
	v_fmac_f32_e32 v23, v1, v34
	v_fmac_f32_e32 v6, v9, v43
	v_mul_f32_e32 v14, v22, v46
	v_mul_f32_e32 v9, v44, v5
	v_mul_f32_e32 v25, v33, v23
	v_mul_f32_e32 v13, v45, v14
	v_fmac_f32_e32 v9, v12, v47
	v_fmac_f32_e32 v25, v0, v32
	v_mul_f32_e32 v12, v44, v13
	ds_bpermute_b32 v0, v137, v9
	ds_bpermute_b32 v35, v137, v12
	v_mul_f32_e32 v28, v18, v41
	v_mul_f32_e32 v26, v16, v152
	v_mul_f32_e32 v27, v17, v38
	v_mul_f32_e32 v31, v40, v28
	v_mul_f32_e32 v10, v39, v6
	v_mul_f32_e32 v29, v150, v26
	v_mul_f32_e32 v30, v37, v27
	v_fmac_f32_e32 v10, v8, v42
	v_mul_f32_e32 v34, v39, v31
	v_mul_f32_e32 v32, v33, v29
	v_mul_f32_e32 v33, v36, v30
	s_waitcnt lgkmcnt(1)
	v_cndmask_b32_e64 v36, v0, v9, s[4:5]
	v_cndmask_b32_e64 v37, v9, v0, s[4:5]
	ds_bpermute_b32 v0, v137, v34
	ds_bpermute_b32 v40, v137, v10
	s_waitcnt lgkmcnt(2)
	v_cndmask_b32_e64 v8, v12, v35, s[4:5]
	v_fmac_f32_e32 v37, 0, v8
	ds_bpermute_b32 v8, v137, v33
	v_cndmask_b32_e64 v1, v35, v12, s[4:5]
	v_mul_f32_e32 v38, v12, v35
	v_fmac_f32_e32 v36, v1, v37
	s_waitcnt lgkmcnt(2)
	v_cndmask_b32_e64 v1, v0, v34, s[4:5]
	s_waitcnt lgkmcnt(1)
	v_cndmask_b32_e64 v39, v40, v10, s[4:5]
	v_cndmask_b32_e64 v0, v34, v0, s[4:5]
	v_cndmask_b32_e64 v40, v10, v40, s[4:5]
	ds_bpermute_b32 v44, v137, v24
	v_mul_f32_e32 v41, v38, v0
	v_fmac_f32_e32 v40, v0, v36
	v_mul_f32_e32 v42, v1, v41
	v_fmac_f32_e32 v39, v1, v40
	s_waitcnt lgkmcnt(1)
	v_cndmask_b32_e64 v0, v8, v33, s[4:5]
	v_cndmask_b32_e64 v1, v33, v8, s[4:5]
	ds_bpermute_b32 v8, v137, v32
	ds_bpermute_b32 v47, v137, v25
	s_waitcnt lgkmcnt(2)
	v_cndmask_b32_e64 v43, v44, v24, s[4:5]
	v_cndmask_b32_e64 v44, v24, v44, s[4:5]
	v_mul_f32_e32 v45, v1, v42
	v_fmac_f32_e32 v44, v1, v39
	v_mul_f32_e32 v46, v0, v45
	v_fmac_f32_e32 v43, v0, v44
	s_waitcnt lgkmcnt(1)
	v_cndmask_b32_e64 v0, v32, v8, s[4:5]
	s_waitcnt lgkmcnt(0)
	v_cndmask_b32_e64 v47, v25, v47, s[4:5]
	v_mul_f32_e32 v93, v0, v46
	v_fmac_f32_e32 v47, v0, v43
	s_and_saveexec_b64 s[12:13], s[4:5]
	v_mul_f32_e32 v0, v32, v93
	v_fma_f32 v1, v32, v47, v25
	ds_write_b64 v136, v[0:1] offset:4096
	s_or_b64 exec, exec, s[12:13]
	s_and_b64 vcc, exec, s[8:9]
	s_waitcnt lgkmcnt(0)
	s_barrier
	s_cbranch_vccnz .LBB0_285
	v_add3_u32 v148, v140, v91, s94
	v_mov_b32_e32 v8, 1.0
	v_mov_b32_e32 v1, 0
	s_mov_b32 s12, 7

.LBB0_288:
	s_or_b64 exec, exec, s[12:13]
	ds_read_b128 v[0:3], v145 offset:40960
	ds_read_b128 v[4:7], v147 offset:40960
	v_add_u32_e32 v8, 0xa000, v147
	s_waitcnt lgkmcnt(1)
	v_mfma_f32_32x32x16_bf16 v[32:47], v[48:51], v[0:3], 0
	v_add_u32_e32 v0, 0xa000, v145
	ds_read_b128 v[0:3], v0 offset:32768
	ds_read_b128 v[8:11], v8 offset:32768
	s_waitcnt lgkmcnt(1)
	v_mfma_f32_32x32x16_bf16 v[16:31], v[48:51], v[0:3], 0
	v_mfma_f32_32x32x16_bf16 v[32:47], v[52:55], v[4:7], v[32:47]
	ds_read_b128 v[0:3], v142 offset:40960
	ds_read_b128 v[4:7], v146 offset:40960
	s_waitcnt lgkmcnt(2)
	v_mfma_f32_32x32x16_bf16 v[16:31], v[52:55], v[8:11], v[16:31]
	v_add_u32_e32 v8, 0xa000, v146
	ds_read_b128 v[8:11], v8 offset:32768
	s_waitcnt lgkmcnt(2)
	v_mfma_f32_32x32x16_bf16 v[32:47], v[56:59], v[0:3], v[32:47]
	v_add_u32_e32 v0, 0xa000, v142
	ds_read_b128 v[0:3], v0 offset:32768
	s_waitcnt lgkmcnt(0)
	v_mfma_f32_32x32x16_bf16 v[16:31], v[56:59], v[0:3], v[16:31]
	v_mfma_f32_32x32x16_bf16 v[32:47], v[60:63], v[4:7], v[32:47]
	ds_read_b128 v[0:3], v141 offset:40960
	ds_read_b128 v[4:7], v144 offset:40960
	v_mfma_f32_32x32x16_bf16 v[16:31], v[60:63], v[8:11], v[16:31]
	v_add_u32_e32 v8, 0xa000, v144
	ds_read_b128 v[8:11], v8 offset:32768
	s_waitcnt lgkmcnt(2)
	v_mfma_f32_32x32x16_bf16 v[32:47], v[64:67], v[0:3], v[32:47]
	v_add_u32_e32 v0, 0xa000, v141
	ds_read_b128 v[0:3], v0 offset:32768
	s_waitcnt lgkmcnt(0)
	v_mfma_f32_32x32x16_bf16 v[16:31], v[64:67], v[0:3], v[16:31]
	v_mfma_f32_32x32x16_bf16 v[32:47], v[68:71], v[4:7], v[32:47]
	ds_read_b128 v[0:3], v139 offset:40960
	ds_read_b128 v[4:7], v143 offset:40960
	v_mfma_f32_32x32x16_bf16 v[16:31], v[68:71], v[8:11], v[16:31]
	v_add_u32_e32 v8, 0xa000, v143
	ds_read_b128 v[8:11], v8 offset:32768
	s_waitcnt lgkmcnt(2)
	v_mfma_f32_32x32x16_bf16 v[32:47], v[72:75], v[0:3], v[32:47]
	v_add_u32_e32 v0, 0xa000, v139
	ds_read_b128 v[0:3], v0 offset:32768
	s_waitcnt lgkmcnt(0)
	v_mfma_f32_32x32x16_bf16 v[16:31], v[72:75], v[0:3], v[16:31]
	v_mfma_f32_32x32x16_bf16 v[32:47], v[76:79], v[4:7], v[32:47]
	v_mfma_f32_32x32x16_bf16 v[16:31], v[76:79], v[8:11], v[16:31]
	v_mfma_f32_32x32x16_bf16 v[0:15], v[72:75], v[80:83], 0
	v_mfma_f32_32x32x16_bf16 v[0:15], v[76:79], v[84:87], v[0:15]
	v_lshl_or_b32 v48, v138, 2, v135
	s_waitcnt vmcnt(16)
	ds_read_b32 v251, v167 offset:384
	v_mul_f32_e32 v49, 0xbfb8aa3b, v173
	v_mul_f32_e32 v48, 0xbfb8aa3b, v174
	v_fmamk_f32 v32, v32, 0xbfb8aa3b, v49
	v_fmamk_f32 v16, v16, 0xbfb8aa3b, v48
	v_exp_f32_e32 v32, v32
	v_exp_f32_e32 v51, v16
	v_fmamk_f32 v17, v17, 0xbfb8aa3b, v48
	v_exp_f32_e32 v52, v17
	v_add_f32_e32 v32, 1.0, v32
	v_add_f32_e32 v51, 1.0, v51
	v_rcp_f32_e32 v17, v32
	v_rcp_f32_e32 v32, v51
	v_fmamk_f32 v33, v33, 0xbfb8aa3b, v49
	v_fmamk_f32 v34, v34, 0xbfb8aa3b, v49
	v_exp_f32_e32 v33, v33
	v_exp_f32_e32 v34, v34
	v_add_f32_e32 v33, 1.0, v33
	v_add_f32_e32 v34, 1.0, v34
	v_rcp_f32_e32 v33, v33
	v_rcp_f32_e32 v34, v34
	v_fmamk_f32 v18, v18, 0xbfb8aa3b, v48
	v_fmamk_f32 v19, v19, 0xbfb8aa3b, v48
	v_exp_f32_e32 v18, v18
	s_waitcnt lgkmcnt(0)
	v_mul_f32_e32 v50, 0x3fb8aa3b, v251
	v_mul_f32_e32 v16, v17, v50
	v_mul_f32_e32 v17, v33, v50
	v_exp_f32_e32 v33, v16
	v_mul_f32_e32 v16, v34, v50
	v_exp_f32_e32 v53, v16
	v_fmamk_f32 v16, v35, 0xbfb8aa3b, v49
	v_exp_f32_e32 v16, v16
	v_exp_f32_e32 v51, v17
	v_add_f32_e32 v16, 1.0, v16
	v_rcp_f32_e32 v16, v16
	v_exp_f32_e32 v19, v19
	v_add_f32_e32 v52, 1.0, v52
	v_add_f32_e32 v18, 1.0, v18
	v_mul_f32_e32 v16, v16, v50
	v_exp_f32_e32 v16, v16
	v_fma_f32 v35, -v53, v53, 1.0
	v_rcp_f32_e32 v17, v52
	v_fma_f32 v34, -v33, v33, 1.0
	v_fma_f32 v52, -v51, v51, 1.0
	v_rcp_f32_e32 v18, v18
	v_sqrt_f32_e32 v35, v35
	v_add_f32_e32 v19, 1.0, v19
	v_fma_f32 v54, -v16, v16, 1.0
	v_sqrt_f32_e32 v34, v34
	v_sqrt_f32_e32 v52, v52
	v_rcp_f32_e32 v19, v19
	v_sqrt_f32_e32 v54, v54
	v_mul_f32_e32 v35, v18, v35
	v_fmamk_f32 v18, v36, 0xbfb8aa3b, v49
	v_mul_f32_e32 v32, v32, v34
	v_mul_f32_e32 v34, v17, v52
	v_mul_f32_e32 v17, v19, v54
	v_fmamk_f32 v19, v20, 0xbfb8aa3b, v48
	v_exp_f32_e32 v18, v18
	v_exp_f32_e32 v19, v19
	v_mul_f32_e32 v3, v3, v17
	v_add_f32_e32 v17, 1.0, v18
	v_rcp_f32_e32 v17, v17
	v_add_f32_e32 v18, 1.0, v19
	v_fmamk_f32 v19, v37, 0xbfb8aa3b, v49
	v_exp_f32_e32 v19, v19
	v_mul_f32_e32 v17, v17, v50
	v_exp_f32_e32 v36, v17
	v_add_f32_e32 v17, 1.0, v19
	v_rcp_f32_e32 v17, v17
	v_fmamk_f32 v19, v21, 0xbfb8aa3b, v48
	v_exp_f32_e32 v19, v19
	v_mul_f32_e32 v17, v17, v50
	v_exp_f32_e32 v37, v17
	v_fmamk_f32 v17, v38, 0xbfb8aa3b, v49
	v_exp_f32_e32 v17, v17
	v_fmamk_f32 v23, v23, 0xbfb8aa3b, v48
	v_add_f32_e32 v19, 1.0, v19
	v_fma_f32 v21, -v37, v37, 1.0
	v_add_f32_e32 v17, 1.0, v17
	v_rcp_f32_e32 v17, v17
	v_fma_f32 v20, -v36, v36, 1.0
	v_rcp_f32_e32 v19, v19
	v_mul_f32_e32 v17, v17, v50
	v_exp_f32_e32 v38, v17
	v_fmamk_f32 v17, v39, 0xbfb8aa3b, v49
	v_exp_f32_e32 v17, v17
	v_sqrt_f32_e32 v21, v21
	v_exp_f32_e32 v23, v23
	v_rcp_f32_e32 v18, v18
	v_add_f32_e32 v17, 1.0, v17
	v_rcp_f32_e32 v17, v17
	v_sqrt_f32_e32 v20, v20
	v_add_f32_e32 v23, 1.0, v23
	v_mul_f32_e32 v55, v19, v21
	v_mul_f32_e32 v17, v17, v50
	v_exp_f32_e32 v17, v17
	v_fmamk_f32 v19, v40, 0xbfb8aa3b, v49
	v_rcp_f32_e32 v23, v23
	v_mul_f32_e32 v54, v18, v20
	v_fma_f32 v52, -v17, v17, 1.0
	v_sqrt_f32_e32 v52, v52
	v_fmamk_f32 v20, v24, 0xbfb8aa3b, v48
	v_fmamk_f32 v22, v22, 0xbfb8aa3b, v48
	v_exp_f32_e32 v19, v19
	v_exp_f32_e32 v20, v20
	v_exp_f32_e32 v22, v22
	v_mul_f32_e32 v18, v23, v52
	v_mul_f32_e32 v7, v7, v18
	v_add_f32_e32 v18, 1.0, v19
	v_rcp_f32_e32 v18, v18
	v_add_f32_e32 v19, 1.0, v20
	v_fmamk_f32 v20, v41, 0xbfb8aa3b, v49
	v_add_f32_e32 v22, 1.0, v22
	v_fma_f32 v39, -v38, v38, 1.0
	v_rcp_f32_e32 v22, v22
	v_sqrt_f32_e32 v39, v39
	v_exp_f32_e32 v20, v20
	v_mul_f32_e32 v18, v18, v50
	v_mul_f32_e32 v21, v22, v39
	v_exp_f32_e32 v39, v18
	v_add_f32_e32 v18, 1.0, v20
	v_rcp_f32_e32 v18, v18
	v_fmamk_f32 v20, v25, 0xbfb8aa3b, v48
	v_exp_f32_e32 v20, v20
	v_mul_f32_e32 v18, v18, v50
	v_exp_f32_e32 v40, v18
	v_fmamk_f32 v18, v42, 0xbfb8aa3b, v49
	v_exp_f32_e32 v18, v18
	v_fmamk_f32 v24, v26, 0xbfb8aa3b, v48
	v_fmamk_f32 v26, v27, 0xbfb8aa3b, v48
	v_add_f32_e32 v20, 1.0, v20
	v_add_f32_e32 v18, 1.0, v18
	v_rcp_f32_e32 v18, v18
	v_fma_f32 v23, -v40, v40, 1.0
	v_fma_f32 v22, -v39, v39, 1.0
	v_mul_f32_e32 v18, v18, v50
	v_exp_f32_e32 v41, v18
	v_fmamk_f32 v18, v43, 0xbfb8aa3b, v49
	v_exp_f32_e32 v18, v18
	v_rcp_f32_e32 v20, v20
	v_sqrt_f32_e32 v23, v23
	v_exp_f32_e32 v26, v26
	v_add_f32_e32 v18, 1.0, v18
	v_rcp_f32_e32 v18, v18
	v_rcp_f32_e32 v19, v19
	v_sqrt_f32_e32 v22, v22
	v_add_f32_e32 v26, 1.0, v26
	v_mul_f32_e32 v18, v18, v50
	v_exp_f32_e32 v18, v18
	v_mul_f32_e32 v43, v20, v23
	v_fmamk_f32 v20, v44, 0xbfb8aa3b, v49
	v_rcp_f32_e32 v26, v26
	v_fma_f32 v27, -v18, v18, 1.0
	v_sqrt_f32_e32 v27, v27
	v_mul_f32_e32 v42, v19, v22
	v_fmamk_f32 v22, v28, 0xbfb8aa3b, v48
	v_exp_f32_e32 v20, v20
	v_exp_f32_e32 v22, v22
	v_mul_f32_e32 v19, v26, v27
	v_mul_f32_e32 v11, v11, v19
	v_add_f32_e32 v19, 1.0, v20
	v_rcp_f32_e32 v19, v19
	v_add_f32_e32 v20, 1.0, v22
	v_fmamk_f32 v22, v45, 0xbfb8aa3b, v49
	v_exp_f32_e32 v22, v22
	v_mul_f32_e32 v19, v19, v50
	v_exp_f32_e32 v44, v19
	v_add_f32_e32 v19, 1.0, v22
	v_rcp_f32_e32 v19, v19
	v_exp_f32_e32 v24, v24
	v_fmamk_f32 v22, v29, 0xbfb8aa3b, v48
	v_mul_f32_e32 v19, v19, v50
	v_exp_f32_e32 v45, v19
	v_fmamk_f32 v19, v46, 0xbfb8aa3b, v49
	v_exp_f32_e32 v19, v19
	v_add_f32_e32 v24, 1.0, v24
	v_fma_f32 v25, -v41, v41, 1.0
	v_add_f32_e32 v19, 1.0, v19
	v_rcp_f32_e32 v19, v19
	v_exp_f32_e32 v22, v22
	v_rcp_f32_e32 v24, v24
	v_sqrt_f32_e32 v25, v25
	v_mul_f32_e32 v19, v19, v50
	v_exp_f32_e32 v46, v19
	v_fmamk_f32 v19, v47, 0xbfb8aa3b, v49
	v_add_f32_e32 v22, 1.0, v22
	v_exp_f32_e32 v19, v19
	v_mul_f32_e32 v52, v24, v25
	v_rcp_f32_e32 v24, v22
	v_fma_f32 v22, -v45, v45, 1.0
	v_sqrt_f32_e32 v25, v22
	v_fmamk_f32 v22, v30, 0xbfb8aa3b, v48
	v_exp_f32_e32 v22, v22
	v_add_f32_e32 v19, 1.0, v19
	v_rcp_f32_e32 v19, v19
	v_fma_f32 v27, -v46, v46, 1.0
	v_add_f32_e32 v22, 1.0, v22
	v_rcp_f32_e32 v26, v22
	v_fmamk_f32 v22, v31, 0xbfb8aa3b, v48
	v_mul_f32_e32 v19, v19, v50
	v_exp_f32_e32 v28, v22
	v_exp_f32_e32 v22, v19
	v_sqrt_f32_e32 v19, v27
	v_fma_f32 v23, -v44, v44, 1.0
	v_add_f32_e32 v27, 1.0, v28
	v_fma_f32 v28, -v22, v22, 1.0
	v_rcp_f32_e32 v27, v27
	v_sqrt_f32_e32 v28, v28
	v_rcp_f32_e32 v20, v20
	v_sqrt_f32_e32 v23, v23
	v_mul_f32_e32 v49, v26, v19
	v_mul_f32_e32 v19, v27, v28
	v_fmac_f32_e32 v7, 0, v17
	v_mul_f32_e32 v15, v15, v19
	v_mul_f32_e32 v19, v38, v7
	v_fmac_f32_e32 v19, v6, v21
	v_fmac_f32_e32 v3, 0, v16
	v_mul_f32_e32 v21, v37, v19
	v_mul_f32_e32 v47, v20, v23
	v_mul_f32_e32 v20, v53, v3
	v_fmac_f32_e32 v21, v5, v55
	v_fmac_f32_e32 v15, 0, v22
	v_mul_f32_e32 v48, v24, v25
	v_fmac_f32_e32 v20, v2, v35
	v_mul_f32_e32 v24, v36, v21
	v_fmac_f32_e32 v11, 0, v18
	v_mul_f32_e32 v2, v46, v15
	v_fmac_f32_e32 v24, v4, v54
	v_mul_f32_e32 v4, v41, v11
	v_fmac_f32_e32 v2, v14, v49
	v_fmac_f32_e32 v4, v10, v52
	v_mul_f32_e32 v5, v45, v2
	v_mul_f32_e32 v23, v51, v20
	v_mul_f32_e32 v6, v40, v4
	v_fmac_f32_e32 v5, v13, v48
	v_fmac_f32_e32 v23, v1, v34
	v_fmac_f32_e32 v6, v9, v43
	v_mul_f32_e32 v14, v22, v46
	v_mul_f32_e32 v9, v44, v5
	v_mul_f32_e32 v25, v33, v23
	v_mul_f32_e32 v13, v45, v14
	v_fmac_f32_e32 v9, v12, v47
	v_fmac_f32_e32 v25, v0, v32
	v_mul_f32_e32 v12, v44, v13
	ds_bpermute_b32 v0, v137, v9
	ds_bpermute_b32 v35, v137, v12
	v_mul_f32_e32 v28, v18, v41
	v_mul_f32_e32 v26, v16, v53
	v_mul_f32_e32 v27, v17, v38
	v_mul_f32_e32 v31, v40, v28
	v_mul_f32_e32 v10, v39, v6
	v_mul_f32_e32 v29, v51, v26
	v_mul_f32_e32 v30, v37, v27
	v_fmac_f32_e32 v10, v8, v42
	v_mul_f32_e32 v34, v39, v31
	v_mul_f32_e32 v32, v33, v29
	v_mul_f32_e32 v33, v36, v30
	s_waitcnt lgkmcnt(1)
	v_cndmask_b32_e64 v36, v0, v9, s[4:5]
	v_cndmask_b32_e64 v37, v9, v0, s[4:5]
	ds_bpermute_b32 v0, v137, v34
	ds_bpermute_b32 v40, v137, v10
	s_waitcnt lgkmcnt(2)
	v_cndmask_b32_e64 v8, v12, v35, s[4:5]
	v_fmac_f32_e32 v37, 0, v8
	ds_bpermute_b32 v8, v137, v33
	v_cndmask_b32_e64 v1, v35, v12, s[4:5]
	v_mul_f32_e32 v38, v12, v35
	v_fmac_f32_e32 v36, v1, v37
	s_waitcnt lgkmcnt(2)
	v_cndmask_b32_e64 v1, v0, v34, s[4:5]
	s_waitcnt lgkmcnt(1)
	v_cndmask_b32_e64 v39, v40, v10, s[4:5]
	v_cndmask_b32_e64 v0, v34, v0, s[4:5]
	v_cndmask_b32_e64 v40, v10, v40, s[4:5]
	ds_bpermute_b32 v44, v137, v24
	v_mul_f32_e32 v41, v38, v0
	v_fmac_f32_e32 v40, v0, v36
	v_mul_f32_e32 v42, v1, v41
	v_fmac_f32_e32 v39, v1, v40
	s_waitcnt lgkmcnt(1)
	v_cndmask_b32_e64 v0, v8, v33, s[4:5]
	v_cndmask_b32_e64 v1, v33, v8, s[4:5]
	ds_bpermute_b32 v8, v137, v32
	ds_bpermute_b32 v47, v137, v25
	s_waitcnt lgkmcnt(2)
	v_cndmask_b32_e64 v43, v44, v24, s[4:5]
	v_cndmask_b32_e64 v44, v24, v44, s[4:5]
	v_mul_f32_e32 v45, v1, v42
	v_fmac_f32_e32 v44, v1, v39
	v_mul_f32_e32 v46, v0, v45
	v_fmac_f32_e32 v43, v0, v44
	s_waitcnt lgkmcnt(1)
	v_cndmask_b32_e64 v0, v32, v8, s[4:5]
	s_waitcnt lgkmcnt(0)
	v_cndmask_b32_e64 v47, v25, v47, s[4:5]
	v_mul_f32_e32 v48, v0, v46
	v_fmac_f32_e32 v47, v0, v43
	s_and_saveexec_b64 s[12:13], s[4:5]
	v_mul_f32_e32 v0, v32, v48
	v_fma_f32 v1, v32, v47, v25
	ds_write_b64 v136, v[0:1] offset:6144
	s_or_b64 exec, exec, s[12:13]
	s_and_b64 vcc, exec, s[8:9]
	s_waitcnt lgkmcnt(0)
	s_barrier
	s_cbranch_vccnz .LBB0_293
	v_add3_u32 v49, v140, v91, s95
	v_mov_b32_e32 v8, 1.0
	v_mov_b32_e32 v1, 0
	s_mov_b32 s8, 7

.LBB0_319:
.LBB0_320:
	s_and_b32 s63, s57, 63
	s_ashr_i32 s62, s89, 6
	s_lshl_b32 s0, s63, 8
	s_lshl_b32 s1, s62, 5
	v_and_b32_e32 v94, 31, v92
	s_add_i32 s8, s1, s0
	v_or_b32_e32 v9, s8, v94
	v_add_u32_e32 v0, -2, v9
	v_cmp_gt_u32_e32 vcc, s80, v0
	v_bfe_u32 v93, v92, 5, 1
	s_lshl_b32 s14, s70, 1
	v_cndmask_b32_e32 v2, v9, v0, vcc
	v_mov_b64_e32 v[0:1], s[52:53]
	v_mad_i64_i32 v[2:3], s[0:1], v2, s81, v[0:1]
	v_lshl_add_u64 v[2:3], v[2:3], 0, s[14:15]
	v_lshlrev_b32_e32 v88, 4, v93
	v_lshl_add_u64 v[4:5], v[2:3], 0, v[88:89]
	v_add_co_u32_e64 v2, s[0:1], s82, v4
	s_waitcnt lgkmcnt(0)
	s_nop 0
	v_addc_co_u32_e64 v3, s[0:1], 0, v5, s[0:1]
	s_barrier
	global_load_dwordx4 v[10:13], v[2:3], off offset:1024
	global_load_dwordx4 v[178:181], v[2:3], off offset:1056
	global_load_dwordx4 v[194:197], v[2:3], off offset:1088
	global_load_dwordx4 v[210:213], v[2:3], off offset:1120
	global_load_dwordx4 v[226:229], v[2:3], off offset:1152
	global_load_dwordx4 v[242:245], v[2:3], off offset:1184
	v_add_u32_e32 v2, -1, v9
	v_cmp_gt_u32_e64 s[0:1], s80, v2
	v_add_u32_e32 v18, 1, v9
	s_cmpk_lt_u32 s8, 0x4000
	v_cndmask_b32_e64 v2, v9, v2, s[0:1]
	v_mad_i64_i32 v[2:3], s[4:5], v2, s81, v[0:1]
	v_lshl_add_u64 v[2:3], v[2:3], 0, s[14:15]
	v_lshl_add_u64 v[2:3], v[2:3], 0, v[88:89]
	v_add_co_u32_e64 v6, s[4:5], s82, v2
	v_lshlrev_b32_e32 v138, 8, v94
	s_nop 0
	v_addc_co_u32_e64 v7, s[4:5], 0, v3, s[4:5]
	global_load_dwordx4 v[14:17], v[6:7], off offset:1024
	global_load_dwordx4 v[182:185], v[6:7], off offset:1056
	global_load_dwordx4 v[198:201], v[6:7], off offset:1088
	global_load_dwordx4 v[214:217], v[6:7], off offset:1120
	global_load_dwordx4 v[230:233], v[6:7], off offset:1152
	global_load_dwordx4 v[246:249], v[6:7], off offset:1184
	v_mad_i64_i32 v[6:7], s[4:5], v9, s81, v[0:1]
	v_cmp_gt_u32_e64 s[4:5], s80, v18
	v_lshl_add_u64 v[6:7], v[6:7], 0, s[14:15]
	v_lshl_add_u64 v[52:53], v[6:7], 0, v[88:89]
	v_cndmask_b32_e64 v9, v9, v18, s[4:5]
	v_mad_i64_i32 v[0:1], s[6:7], v9, s81, v[0:1]
	v_add_co_u32_e64 v6, s[6:7], s82, v52
	v_lshl_add_u64 v[0:1], v[0:1], 0, s[14:15]
	s_nop 0
	v_addc_co_u32_e64 v7, s[6:7], 0, v53, s[6:7]
	global_load_dwordx4 v[18:21], v[6:7], off offset:1024
	global_load_dwordx4 v[186:189], v[6:7], off offset:1056
	global_load_dwordx4 v[202:205], v[6:7], off offset:1088
	global_load_dwordx4 v[218:221], v[6:7], off offset:1120
	global_load_dwordx4 v[234:237], v[6:7], off offset:1152
	global_load_dwordx4 v[252:255], v[6:7], off offset:1184
	v_lshl_add_u64 v[6:7], v[0:1], 0, v[88:89]
	v_add_co_u32_e64 v0, s[6:7], s82, v6
	v_lshl_add_u32 v9, v93, 5, 16
	s_nop 0
	v_addc_co_u32_e64 v1, s[6:7], 0, v7, s[6:7]
	global_load_dwordx4 v[22:25], v[0:1], off offset:1024
	global_load_dwordx4 v[190:193], v[0:1], off offset:1056
	global_load_dwordx4 v[206:209], v[0:1], off offset:1088
	global_load_dwordx4 v[222:225], v[0:1], off offset:1120
	global_load_dwordx4 v[238:241], v[0:1], off offset:1152
	global_load_dwordx4 v[168:171], v[0:1], off offset:1184
	s_waitcnt vmcnt(26)
	s_waitcnt lgkmcnt(4)
	v_lshl_add_u64 v[0:1], v[4:5], 0, s[30:31]
	s_cselect_b64 s[6:7], -1, 0
	v_lshl_add_u64 v[6:7], v[6:7], 0, s[30:31]
	v_and_b32_e32 v8, 0x70, v8
	v_add_u32_e32 v95, 16, v138
	v_or_b32_e32 v91, s70, v94
	s_waitcnt vmcnt(23)
	s_waitcnt vmcnt(17)
	s_waitcnt lgkmcnt(3)
	s_waitcnt lgkmcnt(1)
	s_waitcnt lgkmcnt(0)
	s_waitcnt vmcnt(11)
	s_waitcnt vmcnt(5)
	ds_read_b128 v[26:29], v9 offset:10240
	ds_read_b128 v[30:33], v9 offset:10256
	ds_read_b128 v[34:37], v9 offset:8192
	ds_read_b128 v[38:41], v9 offset:8208
	ds_read_b128 v[42:45], v9 offset:8704
	ds_read_b128 v[80:83], v9 offset:8720
	s_mov_b64 exec, vcc
	v_lshlrev_b32_e32 v4, 16, v10
	v_and_b32_e32 v5, 0xffff0000, v10
	v_lshlrev_b32_e32 v46, 16, v11
	v_and_b32_e32 v47, 0xffff0000, v11
	s_waitcnt lgkmcnt(2)
	v_pk_fma_f32 v[26:27], v[34:35], v[4:5], v[26:27]
	v_pk_fma_f32 v[28:29], v[36:37], v[46:47], v[28:29]
	v_lshlrev_b32_e32 v84, 16, v12
	v_and_b32_e32 v85, 0xffff0000, v12
	v_lshlrev_b32_e32 v86, 16, v13
	v_and_b32_e32 v87, 0xffff0000, v13
	v_pk_fma_f32 v[30:31], v[38:39], v[84:85], v[30:31]
	v_pk_fma_f32 v[32:33], v[40:41], v[86:87], v[32:33]
	s_mov_b64 exec, -1
	ds_read_b128 v[34:37], v9 offset:9216
	ds_read_b128 v[38:41], v9 offset:9232
	s_mov_b64 exec, s[0:1]
	v_lshlrev_b32_e32 v4, 16, v14
	v_and_b32_e32 v5, 0xffff0000, v14
	v_lshlrev_b32_e32 v46, 16, v15
	v_and_b32_e32 v47, 0xffff0000, v15
	s_waitcnt lgkmcnt(2)
	v_pk_fma_f32 v[26:27], v[42:43], v[4:5], v[26:27]
	v_pk_fma_f32 v[28:29], v[44:45], v[46:47], v[28:29]
	v_lshlrev_b32_e32 v84, 16, v16
	v_and_b32_e32 v85, 0xffff0000, v16
	v_lshlrev_b32_e32 v86, 16, v17
	v_and_b32_e32 v87, 0xffff0000, v17
	v_pk_fma_f32 v[30:31], v[80:81], v[84:85], v[30:31]
	v_pk_fma_f32 v[32:33], v[82:83], v[86:87], v[32:33]
	s_mov_b64 exec, -1
	ds_read_b128 v[42:45], v9 offset:9728
	ds_read_b128 v[80:83], v9 offset:9744
	v_lshlrev_b32_e32 v4, 16, v18
	v_and_b32_e32 v5, 0xffff0000, v18
	v_lshlrev_b32_e32 v46, 16, v19
	v_and_b32_e32 v47, 0xffff0000, v19
	s_waitcnt lgkmcnt(2)
	v_pk_fma_f32 v[26:27], v[34:35], v[4:5], v[26:27]
	v_pk_fma_f32 v[28:29], v[36:37], v[46:47], v[28:29]
	v_lshlrev_b32_e32 v84, 16, v20
	v_and_b32_e32 v85, 0xffff0000, v20
	v_lshlrev_b32_e32 v86, 16, v21
	v_and_b32_e32 v87, 0xffff0000, v21
	v_pk_fma_f32 v[30:31], v[38:39], v[84:85], v[30:31]
	v_pk_fma_f32 v[32:33], v[40:41], v[86:87], v[32:33]
	s_mov_b64 exec, s[4:5]
	v_lshlrev_b32_e32 v4, 16, v22
	v_and_b32_e32 v5, 0xffff0000, v22
	v_lshlrev_b32_e32 v46, 16, v23
	v_and_b32_e32 v47, 0xffff0000, v23
	s_waitcnt lgkmcnt(0)
	v_pk_fma_f32 v[26:27], v[42:43], v[4:5], v[26:27]
	v_pk_fma_f32 v[28:29], v[44:45], v[46:47], v[28:29]
	v_lshlrev_b32_e32 v84, 16, v24
	v_and_b32_e32 v85, 0xffff0000, v24
	v_lshlrev_b32_e32 v86, 16, v25
	v_and_b32_e32 v87, 0xffff0000, v25
	v_pk_fma_f32 v[30:31], v[80:81], v[84:85], v[30:31]
	v_pk_fma_f32 v[32:33], v[82:83], v[86:87], v[32:33]
	s_mov_b64 exec, -1
	v_cvt_pk_bf16_f32 v48, v26, v27
	v_cvt_pk_bf16_f32 v49, v28, v29
	v_cvt_pk_bf16_f32 v50, v30, v31
	v_cvt_pk_bf16_f32 v51, v32, v33
	s_waitcnt lgkmcnt(3)
	s_waitcnt lgkmcnt(1)
	s_waitcnt lgkmcnt(0)
	s_nop 0
	v_lshl_add_u64 v[4:5], v[2:3], 0, s[30:31]
	v_lshl_add_u64 v[2:3], v[52:53], 0, s[30:31]
	s_waitcnt vmcnt(4)
	s_waitcnt vmcnt(4)
	s_waitcnt lgkmcnt(3)
	s_waitcnt lgkmcnt(1)
	s_waitcnt lgkmcnt(0)
	s_waitcnt vmcnt(4)
	ds_read_b128 v[26:29], v9 offset:10304
	ds_read_b128 v[30:33], v9 offset:10320
	ds_read_b128 v[34:37], v9 offset:8256
	ds_read_b128 v[38:41], v9 offset:8272
	ds_read_b128 v[42:45], v9 offset:8768
	ds_read_b128 v[80:83], v9 offset:8784
	s_mov_b64 exec, vcc
	v_lshlrev_b32_e32 v46, 16, v178
	v_and_b32_e32 v47, 0xffff0000, v178
	v_lshlrev_b32_e32 v84, 16, v179
	v_and_b32_e32 v85, 0xffff0000, v179
	s_waitcnt lgkmcnt(2)
	v_pk_fma_f32 v[26:27], v[34:35], v[46:47], v[26:27]
	v_pk_fma_f32 v[28:29], v[36:37], v[84:85], v[28:29]
	v_lshlrev_b32_e32 v86, 16, v180
	v_and_b32_e32 v87, 0xffff0000, v180
	v_lshlrev_b32_e32 v96, 16, v181
	v_and_b32_e32 v97, 0xffff0000, v181
	v_pk_fma_f32 v[30:31], v[38:39], v[86:87], v[30:31]
	v_pk_fma_f32 v[32:33], v[40:41], v[96:97], v[32:33]
	s_mov_b64 exec, -1
	ds_read_b128 v[34:37], v9 offset:9280
	ds_read_b128 v[38:41], v9 offset:9296
	s_mov_b64 exec, s[0:1]
	v_lshlrev_b32_e32 v46, 16, v182
	v_and_b32_e32 v47, 0xffff0000, v182
	v_lshlrev_b32_e32 v84, 16, v183
	v_and_b32_e32 v85, 0xffff0000, v183
	s_waitcnt lgkmcnt(2)
	v_pk_fma_f32 v[26:27], v[42:43], v[46:47], v[26:27]
	v_pk_fma_f32 v[28:29], v[44:45], v[84:85], v[28:29]
	v_lshlrev_b32_e32 v86, 16, v184
	v_and_b32_e32 v87, 0xffff0000, v184
	v_lshlrev_b32_e32 v96, 16, v185
	v_and_b32_e32 v97, 0xffff0000, v185
	v_pk_fma_f32 v[30:31], v[80:81], v[86:87], v[30:31]
	v_pk_fma_f32 v[32:33], v[82:83], v[96:97], v[32:33]
	s_mov_b64 exec, -1
	ds_read_b128 v[42:45], v9 offset:9792
	ds_read_b128 v[80:83], v9 offset:9808
	v_lshlrev_b32_e32 v46, 16, v186
	v_and_b32_e32 v47, 0xffff0000, v186
	v_lshlrev_b32_e32 v84, 16, v187
	v_and_b32_e32 v85, 0xffff0000, v187
	s_waitcnt lgkmcnt(2)
	v_pk_fma_f32 v[26:27], v[34:35], v[46:47], v[26:27]
	v_pk_fma_f32 v[28:29], v[36:37], v[84:85], v[28:29]
	v_lshlrev_b32_e32 v86, 16, v188
	v_and_b32_e32 v87, 0xffff0000, v188
	v_lshlrev_b32_e32 v96, 16, v189
	v_and_b32_e32 v97, 0xffff0000, v189
	v_pk_fma_f32 v[30:31], v[38:39], v[86:87], v[30:31]
	v_pk_fma_f32 v[32:33], v[40:41], v[96:97], v[32:33]
	s_mov_b64 exec, s[4:5]
	v_lshlrev_b32_e32 v46, 16, v190
	v_and_b32_e32 v47, 0xffff0000, v190
	v_lshlrev_b32_e32 v84, 16, v191
	v_and_b32_e32 v85, 0xffff0000, v191
	s_waitcnt lgkmcnt(0)
	v_pk_fma_f32 v[26:27], v[42:43], v[46:47], v[26:27]
	v_pk_fma_f32 v[28:29], v[44:45], v[84:85], v[28:29]
	v_lshlrev_b32_e32 v86, 16, v192
	v_and_b32_e32 v87, 0xffff0000, v192
	v_lshlrev_b32_e32 v96, 16, v193
	v_and_b32_e32 v97, 0xffff0000, v193
	v_pk_fma_f32 v[30:31], v[80:81], v[86:87], v[30:31]
	v_pk_fma_f32 v[32:33], v[82:83], v[96:97], v[32:33]
	s_mov_b64 exec, -1
	v_cvt_pk_bf16_f32 v52, v26, v27
	v_cvt_pk_bf16_f32 v53, v28, v29
	v_cvt_pk_bf16_f32 v54, v30, v31
	v_cvt_pk_bf16_f32 v55, v32, v33
	s_waitcnt lgkmcnt(3)
	s_waitcnt lgkmcnt(1)
	s_waitcnt lgkmcnt(0)
	s_nop 0
	global_load_dwordx4 v[178:181], v[0:1], off offset:192
	global_load_dwordx4 v[182:185], v[4:5], off offset:192
	global_load_dwordx4 v[186:189], v[2:3], off offset:192
	global_load_dwordx4 v[190:193], v[6:7], off offset:192
	s_waitcnt vmcnt(7)
	s_waitcnt vmcnt(7)
	s_waitcnt lgkmcnt(3)
	s_waitcnt lgkmcnt(1)
	s_waitcnt lgkmcnt(0)
	s_waitcnt vmcnt(7)
	s_waitcnt vmcnt(7)
	ds_read_b128 v[26:29], v9 offset:10368
	ds_read_b128 v[30:33], v9 offset:10384
	ds_read_b128 v[34:37], v9 offset:8320
	ds_read_b128 v[38:41], v9 offset:8336
	ds_read_b128 v[42:45], v9 offset:8832
	ds_read_b128 v[80:83], v9 offset:8848
	s_mov_b64 exec, vcc
	v_lshlrev_b32_e32 v46, 16, v194
	v_and_b32_e32 v47, 0xffff0000, v194
	v_lshlrev_b32_e32 v84, 16, v195
	v_and_b32_e32 v85, 0xffff0000, v195
	s_waitcnt lgkmcnt(2)
	v_pk_fma_f32 v[26:27], v[34:35], v[46:47], v[26:27]
	v_pk_fma_f32 v[28:29], v[36:37], v[84:85], v[28:29]
	v_lshlrev_b32_e32 v86, 16, v196
	v_and_b32_e32 v87, 0xffff0000, v196
	v_lshlrev_b32_e32 v96, 16, v197
	v_and_b32_e32 v97, 0xffff0000, v197
	v_pk_fma_f32 v[30:31], v[38:39], v[86:87], v[30:31]
	v_pk_fma_f32 v[32:33], v[40:41], v[96:97], v[32:33]
	s_mov_b64 exec, -1
	ds_read_b128 v[34:37], v9 offset:9344
	ds_read_b128 v[38:41], v9 offset:9360
	s_mov_b64 exec, s[0:1]
	v_lshlrev_b32_e32 v46, 16, v198
	v_and_b32_e32 v47, 0xffff0000, v198
	v_lshlrev_b32_e32 v84, 16, v199
	v_and_b32_e32 v85, 0xffff0000, v199
	s_waitcnt lgkmcnt(2)
	v_pk_fma_f32 v[26:27], v[42:43], v[46:47], v[26:27]
	v_pk_fma_f32 v[28:29], v[44:45], v[84:85], v[28:29]
	v_lshlrev_b32_e32 v86, 16, v200
	v_and_b32_e32 v87, 0xffff0000, v200
	v_lshlrev_b32_e32 v96, 16, v201
	v_and_b32_e32 v97, 0xffff0000, v201
	v_pk_fma_f32 v[30:31], v[80:81], v[86:87], v[30:31]
	v_pk_fma_f32 v[32:33], v[82:83], v[96:97], v[32:33]
	s_mov_b64 exec, -1
	ds_read_b128 v[42:45], v9 offset:9856
	ds_read_b128 v[80:83], v9 offset:9872
	v_lshlrev_b32_e32 v46, 16, v202
	v_and_b32_e32 v47, 0xffff0000, v202
	v_lshlrev_b32_e32 v84, 16, v203
	v_and_b32_e32 v85, 0xffff0000, v203
	s_waitcnt lgkmcnt(2)
	v_pk_fma_f32 v[26:27], v[34:35], v[46:47], v[26:27]
	v_pk_fma_f32 v[28:29], v[36:37], v[84:85], v[28:29]
	v_lshlrev_b32_e32 v86, 16, v204
	v_and_b32_e32 v87, 0xffff0000, v204
	v_lshlrev_b32_e32 v96, 16, v205
	v_and_b32_e32 v97, 0xffff0000, v205
	v_pk_fma_f32 v[30:31], v[38:39], v[86:87], v[30:31]
	v_pk_fma_f32 v[32:33], v[40:41], v[96:97], v[32:33]
	s_mov_b64 exec, s[4:5]
	v_lshlrev_b32_e32 v46, 16, v206
	v_and_b32_e32 v47, 0xffff0000, v206
	v_lshlrev_b32_e32 v84, 16, v207
	v_and_b32_e32 v85, 0xffff0000, v207
	s_waitcnt lgkmcnt(0)
	v_pk_fma_f32 v[26:27], v[42:43], v[46:47], v[26:27]
	v_pk_fma_f32 v[28:29], v[44:45], v[84:85], v[28:29]
	v_lshlrev_b32_e32 v86, 16, v208
	v_and_b32_e32 v87, 0xffff0000, v208
	v_lshlrev_b32_e32 v96, 16, v209
	v_and_b32_e32 v97, 0xffff0000, v209
	v_pk_fma_f32 v[30:31], v[80:81], v[86:87], v[30:31]
	v_pk_fma_f32 v[32:33], v[82:83], v[96:97], v[32:33]
	s_mov_b64 exec, -1
	v_cvt_pk_bf16_f32 v56, v26, v27
	v_cvt_pk_bf16_f32 v57, v28, v29
	v_cvt_pk_bf16_f32 v58, v30, v31
	v_cvt_pk_bf16_f32 v59, v32, v33
	s_waitcnt lgkmcnt(3)
	s_waitcnt lgkmcnt(1)
	s_waitcnt lgkmcnt(0)
	s_nop 0
	global_load_dwordx4 v[194:197], v[0:1], off offset:224
	global_load_dwordx4 v[198:201], v[4:5], off offset:224
	global_load_dwordx4 v[202:205], v[2:3], off offset:224
	global_load_dwordx4 v[206:209], v[6:7], off offset:224
	s_waitcnt vmcnt(10)
	s_waitcnt vmcnt(10)
	s_waitcnt lgkmcnt(3)
	s_waitcnt lgkmcnt(1)
	s_waitcnt lgkmcnt(0)
	s_waitcnt vmcnt(10)
	s_waitcnt vmcnt(10)
	ds_read_b128 v[0:3], v9 offset:10432
	ds_read_b128 v[4:7], v9 offset:10448
	ds_read_b128 v[26:29], v9 offset:8384
	ds_read_b128 v[30:33], v9 offset:8400
	ds_read_b128 v[34:37], v9 offset:8896
	ds_read_b128 v[38:41], v9 offset:8912
	s_mov_b64 exec, vcc
	v_lshlrev_b32_e32 v42, 16, v210
	v_and_b32_e32 v43, 0xffff0000, v210
	v_lshlrev_b32_e32 v44, 16, v211
	v_and_b32_e32 v45, 0xffff0000, v211
	s_waitcnt lgkmcnt(2)
	v_pk_fma_f32 v[0:1], v[26:27], v[42:43], v[0:1]
	v_pk_fma_f32 v[2:3], v[28:29], v[44:45], v[2:3]
	v_lshlrev_b32_e32 v46, 16, v212
	v_and_b32_e32 v47, 0xffff0000, v212
	v_lshlrev_b32_e32 v80, 16, v213
	v_and_b32_e32 v81, 0xffff0000, v213
	v_pk_fma_f32 v[4:5], v[30:31], v[46:47], v[4:5]
	v_pk_fma_f32 v[6:7], v[32:33], v[80:81], v[6:7]
	s_mov_b64 exec, -1
	ds_read_b128 v[26:29], v9 offset:9408
	ds_read_b128 v[30:33], v9 offset:9424
	s_mov_b64 exec, s[0:1]
	v_lshlrev_b32_e32 v42, 16, v214
	v_and_b32_e32 v43, 0xffff0000, v214
	v_lshlrev_b32_e32 v44, 16, v215
	v_and_b32_e32 v45, 0xffff0000, v215
	s_waitcnt lgkmcnt(2)
	v_pk_fma_f32 v[0:1], v[34:35], v[42:43], v[0:1]
	v_pk_fma_f32 v[2:3], v[36:37], v[44:45], v[2:3]
	v_lshlrev_b32_e32 v46, 16, v216
	v_and_b32_e32 v47, 0xffff0000, v216
	v_lshlrev_b32_e32 v80, 16, v217
	v_and_b32_e32 v81, 0xffff0000, v217
	v_pk_fma_f32 v[4:5], v[38:39], v[46:47], v[4:5]
	v_pk_fma_f32 v[6:7], v[40:41], v[80:81], v[6:7]
	s_mov_b64 exec, -1
	ds_read_b128 v[34:37], v9 offset:9920
	ds_read_b128 v[38:41], v9 offset:9936
	v_lshlrev_b32_e32 v42, 16, v218
	v_and_b32_e32 v43, 0xffff0000, v218
	v_lshlrev_b32_e32 v44, 16, v219
	v_and_b32_e32 v45, 0xffff0000, v219
	s_waitcnt lgkmcnt(2)
	v_pk_fma_f32 v[0:1], v[26:27], v[42:43], v[0:1]
	v_pk_fma_f32 v[2:3], v[28:29], v[44:45], v[2:3]
	v_lshlrev_b32_e32 v46, 16, v220
	v_and_b32_e32 v47, 0xffff0000, v220
	v_lshlrev_b32_e32 v80, 16, v221
	v_and_b32_e32 v81, 0xffff0000, v221
	v_pk_fma_f32 v[4:5], v[30:31], v[46:47], v[4:5]
	v_pk_fma_f32 v[6:7], v[32:33], v[80:81], v[6:7]
	s_mov_b64 exec, s[4:5]
	v_lshlrev_b32_e32 v42, 16, v222
	v_and_b32_e32 v43, 0xffff0000, v222
	v_lshlrev_b32_e32 v44, 16, v223
	v_and_b32_e32 v45, 0xffff0000, v223
	s_waitcnt lgkmcnt(0)
	v_pk_fma_f32 v[0:1], v[34:35], v[42:43], v[0:1]
	v_pk_fma_f32 v[2:3], v[36:37], v[44:45], v[2:3]
	v_lshlrev_b32_e32 v46, 16, v224
	v_and_b32_e32 v47, 0xffff0000, v224
	v_lshlrev_b32_e32 v80, 16, v225
	v_and_b32_e32 v81, 0xffff0000, v225
	v_pk_fma_f32 v[4:5], v[38:39], v[46:47], v[4:5]
	v_pk_fma_f32 v[6:7], v[40:41], v[80:81], v[6:7]
	s_mov_b64 exec, -1
	v_cvt_pk_bf16_f32 v60, v0, v1
	v_cvt_pk_bf16_f32 v61, v2, v3
	v_cvt_pk_bf16_f32 v62, v4, v5
	v_cvt_pk_bf16_f32 v63, v6, v7
	s_waitcnt lgkmcnt(3)
	s_waitcnt lgkmcnt(1)
	s_waitcnt lgkmcnt(0)
	s_nop 0
	s_waitcnt vmcnt(9)
	s_waitcnt vmcnt(9)
	s_waitcnt lgkmcnt(3)
	s_waitcnt lgkmcnt(1)
	s_waitcnt lgkmcnt(0)
	s_waitcnt vmcnt(9)
	s_waitcnt vmcnt(9)
	ds_read_b128 v[0:3], v9 offset:10496
	ds_read_b128 v[4:7], v9 offset:10512
	ds_read_b128 v[26:29], v9 offset:8448
	ds_read_b128 v[30:33], v9 offset:8464
	ds_read_b128 v[34:37], v9 offset:8960
	ds_read_b128 v[38:41], v9 offset:8976
	s_mov_b64 exec, vcc
	v_lshlrev_b32_e32 v42, 16, v226
	v_and_b32_e32 v43, 0xffff0000, v226
	v_lshlrev_b32_e32 v44, 16, v227
	v_and_b32_e32 v45, 0xffff0000, v227
	s_waitcnt lgkmcnt(2)
	v_pk_fma_f32 v[0:1], v[26:27], v[42:43], v[0:1]
	v_pk_fma_f32 v[2:3], v[28:29], v[44:45], v[2:3]
	v_lshlrev_b32_e32 v46, 16, v228
	v_and_b32_e32 v47, 0xffff0000, v228
	v_lshlrev_b32_e32 v80, 16, v229
	v_and_b32_e32 v81, 0xffff0000, v229
	v_pk_fma_f32 v[4:5], v[30:31], v[46:47], v[4:5]
	v_pk_fma_f32 v[6:7], v[32:33], v[80:81], v[6:7]
	s_mov_b64 exec, -1
	ds_read_b128 v[26:29], v9 offset:9472
	ds_read_b128 v[30:33], v9 offset:9488
	s_mov_b64 exec, s[0:1]
	v_lshlrev_b32_e32 v42, 16, v230
	v_and_b32_e32 v43, 0xffff0000, v230
	v_lshlrev_b32_e32 v44, 16, v231
	v_and_b32_e32 v45, 0xffff0000, v231
	s_waitcnt lgkmcnt(2)
	v_pk_fma_f32 v[0:1], v[34:35], v[42:43], v[0:1]
	v_pk_fma_f32 v[2:3], v[36:37], v[44:45], v[2:3]
	v_lshlrev_b32_e32 v46, 16, v232
	v_and_b32_e32 v47, 0xffff0000, v232
	v_lshlrev_b32_e32 v80, 16, v233
	v_and_b32_e32 v81, 0xffff0000, v233
	v_pk_fma_f32 v[4:5], v[38:39], v[46:47], v[4:5]
	v_pk_fma_f32 v[6:7], v[40:41], v[80:81], v[6:7]
	s_mov_b64 exec, -1
	ds_read_b128 v[34:37], v9 offset:9984
	ds_read_b128 v[38:41], v9 offset:10000
	v_lshlrev_b32_e32 v42, 16, v234
	v_and_b32_e32 v43, 0xffff0000, v234
	v_lshlrev_b32_e32 v44, 16, v235
	v_and_b32_e32 v45, 0xffff0000, v235
	s_waitcnt lgkmcnt(2)
	v_pk_fma_f32 v[0:1], v[26:27], v[42:43], v[0:1]
	v_pk_fma_f32 v[2:3], v[28:29], v[44:45], v[2:3]
	v_lshlrev_b32_e32 v46, 16, v236
	v_and_b32_e32 v47, 0xffff0000, v236
	v_lshlrev_b32_e32 v80, 16, v237
	v_and_b32_e32 v81, 0xffff0000, v237
	v_pk_fma_f32 v[4:5], v[30:31], v[46:47], v[4:5]
	v_pk_fma_f32 v[6:7], v[32:33], v[80:81], v[6:7]
	s_mov_b64 exec, s[4:5]
	v_lshlrev_b32_e32 v42, 16, v238
	v_and_b32_e32 v43, 0xffff0000, v238
	v_lshlrev_b32_e32 v44, 16, v239
	v_and_b32_e32 v45, 0xffff0000, v239
	s_waitcnt lgkmcnt(0)
	v_pk_fma_f32 v[0:1], v[34:35], v[42:43], v[0:1]
	v_pk_fma_f32 v[2:3], v[36:37], v[44:45], v[2:3]
	v_lshlrev_b32_e32 v46, 16, v240
	v_and_b32_e32 v47, 0xffff0000, v240
	v_lshlrev_b32_e32 v80, 16, v241
	v_and_b32_e32 v81, 0xffff0000, v241
	v_pk_fma_f32 v[4:5], v[38:39], v[46:47], v[4:5]
	v_pk_fma_f32 v[6:7], v[40:41], v[80:81], v[6:7]
	s_mov_b64 exec, -1
	v_cvt_pk_bf16_f32 v64, v0, v1
	v_cvt_pk_bf16_f32 v65, v2, v3
	v_cvt_pk_bf16_f32 v66, v4, v5
	v_cvt_pk_bf16_f32 v67, v6, v7
	s_waitcnt lgkmcnt(3)
	s_waitcnt lgkmcnt(1)
	s_waitcnt lgkmcnt(0)
	s_nop 0
	s_waitcnt vmcnt(8)
	s_waitcnt vmcnt(8)
	s_waitcnt lgkmcnt(3)
	s_waitcnt lgkmcnt(1)
	s_waitcnt lgkmcnt(0)
	s_waitcnt vmcnt(8)
	s_waitcnt vmcnt(8)
	ds_read_b128 v[0:3], v9 offset:10560
	ds_read_b128 v[4:7], v9 offset:10576
	ds_read_b128 v[26:29], v9 offset:8512
	ds_read_b128 v[30:33], v9 offset:8528
	ds_read_b128 v[34:37], v9 offset:9024
	ds_read_b128 v[38:41], v9 offset:9040
	s_mov_b64 exec, vcc
	v_lshlrev_b32_e32 v42, 16, v242
	v_and_b32_e32 v43, 0xffff0000, v242
	v_lshlrev_b32_e32 v44, 16, v243
	v_and_b32_e32 v45, 0xffff0000, v243
	s_waitcnt lgkmcnt(2)
	v_pk_fma_f32 v[0:1], v[26:27], v[42:43], v[0:1]
	v_pk_fma_f32 v[2:3], v[28:29], v[44:45], v[2:3]
	v_lshlrev_b32_e32 v46, 16, v244
	v_and_b32_e32 v47, 0xffff0000, v244
	v_lshlrev_b32_e32 v80, 16, v245
	v_and_b32_e32 v81, 0xffff0000, v245
	v_pk_fma_f32 v[4:5], v[30:31], v[46:47], v[4:5]
	v_pk_fma_f32 v[6:7], v[32:33], v[80:81], v[6:7]
	s_mov_b64 exec, -1
	ds_read_b128 v[26:29], v9 offset:9536
	ds_read_b128 v[30:33], v9 offset:9552
	s_mov_b64 exec, s[0:1]
	v_lshlrev_b32_e32 v42, 16, v246
	v_and_b32_e32 v43, 0xffff0000, v246
	v_lshlrev_b32_e32 v44, 16, v247
	v_and_b32_e32 v45, 0xffff0000, v247
	s_waitcnt lgkmcnt(2)
	v_pk_fma_f32 v[0:1], v[34:35], v[42:43], v[0:1]
	v_pk_fma_f32 v[2:3], v[36:37], v[44:45], v[2:3]
	v_lshlrev_b32_e32 v46, 16, v248
	v_and_b32_e32 v47, 0xffff0000, v248
	v_lshlrev_b32_e32 v80, 16, v249
	v_and_b32_e32 v81, 0xffff0000, v249
	v_pk_fma_f32 v[4:5], v[38:39], v[46:47], v[4:5]
	v_pk_fma_f32 v[6:7], v[40:41], v[80:81], v[6:7]
	s_mov_b64 exec, -1
	ds_read_b128 v[34:37], v9 offset:10048
	ds_read_b128 v[38:41], v9 offset:10064
	v_lshlrev_b32_e32 v42, 16, v252
	v_and_b32_e32 v43, 0xffff0000, v252
	v_lshlrev_b32_e32 v44, 16, v253
	v_and_b32_e32 v45, 0xffff0000, v253
	s_waitcnt lgkmcnt(2)
	v_pk_fma_f32 v[0:1], v[26:27], v[42:43], v[0:1]
	v_pk_fma_f32 v[2:3], v[28:29], v[44:45], v[2:3]
	v_lshlrev_b32_e32 v46, 16, v254
	v_and_b32_e32 v47, 0xffff0000, v254
	v_lshlrev_b32_e32 v80, 16, v255
	v_and_b32_e32 v81, 0xffff0000, v255
	v_pk_fma_f32 v[4:5], v[30:31], v[46:47], v[4:5]
	v_pk_fma_f32 v[6:7], v[32:33], v[80:81], v[6:7]
	s_mov_b64 exec, s[4:5]
	v_lshlrev_b32_e32 v42, 16, v168
	v_and_b32_e32 v43, 0xffff0000, v168
	v_lshlrev_b32_e32 v44, 16, v169
	v_and_b32_e32 v45, 0xffff0000, v169
	s_waitcnt lgkmcnt(0)
	v_pk_fma_f32 v[0:1], v[34:35], v[42:43], v[0:1]
	v_pk_fma_f32 v[2:3], v[36:37], v[44:45], v[2:3]
	v_lshlrev_b32_e32 v46, 16, v170
	v_and_b32_e32 v47, 0xffff0000, v170
	v_lshlrev_b32_e32 v80, 16, v171
	v_and_b32_e32 v81, 0xffff0000, v171
	v_pk_fma_f32 v[4:5], v[38:39], v[46:47], v[4:5]
	v_pk_fma_f32 v[6:7], v[40:41], v[80:81], v[6:7]
	s_mov_b64 exec, -1
	v_cvt_pk_bf16_f32 v68, v0, v1
	v_cvt_pk_bf16_f32 v69, v2, v3
	v_cvt_pk_bf16_f32 v70, v4, v5
	v_cvt_pk_bf16_f32 v71, v6, v7
	s_waitcnt lgkmcnt(3)
	s_waitcnt lgkmcnt(1)
	s_waitcnt lgkmcnt(0)
	s_nop 0
	s_waitcnt vmcnt(4)
	s_waitcnt vmcnt(4)
	s_waitcnt lgkmcnt(3)
	s_waitcnt lgkmcnt(1)
	s_waitcnt lgkmcnt(0)
	s_waitcnt vmcnt(4)
	s_waitcnt vmcnt(4)
	ds_read_b128 v[0:3], v9 offset:10624
	ds_read_b128 v[4:7], v9 offset:10640
	ds_read_b128 v[26:29], v9 offset:8576
	ds_read_b128 v[30:33], v9 offset:8592
	ds_read_b128 v[34:37], v9 offset:9088
	ds_read_b128 v[38:41], v9 offset:9104
	s_mov_b64 exec, vcc
	v_lshlrev_b32_e32 v42, 16, v178
	v_and_b32_e32 v43, 0xffff0000, v178
	v_lshlrev_b32_e32 v44, 16, v179
	v_and_b32_e32 v45, 0xffff0000, v179
	s_waitcnt lgkmcnt(2)
	v_pk_fma_f32 v[0:1], v[26:27], v[42:43], v[0:1]
	v_pk_fma_f32 v[2:3], v[28:29], v[44:45], v[2:3]
	v_lshlrev_b32_e32 v46, 16, v180
	v_and_b32_e32 v47, 0xffff0000, v180
	v_lshlrev_b32_e32 v80, 16, v181
	v_and_b32_e32 v81, 0xffff0000, v181
	v_pk_fma_f32 v[4:5], v[30:31], v[46:47], v[4:5]
	v_pk_fma_f32 v[6:7], v[32:33], v[80:81], v[6:7]
	s_mov_b64 exec, -1
	ds_read_b128 v[26:29], v9 offset:9600
	ds_read_b128 v[30:33], v9 offset:9616
	s_mov_b64 exec, s[0:1]
	v_lshlrev_b32_e32 v42, 16, v182
	v_and_b32_e32 v43, 0xffff0000, v182
	v_lshlrev_b32_e32 v44, 16, v183
	v_and_b32_e32 v45, 0xffff0000, v183
	s_waitcnt lgkmcnt(2)
	v_pk_fma_f32 v[0:1], v[34:35], v[42:43], v[0:1]
	v_pk_fma_f32 v[2:3], v[36:37], v[44:45], v[2:3]
	v_lshlrev_b32_e32 v46, 16, v184
	v_and_b32_e32 v47, 0xffff0000, v184
	v_lshlrev_b32_e32 v80, 16, v185
	v_and_b32_e32 v81, 0xffff0000, v185
	v_pk_fma_f32 v[4:5], v[38:39], v[46:47], v[4:5]
	v_pk_fma_f32 v[6:7], v[40:41], v[80:81], v[6:7]
	s_mov_b64 exec, -1
	ds_read_b128 v[34:37], v9 offset:10112
	ds_read_b128 v[38:41], v9 offset:10128
	v_lshlrev_b32_e32 v42, 16, v186
	v_and_b32_e32 v43, 0xffff0000, v186
	v_lshlrev_b32_e32 v44, 16, v187
	v_and_b32_e32 v45, 0xffff0000, v187
	s_waitcnt lgkmcnt(2)
	v_pk_fma_f32 v[0:1], v[26:27], v[42:43], v[0:1]
	v_pk_fma_f32 v[2:3], v[28:29], v[44:45], v[2:3]
	v_lshlrev_b32_e32 v46, 16, v188
	v_and_b32_e32 v47, 0xffff0000, v188
	v_lshlrev_b32_e32 v80, 16, v189
	v_and_b32_e32 v81, 0xffff0000, v189
	v_pk_fma_f32 v[4:5], v[30:31], v[46:47], v[4:5]
	v_pk_fma_f32 v[6:7], v[32:33], v[80:81], v[6:7]
	s_mov_b64 exec, s[4:5]
	v_lshlrev_b32_e32 v42, 16, v190
	v_and_b32_e32 v43, 0xffff0000, v190
	v_lshlrev_b32_e32 v44, 16, v191
	v_and_b32_e32 v45, 0xffff0000, v191
	s_waitcnt lgkmcnt(0)
	v_pk_fma_f32 v[0:1], v[34:35], v[42:43], v[0:1]
	v_pk_fma_f32 v[2:3], v[36:37], v[44:45], v[2:3]
	v_lshlrev_b32_e32 v46, 16, v192
	v_and_b32_e32 v47, 0xffff0000, v192
	v_lshlrev_b32_e32 v80, 16, v193
	v_and_b32_e32 v81, 0xffff0000, v193
	v_pk_fma_f32 v[4:5], v[38:39], v[46:47], v[4:5]
	v_pk_fma_f32 v[6:7], v[40:41], v[80:81], v[6:7]
	s_mov_b64 exec, -1
	v_cvt_pk_bf16_f32 v72, v0, v1
	v_cvt_pk_bf16_f32 v73, v2, v3
	v_cvt_pk_bf16_f32 v74, v4, v5
	v_cvt_pk_bf16_f32 v75, v6, v7
	s_waitcnt lgkmcnt(3)
	s_waitcnt lgkmcnt(1)
	s_waitcnt lgkmcnt(0)
	v_lshlrev_b32_e32 v38, 3, v93
	s_nop 0
	s_nop 0
	v_or_b32_e32 v39, 16, v38
	s_waitcnt vmcnt(0)
	s_waitcnt vmcnt(0)
	s_waitcnt lgkmcnt(3)
	s_waitcnt lgkmcnt(1)
	s_waitcnt lgkmcnt(0)
	s_waitcnt vmcnt(0)
	s_waitcnt vmcnt(0)
	ds_read_b128 v[0:3], v9 offset:10688
	ds_read_b128 v[4:7], v9 offset:10704
	ds_read_b128 v[26:29], v9 offset:8640
	ds_read_b128 v[30:33], v9 offset:8656
	ds_read_b128 v[34:37], v9 offset:9152
	ds_read_b128 v[40:43], v9 offset:9168
	s_mov_b64 exec, vcc
	v_lshlrev_b32_e32 v44, 16, v194
	v_and_b32_e32 v45, 0xffff0000, v194
	v_lshlrev_b32_e32 v46, 16, v195
	v_and_b32_e32 v47, 0xffff0000, v195
	s_waitcnt lgkmcnt(2)
	v_pk_fma_f32 v[0:1], v[26:27], v[44:45], v[0:1]
	v_pk_fma_f32 v[2:3], v[28:29], v[46:47], v[2:3]
	v_lshlrev_b32_e32 v80, 16, v196
	v_and_b32_e32 v81, 0xffff0000, v196
	v_lshlrev_b32_e32 v82, 16, v197
	v_and_b32_e32 v83, 0xffff0000, v197
	v_pk_fma_f32 v[4:5], v[30:31], v[80:81], v[4:5]
	v_pk_fma_f32 v[6:7], v[32:33], v[82:83], v[6:7]
	s_mov_b64 exec, -1
	ds_read_b128 v[26:29], v9 offset:9664
	ds_read_b128 v[30:33], v9 offset:9680
	s_mov_b64 exec, s[0:1]
	v_lshlrev_b32_e32 v44, 16, v198
	v_and_b32_e32 v45, 0xffff0000, v198
	v_lshlrev_b32_e32 v46, 16, v199
	v_and_b32_e32 v47, 0xffff0000, v199
	s_waitcnt lgkmcnt(2)
	v_pk_fma_f32 v[0:1], v[34:35], v[44:45], v[0:1]
	v_pk_fma_f32 v[2:3], v[36:37], v[46:47], v[2:3]
	v_lshlrev_b32_e32 v80, 16, v200
	v_and_b32_e32 v81, 0xffff0000, v200
	v_lshlrev_b32_e32 v82, 16, v201
	v_and_b32_e32 v83, 0xffff0000, v201
	v_pk_fma_f32 v[4:5], v[40:41], v[80:81], v[4:5]
	v_pk_fma_f32 v[6:7], v[42:43], v[82:83], v[6:7]
	s_mov_b64 exec, -1
	ds_read_b128 v[34:37], v9 offset:10176
	ds_read_b128 v[40:43], v9 offset:10192
	v_lshlrev_b32_e32 v44, 16, v202
	v_and_b32_e32 v45, 0xffff0000, v202
	v_lshlrev_b32_e32 v46, 16, v203
	v_and_b32_e32 v47, 0xffff0000, v203
	s_waitcnt lgkmcnt(2)
	v_pk_fma_f32 v[0:1], v[26:27], v[44:45], v[0:1]
	v_pk_fma_f32 v[2:3], v[28:29], v[46:47], v[2:3]
	v_lshlrev_b32_e32 v80, 16, v204
	v_and_b32_e32 v81, 0xffff0000, v204
	v_lshlrev_b32_e32 v82, 16, v205
	v_and_b32_e32 v83, 0xffff0000, v205
	v_pk_fma_f32 v[4:5], v[30:31], v[80:81], v[4:5]
	v_pk_fma_f32 v[6:7], v[32:33], v[82:83], v[6:7]
	s_mov_b64 exec, s[4:5]
	v_lshlrev_b32_e32 v44, 16, v206
	v_and_b32_e32 v45, 0xffff0000, v206
	v_lshlrev_b32_e32 v46, 16, v207
	v_and_b32_e32 v47, 0xffff0000, v207
	s_waitcnt lgkmcnt(0)
	v_pk_fma_f32 v[0:1], v[34:35], v[44:45], v[0:1]
	v_pk_fma_f32 v[2:3], v[36:37], v[46:47], v[2:3]
	v_lshlrev_b32_e32 v80, 16, v208
	v_and_b32_e32 v81, 0xffff0000, v208
	v_lshlrev_b32_e32 v82, 16, v209
	v_and_b32_e32 v83, 0xffff0000, v209
	v_pk_fma_f32 v[4:5], v[40:41], v[80:81], v[4:5]
	v_pk_fma_f32 v[6:7], v[42:43], v[82:83], v[6:7]
	s_mov_b64 exec, -1
	v_cvt_pk_bf16_f32 v76, v0, v1
	v_cvt_pk_bf16_f32 v77, v2, v3
	v_cvt_pk_bf16_f32 v78, v4, v5
	v_cvt_pk_bf16_f32 v79, v6, v7
	s_waitcnt lgkmcnt(3)
	s_waitcnt lgkmcnt(1)
	s_waitcnt lgkmcnt(0)
	v_cmp_eq_u32_e32 vcc, v38, v94
	v_or_b32_e32 v2, 1, v38
	v_cndmask_b32_e32 v0, 0, v134, vcc
	v_or_b32_e32 v1, 2, v38
	v_cmp_eq_u32_e32 vcc, v2, v94
	v_or_b32_e32 v4, 3, v38
	v_or_b32_e32 v3, 4, v38
	v_cndmask_b32_e32 v2, 0, v134, vcc
	v_cmp_eq_u32_e32 vcc, v1, v94
	v_or_b32_e32 v5, 6, v38
	v_or_b32_e32 v6, 5, v38
	v_cndmask_b32_e32 v1, 0, v134, vcc
	v_cmp_eq_u32_e32 vcc, v4, v94
	v_or_b32_e32 v7, 7, v38
	v_or_b32_e32 v11, 17, v38
	v_cndmask_b32_e32 v4, 0, v134, vcc
	v_cmp_eq_u32_e32 vcc, v3, v94
	v_or_b32_e32 v10, 18, v38
	v_or_b32_e32 v13, 19, v38
	v_cndmask_b32_e32 v3, 0, v134, vcc
	v_cmp_eq_u32_e32 vcc, v5, v94
	v_or_b32_e32 v12, 20, v38
	v_or_b32_e32 v14, 22, v38
	v_cndmask_b32_e32 v5, 0, v134, vcc
	v_cmp_eq_u32_e32 vcc, v6, v94
	v_or_b32_e32 v15, 21, v38
	v_or_b32_e32 v16, 23, v38
	v_cndmask_b32_e32 v6, 0, v134, vcc
	v_cmp_eq_u32_e32 vcc, v7, v94
	v_and_b32_e32 v18, 64, v132
	v_xor_b32_e32 v17, 32, v132
	v_cndmask_b32_e32 v7, 0, v134, vcc
	v_cmp_eq_u32_e32 vcc, v39, v94
	v_add_u32_e32 v18, 64, v18
	s_lshl_b32 s4, s62, 8
	v_cndmask_b32_e32 v9, 0, v134, vcc
	v_cmp_eq_u32_e32 vcc, v11, v94
	s_add_i32 s4, s4, 16
	v_cmp_eq_u32_e64 s[0:1], 0, v93
	v_cndmask_b32_e32 v11, 0, v134, vcc
	v_cmp_eq_u32_e32 vcc, v10, v94
	v_lshl_add_u32 v139, v94, 3, s4
	v_perm_b32 v82, v6, v3, s83
	v_cndmask_b32_e32 v10, 0, v134, vcc
	v_cmp_eq_u32_e32 vcc, v13, v94
	v_perm_b32 v81, v4, v1, s83
	v_perm_b32 v83, v7, v5, s83
	v_cndmask_b32_e32 v13, 0, v134, vcc
	v_cmp_eq_u32_e32 vcc, v12, v94
	v_perm_b32 v80, v2, v0, s83
	v_perm_b32 v85, v13, v10, s83
	v_cndmask_b32_e32 v12, 0, v134, vcc
	v_cmp_eq_u32_e32 vcc, v14, v94
	v_perm_b32 v84, v11, v9, s83
	s_nop 0
	v_cndmask_b32_e32 v14, 0, v134, vcc
	v_cmp_eq_u32_e32 vcc, v15, v94
	s_nop 1
	v_cndmask_b32_e32 v15, 0, v134, vcc
	v_cmp_eq_u32_e32 vcc, v16, v94
	v_perm_b32 v86, v15, v12, s83
	s_nop 0
	v_cndmask_b32_e32 v16, 0, v134, vcc
	v_cmp_lt_i32_e32 vcc, v17, v18
	v_perm_b32 v87, v16, v14, s83
	s_nop 0
	v_cndmask_b32_e32 v17, v132, v17, vcc
	v_lshlrev_b32_e32 v140, 2, v17
	v_lshlrev_b32_e32 v175, 2, v91
	global_load_dword v172, v175, s[42:43]
	global_load_dword v173, v175, s[36:37]
	global_load_dword v174, v175, s[40:41]
	v_xad_u32 v148, v88, v8, v95
	ds_read_b128 v[0:3], v148 offset:16384
	ds_read_b128 v[4:7], v148 offset:49152
	s_waitcnt lgkmcnt(1)
	v_mfma_f32_32x32x16_bf16 v[32:47], v[48:51], v[0:3], 0
	v_or_b32_e32 v0, 32, v88
	v_xad_u32 v150, v0, v8, v95
	s_waitcnt lgkmcnt(0)
	v_mfma_f32_32x32x16_bf16 v[16:31], v[48:51], v[4:7], 0
	ds_read_b128 v[0:3], v150 offset:16384
	ds_read_b128 v[4:7], v150 offset:49152
	s_waitcnt lgkmcnt(1)
	v_mfma_f32_32x32x16_bf16 v[32:47], v[52:55], v[0:3], v[32:47]
	v_or_b32_e32 v0, 64, v88
	v_xad_u32 v145, v0, v8, v95
	s_waitcnt lgkmcnt(0)
	v_mfma_f32_32x32x16_bf16 v[16:31], v[52:55], v[4:7], v[16:31]
	ds_read_b128 v[0:3], v145 offset:16384
	ds_read_b128 v[4:7], v145 offset:49152
	s_waitcnt lgkmcnt(1)
	v_mfma_f32_32x32x16_bf16 v[32:47], v[56:59], v[0:3], v[32:47]
	v_or_b32_e32 v0, 0x60, v88
	v_xad_u32 v149, v0, v8, v95
	s_waitcnt lgkmcnt(0)
	v_mfma_f32_32x32x16_bf16 v[16:31], v[56:59], v[4:7], v[16:31]
	ds_read_b128 v[0:3], v149 offset:16384
	ds_read_b128 v[4:7], v149 offset:49152
	s_waitcnt lgkmcnt(1)
	v_mfma_f32_32x32x16_bf16 v[32:47], v[60:63], v[0:3], v[32:47]
	v_or_b32_e32 v0, 0x80, v88
	v_xad_u32 v144, v0, v8, v95
	s_waitcnt lgkmcnt(0)
	v_mfma_f32_32x32x16_bf16 v[16:31], v[60:63], v[4:7], v[16:31]
	ds_read_b128 v[0:3], v144 offset:16384
	ds_read_b128 v[4:7], v144 offset:49152
	s_waitcnt lgkmcnt(1)
	v_mfma_f32_32x32x16_bf16 v[32:47], v[64:67], v[0:3], v[32:47]
	v_or_b32_e32 v0, 0xa0, v88
	v_xad_u32 v147, v0, v8, v95
	s_waitcnt lgkmcnt(0)
	v_mfma_f32_32x32x16_bf16 v[16:31], v[64:67], v[4:7], v[16:31]
	ds_read_b128 v[0:3], v147 offset:16384
	ds_read_b128 v[4:7], v147 offset:49152
	s_waitcnt lgkmcnt(1)
	v_mfma_f32_32x32x16_bf16 v[32:47], v[68:71], v[0:3], v[32:47]
	v_or_b32_e32 v0, 0xc0, v88
	v_xad_u32 v143, v0, v8, v95
	s_waitcnt lgkmcnt(0)
	v_mfma_f32_32x32x16_bf16 v[16:31], v[68:71], v[4:7], v[16:31]
	ds_read_b128 v[0:3], v143 offset:16384
	ds_read_b128 v[4:7], v143 offset:49152
	s_waitcnt lgkmcnt(1)
	v_mfma_f32_32x32x16_bf16 v[32:47], v[72:75], v[0:3], v[32:47]
	v_or_b32_e32 v0, 0xe0, v88
	v_xad_u32 v146, v0, v8, v95
	s_waitcnt lgkmcnt(0)
	v_mfma_f32_32x32x16_bf16 v[16:31], v[72:75], v[4:7], v[16:31]
	ds_read_b128 v[0:3], v146 offset:16384
	ds_read_b128 v[4:7], v146 offset:49152
	s_waitcnt lgkmcnt(1)
	v_mfma_f32_32x32x16_bf16 v[32:47], v[76:79], v[0:3], v[32:47]
	s_waitcnt lgkmcnt(0)
	v_mfma_f32_32x32x16_bf16 v[16:31], v[76:79], v[4:7], v[16:31]
	v_mfma_f32_32x32x16_bf16 v[0:15], v[48:51], v[80:83], 0
	v_mfma_f32_32x32x16_bf16 v[0:15], v[52:55], v[84:87], v[0:15]
	v_lshlrev_b32_e32 v88, 2, v91
	s_waitcnt vmcnt(0)
	ds_read_b32 v251, v167
	v_mul_f32_e32 v97, 0xbfb8aa3b, v173
	v_mul_f32_e32 v96, 0xbfb8aa3b, v174
	v_fmamk_f32 v32, v32, 0xbfb8aa3b, v97
	v_fmamk_f32 v34, v34, 0xbfb8aa3b, v97
	v_fmamk_f32 v33, v33, 0xbfb8aa3b, v97
	v_fmamk_f32 v35, v35, 0xbfb8aa3b, v97
	v_fmamk_f32 v16, v16, 0xbfb8aa3b, v96
	v_fmamk_f32 v17, v17, 0xbfb8aa3b, v96
	v_exp_f32_e32 v32, v32
	v_exp_f32_e32 v34, v34
	v_exp_f32_e32 v33, v33
	v_exp_f32_e32 v107, v35
	v_exp_f32_e32 v91, v16
	v_exp_f32_e32 v98, v17
	v_add_f32_e32 v32, 1.0, v32
	v_add_f32_e32 v108, 1.0, v34
	v_add_f32_e32 v33, 1.0, v33
	v_rcp_f32_e32 v109, v32
	v_rcp_f32_e32 v111, v33
	v_add_f32_e32 v91, 1.0, v91
	v_rcp_f32_e32 v110, v91
	v_add_f32_e32 v98, 1.0, v98
	v_rcp_f32_e32 v112, v98
	v_fmamk_f32 v18, v18, 0xbfb8aa3b, v96
	v_exp_f32_e32 v18, v18
	v_fmamk_f32 v20, v20, 0xbfb8aa3b, v96
	v_add_f32_e32 v18, 1.0, v18
	v_exp_f32_e32 v20, v20
	v_fmamk_f32 v19, v19, 0xbfb8aa3b, v96
	v_exp_f32_e32 v19, v19
	v_fmamk_f32 v21, v21, 0xbfb8aa3b, v96
	s_waitcnt lgkmcnt(0)
	v_mul_f32_e32 v33, 0x3fb8aa3b, v251
	v_mul_f32_e32 v16, v109, v33
	v_exp_f32_e32 v32, v16
	v_mul_f32_e32 v17, v111, v33
	v_exp_f32_e32 v34, v17
	v_rcp_f32_e32 v16, v108
	v_rcp_f32_e32 v17, v18
	v_fma_f32 v18, -v32, v32, 1.0
	v_sqrt_f32_e32 v18, v18
	v_mul_f32_e32 v16, v16, v33
	v_add_f32_e32 v19, 1.0, v19
	v_mul_f32_e32 v18, v110, v18
	v_mul_f32_e32 v18, v0, v18
	v_exp_f32_e32 v0, v16
	v_add_f32_e32 v16, 1.0, v107
	v_rcp_f32_e32 v16, v16
	v_rcp_f32_e32 v19, v19
	v_fma_f32 v91, -v0, v0, 1.0
	v_sqrt_f32_e32 v91, v91
	v_mul_f32_e32 v16, v16, v33
	v_exp_f32_e32 v98, v16
	v_fmamk_f32 v16, v36, 0xbfb8aa3b, v97
	v_exp_f32_e32 v16, v16
	v_mul_f32_e32 v91, v17, v91
	v_add_f32_e32 v17, 1.0, v20
	v_fma_f32 v36, -v98, v98, 1.0
	v_add_f32_e32 v16, 1.0, v16
	v_rcp_f32_e32 v16, v16
	v_sqrt_f32_e32 v36, v36
	v_rcp_f32_e32 v17, v17
	v_mul_f32_e32 v16, v16, v33
	v_exp_f32_e32 v20, v16
	v_fmamk_f32 v16, v37, 0xbfb8aa3b, v97
	v_exp_f32_e32 v16, v16
	v_mul_f32_e32 v36, v19, v36
	v_fma_f32 v19, -v20, v20, 1.0
	v_sqrt_f32_e32 v19, v19
	v_add_f32_e32 v16, 1.0, v16
	v_rcp_f32_e32 v16, v16
	v_exp_f32_e32 v21, v21
	v_mul_f32_e32 v17, v17, v19
	v_mul_f32_e32 v19, v4, v17
	v_mul_f32_e32 v16, v16, v33
	v_exp_f32_e32 v37, v16
	v_fmamk_f32 v16, v38, 0xbfb8aa3b, v97
	v_exp_f32_e32 v16, v16
	v_add_f32_e32 v4, 1.0, v21
	v_fmamk_f32 v21, v22, 0xbfb8aa3b, v96
	v_add_f32_e32 v16, 1.0, v16
	v_rcp_f32_e32 v16, v16
	v_fma_f32 v17, -v37, v37, 1.0
	v_exp_f32_e32 v21, v21
	v_rcp_f32_e32 v4, v4
	v_mul_f32_e32 v16, v16, v33
	v_sqrt_f32_e32 v17, v17
	v_exp_f32_e32 v38, v16
	v_add_f32_e32 v16, 1.0, v21
	v_fmamk_f32 v21, v39, 0xbfb8aa3b, v97
	v_mul_f32_e32 v4, v4, v17
	v_fma_f32 v17, -v38, v38, 1.0
	v_rcp_f32_e32 v16, v16
	v_sqrt_f32_e32 v17, v17
	v_exp_f32_e32 v21, v21
	v_fmamk_f32 v22, v23, 0xbfb8aa3b, v96
	v_mul_f32_e32 v23, v16, v17
	v_add_f32_e32 v16, 1.0, v21
	v_rcp_f32_e32 v16, v16
	v_fmamk_f32 v21, v40, 0xbfb8aa3b, v97
	v_exp_f32_e32 v21, v21
	v_mul_f32_e32 v16, v16, v33
	v_exp_f32_e32 v39, v16
	v_add_f32_e32 v16, 1.0, v21
	v_rcp_f32_e32 v16, v16
	v_exp_f32_e32 v22, v22
	v_fmamk_f32 v21, v24, 0xbfb8aa3b, v96
	v_mul_f32_e32 v16, v16, v33
	v_add_f32_e32 v17, 1.0, v22
	v_fma_f32 v22, -v39, v39, 1.0
	v_sqrt_f32_e32 v24, v22
	v_exp_f32_e32 v22, v16
	v_fmamk_f32 v16, v41, 0xbfb8aa3b, v97
	v_exp_f32_e32 v16, v16
	v_exp_f32_e32 v21, v21
	v_fma_f32 v40, -v22, v22, 1.0
	v_rcp_f32_e32 v17, v17
	v_add_f32_e32 v16, 1.0, v16
	v_rcp_f32_e32 v16, v16
	v_add_f32_e32 v21, 1.0, v21
	v_rcp_f32_e32 v21, v21
	v_sqrt_f32_e32 v40, v40
	v_mul_f32_e32 v16, v16, v33
	v_mul_f32_e32 v24, v17, v24
	v_mul_f32_e32 v17, v21, v40
	v_exp_f32_e32 v40, v16
	v_fmamk_f32 v16, v42, 0xbfb8aa3b, v97
	v_fmamk_f32 v25, v25, 0xbfb8aa3b, v96
	v_exp_f32_e32 v16, v16
	v_exp_f32_e32 v25, v25
	v_fma_f32 v35, -v34, v34, 1.0
	v_sqrt_f32_e32 v35, v35
	v_add_f32_e32 v16, 1.0, v16
	v_add_f32_e32 v21, 1.0, v25
	v_rcp_f32_e32 v16, v16
	v_rcp_f32_e32 v25, v21
	v_fma_f32 v21, -v40, v40, 1.0
	v_sqrt_f32_e32 v41, v21
	v_fmamk_f32 v21, v26, 0xbfb8aa3b, v96
	v_mul_f32_e32 v16, v16, v33
	v_exp_f32_e32 v26, v21
	v_mul_f32_e32 v21, v8, v17
	v_mul_f32_e32 v8, v25, v41
	v_exp_f32_e32 v41, v16
	v_fmamk_f32 v16, v43, 0xbfb8aa3b, v97
	v_exp_f32_e32 v16, v16
	v_add_f32_e32 v17, 1.0, v26
	v_fma_f32 v25, -v41, v41, 1.0
	v_fmamk_f32 v26, v27, 0xbfb8aa3b, v96
	v_add_f32_e32 v16, 1.0, v16
	v_rcp_f32_e32 v16, v16
	v_rcp_f32_e32 v17, v17
	v_sqrt_f32_e32 v25, v25
	v_mul_f32_e32 v16, v16, v33
	v_exp_f32_e32 v26, v26
	v_exp_f32_e32 v99, v16
	v_mul_f32_e32 v100, v17, v25
	v_fmamk_f32 v25, v44, 0xbfb8aa3b, v97
	v_add_f32_e32 v16, 1.0, v26
	v_fmamk_f32 v26, v28, 0xbfb8aa3b, v96
	v_fma_f32 v17, -v99, v99, 1.0
	v_exp_f32_e32 v25, v25
	v_rcp_f32_e32 v16, v16
	v_sqrt_f32_e32 v17, v17
	v_exp_f32_e32 v26, v26
	v_add_f32_e32 v25, 1.0, v25
	v_rcp_f32_e32 v25, v25
	v_mul_f32_e32 v101, v16, v17
	v_add_f32_e32 v16, 1.0, v26
	v_fmamk_f32 v26, v29, 0xbfb8aa3b, v96
	v_exp_f32_e32 v26, v26
	v_rcp_f32_e32 v17, v16
	v_mul_f32_e32 v16, v25, v33
	v_fmamk_f32 v25, v45, 0xbfb8aa3b, v97
	v_exp_f32_e32 v25, v25
	v_add_f32_e32 v26, 1.0, v26
	v_rcp_f32_e32 v42, v26
	v_fmamk_f32 v26, v46, 0xbfb8aa3b, v97
	v_exp_f32_e32 v26, v26
	v_add_f32_e32 v25, 1.0, v25
	v_rcp_f32_e32 v25, v25
	v_fmamk_f32 v27, v30, 0xbfb8aa3b, v96
	v_exp_f32_e32 v27, v27
	v_add_f32_e32 v26, 1.0, v26
	v_rcp_f32_e32 v26, v26
	v_mul_f32_e32 v25, v25, v33
	v_exp_f32_e32 v43, v25
	v_add_f32_e32 v25, 1.0, v27
	v_rcp_f32_e32 v44, v25
	v_mul_f32_e32 v25, v26, v33
	v_fmamk_f32 v26, v47, 0xbfb8aa3b, v97
	v_exp_f32_e32 v26, v26
	v_fmamk_f32 v27, v31, 0xbfb8aa3b, v96
	v_exp_f32_e32 v27, v27
	v_add_f32_e32 v26, 1.0, v26
	v_rcp_f32_e32 v26, v26
	v_exp_f32_e32 v16, v16
	v_fmac_f32_e32 v18, 0, v32
	v_mul_f32_e32 v35, v112, v35
	v_exp_f32_e32 v45, v25
	v_add_f32_e32 v25, 1.0, v27
	v_mul_f32_e32 v31, v34, v18
	v_rcp_f32_e32 v46, v25
	v_mul_f32_e32 v25, v26, v33
	v_fmac_f32_e32 v31, v1, v35
	v_mul_f32_e32 v33, v32, v34
	v_mul_f32_e32 v30, v0, v31
	v_mul_f32_e32 v34, v0, v33
	v_fma_f32 v0, -v16, v16, 1.0
	v_sqrt_f32_e32 v1, v0
	v_fmac_f32_e32 v30, v2, v91
	v_fmac_f32_e32 v21, 0, v22
	v_fma_f32 v2, -v43, v43, 1.0
	v_exp_f32_e32 v47, v25
	v_mul_f32_e32 v25, v40, v21
	v_mov_b32_e32 v0, v89
	v_sqrt_f32_e32 v2, v2
	v_fmac_f32_e32 v25, v9, v8
	v_pk_mul_f32 v[8:9], v[16:17], v[0:1]
	v_mul_f32_e32 v29, v98, v30
	v_fmac_f32_e32 v19, 0, v20
	v_fmac_f32_e32 v8, v12, v9
	v_fmac_f32_e32 v29, v3, v36
	v_mul_f32_e32 v28, v37, v19
	v_mov_b32_e32 v3, v8
	v_fmac_f32_e32 v28, v5, v4
	v_pk_mul_f32 v[4:5], v[42:43], v[2:3]
	v_fma_f32 v0, -v45, v45, 1.0
	v_fmac_f32_e32 v5, v13, v4
	v_sqrt_f32_e32 v4, v0
	v_mul_f32_e32 v27, v38, v28
	v_fmac_f32_e32 v27, v6, v23
	v_mul_f32_e32 v26, v39, v27
	v_fmac_f32_e32 v26, v7, v24
	v_pk_mul_f32 v[6:7], v[44:45], v[4:5]
	v_fma_f32 v0, -v47, v47, 1.0
	v_fmac_f32_e32 v7, v14, v6
	v_sqrt_f32_e32 v6, v0
	ds_bpermute_b32 v0, v140, v29
	v_mul_f32_e32 v24, v41, v25
	v_mul_f32_e32 v35, v98, v34
	v_mul_f32_e32 v36, v20, v37
	v_fmac_f32_e32 v24, v10, v100
	v_mul_f32_e32 v37, v38, v36
	v_mul_f32_e32 v23, v99, v24
	ds_bpermute_b32 v13, v140, v35
	v_mul_f32_e32 v38, v39, v37
	v_fmac_f32_e32 v23, v11, v101
	v_pk_mul_f32 v[10:11], v[46:47], v[6:7]
	s_waitcnt lgkmcnt(1)
	v_cndmask_b32_e64 v14, v29, v0, s[0:1]
	v_fmac_f32_e32 v11, v15, v10
	v_cndmask_b32_e64 v10, v0, v29, s[0:1]
	ds_bpermute_b32 v0, v140, v38
	ds_bpermute_b32 v3, v140, v26
	v_mul_f32_e32 v39, v22, v40
	v_mul_f32_e32 v40, v41, v39
	s_waitcnt lgkmcnt(2)
	v_cndmask_b32_e64 v1, v13, v35, s[0:1]
	v_mul_f32_e32 v12, v99, v40
	v_mul_f32_e32 v9, v16, v43
	v_cndmask_b32_e64 v2, v35, v13, s[0:1]
	v_fmac_f32_e32 v10, 0, v1
	v_mul_f32_e32 v4, v45, v9
	v_mul_f32_e32 v15, v35, v13
	v_fmac_f32_e32 v14, v2, v10
	s_waitcnt lgkmcnt(1)
	v_cndmask_b32_e64 v1, v0, v38, s[0:1]
	s_waitcnt lgkmcnt(0)
	v_cndmask_b32_e64 v17, v3, v26, s[0:1]
	v_cndmask_b32_e64 v41, v26, v3, s[0:1]
	ds_bpermute_b32 v2, v140, v12
	ds_bpermute_b32 v3, v140, v23
	v_mul_f32_e32 v6, v47, v4
	v_cndmask_b32_e64 v0, v38, v0, s[0:1]
	v_mul_f32_e32 v42, v15, v1
	v_fmac_f32_e32 v17, v1, v14
	v_mul_f32_e32 v43, v0, v42
	v_fmac_f32_e32 v41, v0, v17
	ds_bpermute_b32 v1, v140, v6
	ds_bpermute_b32 v0, v140, v11
	s_waitcnt lgkmcnt(3)
	v_cndmask_b32_e64 v47, v2, v12, s[0:1]
	s_waitcnt lgkmcnt(2)
	v_cndmask_b32_e64 v44, v3, v23, s[0:1]
	v_cndmask_b32_e64 v2, v12, v2, s[0:1]
	v_cndmask_b32_e64 v45, v23, v3, s[0:1]
	v_mul_f32_e32 v46, v47, v43
	v_fmac_f32_e32 v44, v47, v41
	v_mul_f32_e32 v47, v2, v46
	v_fmac_f32_e32 v45, v2, v44
	s_waitcnt lgkmcnt(1)
	v_cndmask_b32_e64 v2, v1, v6, s[0:1]
	s_waitcnt lgkmcnt(0)
	v_cndmask_b32_e64 v91, v0, v11, s[0:1]
	v_mul_f32_e32 v96, v2, v47
	v_fmac_f32_e32 v91, v2, v45
	s_and_saveexec_b64 s[4:5], s[0:1]
	v_mul_f32_e32 v3, v91, v1
	v_mul_f32_e32 v2, v96, v1
	v_add_f32_e32 v3, v3, v0
	ds_write_b64 v139, v[2:3]
	s_or_b64 exec, exec, s[4:5]
	s_cmp_gt_i32 s62, 0
	s_cselect_b64 s[12:13], -1, 0
	s_cmp_lt_i32 s62, 1
	v_mul_i32_i24_e32 v141, 0xffffff08, v94
	s_waitcnt lgkmcnt(0)
	s_barrier
	s_cbranch_scc1 .LBB0_327
	s_cmp_lt_u32 s62, 8
	s_cbranch_scc1 .LBB0_328
	v_add_u32_e32 v95, v95, v141
	s_and_b32 s4, s62, 0x7ffffff8
	v_mov_b32_e32 v0, 1.0
	v_mov_b32_e32 v3, 0
	s_mov_b32 s5, 0

.LBB0_333:
	s_or_b64 exec, exec, s[6:7]
	ds_read_b128 v[0:3], v148 offset:24576
	ds_read_b128 v[4:7], v148 offset:57344
	s_waitcnt lgkmcnt(1)
	v_mfma_f32_32x32x16_bf16 v[32:47], v[48:51], v[0:3], 0
	s_waitcnt lgkmcnt(0)
	v_mfma_f32_32x32x16_bf16 v[16:31], v[48:51], v[4:7], 0
	ds_read_b128 v[0:3], v150 offset:24576
	ds_read_b128 v[4:7], v150 offset:57344
	s_waitcnt lgkmcnt(1)
	v_mfma_f32_32x32x16_bf16 v[32:47], v[52:55], v[0:3], v[32:47]
	s_waitcnt lgkmcnt(0)
	v_mfma_f32_32x32x16_bf16 v[16:31], v[52:55], v[4:7], v[16:31]
	ds_read_b128 v[0:3], v145 offset:24576
	ds_read_b128 v[4:7], v145 offset:57344
	s_waitcnt lgkmcnt(1)
	v_mfma_f32_32x32x16_bf16 v[32:47], v[56:59], v[0:3], v[32:47]
	s_waitcnt lgkmcnt(0)
	v_mfma_f32_32x32x16_bf16 v[16:31], v[56:59], v[4:7], v[16:31]
	ds_read_b128 v[0:3], v149 offset:24576
	ds_read_b128 v[4:7], v149 offset:57344
	s_waitcnt lgkmcnt(1)
	v_mfma_f32_32x32x16_bf16 v[32:47], v[60:63], v[0:3], v[32:47]
	s_waitcnt lgkmcnt(0)
	v_mfma_f32_32x32x16_bf16 v[16:31], v[60:63], v[4:7], v[16:31]
	ds_read_b128 v[0:3], v144 offset:24576
	ds_read_b128 v[4:7], v144 offset:57344
	s_waitcnt lgkmcnt(1)
	v_mfma_f32_32x32x16_bf16 v[32:47], v[64:67], v[0:3], v[32:47]
	s_waitcnt lgkmcnt(0)
	v_mfma_f32_32x32x16_bf16 v[16:31], v[64:67], v[4:7], v[16:31]
	ds_read_b128 v[0:3], v147 offset:24576
	ds_read_b128 v[4:7], v147 offset:57344
	s_waitcnt lgkmcnt(1)
	v_mfma_f32_32x32x16_bf16 v[32:47], v[68:71], v[0:3], v[32:47]
	s_waitcnt lgkmcnt(0)
	v_mfma_f32_32x32x16_bf16 v[16:31], v[68:71], v[4:7], v[16:31]
	ds_read_b128 v[0:3], v143 offset:24576
	ds_read_b128 v[4:7], v143 offset:57344
	s_waitcnt lgkmcnt(1)
	v_mfma_f32_32x32x16_bf16 v[32:47], v[72:75], v[0:3], v[32:47]
	s_waitcnt lgkmcnt(0)
	v_mfma_f32_32x32x16_bf16 v[16:31], v[72:75], v[4:7], v[16:31]
	ds_read_b128 v[0:3], v146 offset:24576
	ds_read_b128 v[4:7], v146 offset:57344
	s_waitcnt lgkmcnt(1)
	v_mfma_f32_32x32x16_bf16 v[32:47], v[76:79], v[0:3], v[32:47]
	s_waitcnt lgkmcnt(0)
	v_mfma_f32_32x32x16_bf16 v[16:31], v[76:79], v[4:7], v[16:31]
	v_mfma_f32_32x32x16_bf16 v[0:15], v[56:59], v[80:83], 0
	v_mfma_f32_32x32x16_bf16 v[0:15], v[60:63], v[84:87], v[0:15]
	s_waitcnt vmcnt(16)
	ds_read_b32 v251, v167 offset:128
	v_mul_f32_e32 v151, 0xbfb8aa3b, v173
	v_mul_f32_e32 v93, 0xbfb8aa3b, v174
	v_fmamk_f32 v32, v32, 0xbfb8aa3b, v151
	v_fmamk_f32 v34, v34, 0xbfb8aa3b, v151
	v_fmamk_f32 v33, v33, 0xbfb8aa3b, v151
	v_fmamk_f32 v35, v35, 0xbfb8aa3b, v151
	v_fmamk_f32 v16, v16, 0xbfb8aa3b, v93
	v_fmamk_f32 v17, v17, 0xbfb8aa3b, v93
	v_exp_f32_e32 v32, v32
	v_exp_f32_e32 v34, v34
	v_exp_f32_e32 v33, v33
	v_exp_f32_e32 v161, v35
	v_exp_f32_e32 v91, v16
	v_exp_f32_e32 v152, v17
	v_add_f32_e32 v32, 1.0, v32
	v_add_f32_e32 v162, 1.0, v34
	v_add_f32_e32 v33, 1.0, v33
	v_rcp_f32_e32 v163, v32
	v_rcp_f32_e32 v165, v33
	v_add_f32_e32 v91, 1.0, v91
	v_rcp_f32_e32 v164, v91
	v_add_f32_e32 v152, 1.0, v152
	v_rcp_f32_e32 v166, v152
	v_fmamk_f32 v18, v18, 0xbfb8aa3b, v93
	v_exp_f32_e32 v18, v18
	v_fmamk_f32 v20, v20, 0xbfb8aa3b, v93
	v_add_f32_e32 v18, 1.0, v18
	v_exp_f32_e32 v20, v20
	v_fmamk_f32 v19, v19, 0xbfb8aa3b, v93
	v_exp_f32_e32 v19, v19
	v_fmamk_f32 v21, v21, 0xbfb8aa3b, v93
	s_waitcnt lgkmcnt(0)
	v_mul_f32_e32 v33, 0x3fb8aa3b, v251
	v_mul_f32_e32 v16, v163, v33
	v_exp_f32_e32 v32, v16
	v_mul_f32_e32 v17, v165, v33
	v_exp_f32_e32 v34, v17
	v_rcp_f32_e32 v16, v162
	v_rcp_f32_e32 v17, v18
	v_fma_f32 v18, -v32, v32, 1.0
	v_sqrt_f32_e32 v18, v18
	v_mul_f32_e32 v16, v16, v33
	v_add_f32_e32 v19, 1.0, v19
	v_mul_f32_e32 v18, v164, v18
	v_mul_f32_e32 v18, v0, v18
	v_exp_f32_e32 v0, v16
	v_add_f32_e32 v16, 1.0, v161
	v_rcp_f32_e32 v16, v16
	v_rcp_f32_e32 v19, v19
	v_fma_f32 v91, -v0, v0, 1.0
	v_sqrt_f32_e32 v91, v91
	v_mul_f32_e32 v16, v16, v33
	v_exp_f32_e32 v152, v16
	v_fmamk_f32 v16, v36, 0xbfb8aa3b, v151
	v_exp_f32_e32 v16, v16
	v_mul_f32_e32 v91, v17, v91
	v_add_f32_e32 v17, 1.0, v20
	v_fma_f32 v36, -v152, v152, 1.0
	v_add_f32_e32 v16, 1.0, v16
	v_rcp_f32_e32 v16, v16
	v_sqrt_f32_e32 v36, v36
	v_rcp_f32_e32 v17, v17
	v_mul_f32_e32 v16, v16, v33
	v_exp_f32_e32 v20, v16
	v_fmamk_f32 v16, v37, 0xbfb8aa3b, v151
	v_exp_f32_e32 v16, v16
	v_mul_f32_e32 v36, v19, v36
	v_fma_f32 v19, -v20, v20, 1.0
	v_sqrt_f32_e32 v19, v19
	v_add_f32_e32 v16, 1.0, v16
	v_rcp_f32_e32 v16, v16
	v_exp_f32_e32 v21, v21
	v_mul_f32_e32 v17, v17, v19
	v_mul_f32_e32 v19, v4, v17
	v_mul_f32_e32 v16, v16, v33
	v_exp_f32_e32 v37, v16
	v_fmamk_f32 v16, v38, 0xbfb8aa3b, v151
	v_exp_f32_e32 v16, v16
	v_add_f32_e32 v4, 1.0, v21
	v_fmamk_f32 v21, v22, 0xbfb8aa3b, v93
	v_add_f32_e32 v16, 1.0, v16
	v_rcp_f32_e32 v16, v16
	v_fma_f32 v17, -v37, v37, 1.0
	v_exp_f32_e32 v21, v21
	v_rcp_f32_e32 v4, v4
	v_mul_f32_e32 v16, v16, v33
	v_sqrt_f32_e32 v17, v17
	v_exp_f32_e32 v38, v16
	v_add_f32_e32 v16, 1.0, v21
	v_fmamk_f32 v21, v39, 0xbfb8aa3b, v151
	v_mul_f32_e32 v4, v4, v17
	v_fma_f32 v17, -v38, v38, 1.0
	v_rcp_f32_e32 v16, v16
	v_sqrt_f32_e32 v17, v17
	v_exp_f32_e32 v21, v21
	v_fmamk_f32 v22, v23, 0xbfb8aa3b, v93
	v_mul_f32_e32 v23, v16, v17
	v_add_f32_e32 v16, 1.0, v21
	v_rcp_f32_e32 v16, v16
	v_fmamk_f32 v21, v40, 0xbfb8aa3b, v151
	v_exp_f32_e32 v21, v21
	v_mul_f32_e32 v16, v16, v33
	v_exp_f32_e32 v39, v16
	v_add_f32_e32 v16, 1.0, v21
	v_rcp_f32_e32 v16, v16
	v_exp_f32_e32 v22, v22
	v_fmamk_f32 v21, v24, 0xbfb8aa3b, v93
	v_mul_f32_e32 v16, v16, v33
	v_add_f32_e32 v17, 1.0, v22
	v_fma_f32 v22, -v39, v39, 1.0
	v_sqrt_f32_e32 v24, v22
	v_exp_f32_e32 v22, v16
	v_fmamk_f32 v16, v41, 0xbfb8aa3b, v151
	v_exp_f32_e32 v16, v16
	v_exp_f32_e32 v21, v21
	v_fma_f32 v40, -v22, v22, 1.0
	v_rcp_f32_e32 v17, v17
	v_add_f32_e32 v16, 1.0, v16
	v_rcp_f32_e32 v16, v16
	v_add_f32_e32 v21, 1.0, v21
	v_rcp_f32_e32 v21, v21
	v_sqrt_f32_e32 v40, v40
	v_mul_f32_e32 v16, v16, v33
	v_mul_f32_e32 v24, v17, v24
	v_mul_f32_e32 v17, v21, v40
	v_exp_f32_e32 v40, v16
	v_fmamk_f32 v16, v42, 0xbfb8aa3b, v151
	v_fmamk_f32 v25, v25, 0xbfb8aa3b, v93
	v_exp_f32_e32 v16, v16
	v_exp_f32_e32 v25, v25
	v_fma_f32 v35, -v34, v34, 1.0
	v_sqrt_f32_e32 v35, v35
	v_add_f32_e32 v16, 1.0, v16
	v_add_f32_e32 v21, 1.0, v25
	v_rcp_f32_e32 v16, v16
	v_rcp_f32_e32 v25, v21
	v_fma_f32 v21, -v40, v40, 1.0
	v_sqrt_f32_e32 v41, v21
	v_fmamk_f32 v21, v26, 0xbfb8aa3b, v93
	v_mul_f32_e32 v16, v16, v33
	v_exp_f32_e32 v26, v21
	v_mul_f32_e32 v21, v8, v17
	v_mul_f32_e32 v8, v25, v41
	v_exp_f32_e32 v41, v16
	v_fmamk_f32 v16, v43, 0xbfb8aa3b, v151
	v_exp_f32_e32 v16, v16
	v_add_f32_e32 v17, 1.0, v26
	v_fma_f32 v25, -v41, v41, 1.0
	v_fmamk_f32 v26, v27, 0xbfb8aa3b, v93
	v_add_f32_e32 v16, 1.0, v16
	v_rcp_f32_e32 v16, v16
	v_rcp_f32_e32 v17, v17
	v_sqrt_f32_e32 v25, v25
	v_mul_f32_e32 v16, v16, v33
	v_exp_f32_e32 v26, v26
	v_exp_f32_e32 v153, v16
	v_mul_f32_e32 v154, v17, v25
	v_fmamk_f32 v25, v44, 0xbfb8aa3b, v151
	v_add_f32_e32 v16, 1.0, v26
	v_fmamk_f32 v26, v28, 0xbfb8aa3b, v93
	v_fma_f32 v17, -v153, v153, 1.0
	v_exp_f32_e32 v25, v25
	v_rcp_f32_e32 v16, v16
	v_sqrt_f32_e32 v17, v17
	v_exp_f32_e32 v26, v26
	v_add_f32_e32 v25, 1.0, v25
	v_rcp_f32_e32 v25, v25
	v_mul_f32_e32 v155, v16, v17
	v_add_f32_e32 v16, 1.0, v26
	v_fmamk_f32 v26, v29, 0xbfb8aa3b, v93
	v_exp_f32_e32 v26, v26
	v_rcp_f32_e32 v17, v16
	v_mul_f32_e32 v16, v25, v33
	v_fmamk_f32 v25, v45, 0xbfb8aa3b, v151
	v_exp_f32_e32 v25, v25
	v_add_f32_e32 v26, 1.0, v26
	v_rcp_f32_e32 v42, v26
	v_fmamk_f32 v26, v46, 0xbfb8aa3b, v151
	v_exp_f32_e32 v26, v26
	v_add_f32_e32 v25, 1.0, v25
	v_rcp_f32_e32 v25, v25
	v_fmamk_f32 v27, v30, 0xbfb8aa3b, v93
	v_exp_f32_e32 v27, v27
	v_add_f32_e32 v26, 1.0, v26
	v_rcp_f32_e32 v26, v26
	v_mul_f32_e32 v25, v25, v33
	v_exp_f32_e32 v43, v25
	v_add_f32_e32 v25, 1.0, v27
	v_rcp_f32_e32 v44, v25
	v_mul_f32_e32 v25, v26, v33
	v_fmamk_f32 v26, v47, 0xbfb8aa3b, v151
	v_exp_f32_e32 v26, v26
	v_fmamk_f32 v27, v31, 0xbfb8aa3b, v93
	v_exp_f32_e32 v27, v27
	v_add_f32_e32 v26, 1.0, v26
	v_rcp_f32_e32 v26, v26
	v_exp_f32_e32 v16, v16
	v_fmac_f32_e32 v18, 0, v32
	v_mul_f32_e32 v35, v166, v35
	v_exp_f32_e32 v45, v25
	v_add_f32_e32 v25, 1.0, v27
	v_mul_f32_e32 v31, v34, v18
	v_rcp_f32_e32 v46, v25
	v_mul_f32_e32 v25, v26, v33
	v_fmac_f32_e32 v31, v1, v35
	v_mul_f32_e32 v33, v32, v34
	v_fmac_f32_e32 v19, 0, v20
	v_mul_f32_e32 v30, v0, v31
	v_mul_f32_e32 v34, v0, v33
	v_mul_f32_e32 v28, v37, v19
	v_fma_f32 v0, -v16, v16, 1.0
	v_fmac_f32_e32 v28, v5, v4
	v_sqrt_f32_e32 v1, v0
	v_mul_f32_e32 v27, v38, v28
	v_fmac_f32_e32 v30, v2, v91
	v_fmac_f32_e32 v27, v6, v23
	v_fma_f32 v2, -v43, v43, 1.0
	v_mul_f32_e32 v26, v39, v27
	v_mov_b32_e32 v0, v89
	v_sqrt_f32_e32 v2, v2
	v_fmac_f32_e32 v26, v7, v24
	v_pk_mul_f32 v[6:7], v[16:17], v[0:1]
	v_mul_f32_e32 v29, v152, v30
	v_fmac_f32_e32 v6, v12, v7
	v_fmac_f32_e32 v29, v3, v36
	v_mov_b32_e32 v3, v6
	v_pk_mul_f32 v[4:5], v[42:43], v[2:3]
	v_fma_f32 v0, -v45, v45, 1.0
	v_exp_f32_e32 v47, v25
	v_fmac_f32_e32 v5, v13, v4
	v_sqrt_f32_e32 v4, v0
	v_fmac_f32_e32 v21, 0, v22
	v_mul_f32_e32 v25, v40, v21
	v_fmac_f32_e32 v25, v9, v8
	v_pk_mul_f32 v[8:9], v[44:45], v[4:5]
	v_fma_f32 v0, -v47, v47, 1.0
	v_fmac_f32_e32 v9, v14, v8
	v_sqrt_f32_e32 v8, v0
	ds_bpermute_b32 v0, v140, v29
	v_mul_f32_e32 v24, v41, v25
	v_mul_f32_e32 v35, v152, v34
	v_mul_f32_e32 v36, v20, v37
	v_fmac_f32_e32 v24, v10, v154
	v_mul_f32_e32 v37, v38, v36
	v_mul_f32_e32 v23, v153, v24
	ds_bpermute_b32 v13, v140, v35
	v_mul_f32_e32 v38, v39, v37
	v_fmac_f32_e32 v23, v11, v155
	v_pk_mul_f32 v[10:11], v[46:47], v[8:9]
	s_waitcnt lgkmcnt(1)
	v_cndmask_b32_e64 v14, v29, v0, s[0:1]
	v_fmac_f32_e32 v11, v15, v10
	v_cndmask_b32_e64 v10, v0, v29, s[0:1]
	ds_bpermute_b32 v0, v140, v38
	ds_bpermute_b32 v3, v140, v26
	v_mul_f32_e32 v39, v22, v40
	v_mul_f32_e32 v40, v41, v39
	s_waitcnt lgkmcnt(2)
	v_cndmask_b32_e64 v1, v13, v35, s[0:1]
	v_mul_f32_e32 v12, v153, v40
	v_mul_f32_e32 v7, v16, v43
	v_cndmask_b32_e64 v2, v35, v13, s[0:1]
	v_fmac_f32_e32 v10, 0, v1
	v_mul_f32_e32 v4, v45, v7
	v_mul_f32_e32 v15, v35, v13
	v_fmac_f32_e32 v14, v2, v10
	s_waitcnt lgkmcnt(1)
	v_cndmask_b32_e64 v1, v0, v38, s[0:1]
	s_waitcnt lgkmcnt(0)
	v_cndmask_b32_e64 v17, v3, v26, s[0:1]
	v_cndmask_b32_e64 v41, v26, v3, s[0:1]
	ds_bpermute_b32 v2, v140, v12
	ds_bpermute_b32 v3, v140, v23
	v_mul_f32_e32 v8, v47, v4
	v_cndmask_b32_e64 v0, v38, v0, s[0:1]
	v_mul_f32_e32 v42, v15, v1
	v_fmac_f32_e32 v17, v1, v14
	v_mul_f32_e32 v43, v0, v42
	v_fmac_f32_e32 v41, v0, v17
	ds_bpermute_b32 v1, v140, v8
	ds_bpermute_b32 v0, v140, v11
	s_waitcnt lgkmcnt(3)
	v_cndmask_b32_e64 v47, v2, v12, s[0:1]
	s_waitcnt lgkmcnt(2)
	v_cndmask_b32_e64 v44, v3, v23, s[0:1]
	v_cndmask_b32_e64 v2, v12, v2, s[0:1]
	v_cndmask_b32_e64 v45, v23, v3, s[0:1]
	v_mul_f32_e32 v46, v47, v43
	v_fmac_f32_e32 v44, v47, v41
	v_mul_f32_e32 v47, v2, v46
	v_fmac_f32_e32 v45, v2, v44
	s_waitcnt lgkmcnt(1)
	v_cndmask_b32_e64 v2, v1, v8, s[0:1]
	s_waitcnt lgkmcnt(0)
	v_cndmask_b32_e64 v91, v0, v11, s[0:1]
	v_mul_f32_e32 v93, v2, v47
	v_fmac_f32_e32 v91, v2, v45
	s_and_saveexec_b64 s[6:7], s[0:1]
	v_mul_f32_e32 v3, v91, v1
	v_mul_f32_e32 v2, v93, v1
	v_add_f32_e32 v3, v3, v0
	ds_write_b64 v139, v[2:3] offset:2048
	s_or_b64 exec, exec, s[6:7]
	v_cndmask_b32_e64 v0, 0, 1, s[12:13]
	v_cmp_ne_u32_e64 s[6:7], 1, v0
	s_andn2_b64 vcc, exec, s[12:13]
	s_waitcnt lgkmcnt(0)
	s_barrier
	s_cbranch_vccnz .LBB0_340
	s_cmp_lt_u32 s62, 8
	s_cbranch_scc1 .LBB0_341
	s_add_i32 s9, 16, 0x800
	s_and_b32 s8, s62, 0x7ffffff8
	v_add3_u32 v151, v141, v138, s9
	v_mov_b32_e32 v0, 1.0
	v_mov_b32_e32 v3, 0
	s_mov_b32 s9, 0

.LBB0_346:
	s_or_b64 exec, exec, s[8:9]
	ds_read_b128 v[0:3], v148 offset:32768
	ds_read_b128 v[4:7], v150 offset:32768
	v_add_u32_e32 v8, 0x8000, v150
	s_waitcnt lgkmcnt(1)
	v_mfma_f32_32x32x16_bf16 v[16:31], v[48:51], v[0:3], 0
	v_add_u32_e32 v0, 0x8000, v148
	ds_read_b128 v[0:3], v0 offset:32768
	ds_read_b128 v[8:11], v8 offset:32768
	s_waitcnt lgkmcnt(1)
	v_mfma_f32_32x32x16_bf16 v[32:47], v[48:51], v[0:3], 0
	v_mfma_f32_32x32x16_bf16 v[16:31], v[52:55], v[4:7], v[16:31]
	ds_read_b128 v[0:3], v145 offset:32768
	ds_read_b128 v[4:7], v149 offset:32768
	s_waitcnt lgkmcnt(2)
	v_mfma_f32_32x32x16_bf16 v[32:47], v[52:55], v[8:11], v[32:47]
	v_add_u32_e32 v8, 0x8000, v149
	ds_read_b128 v[8:11], v8 offset:32768
	s_waitcnt lgkmcnt(2)
	v_mfma_f32_32x32x16_bf16 v[16:31], v[56:59], v[0:3], v[16:31]
	v_add_u32_e32 v0, 0x8000, v145
	ds_read_b128 v[0:3], v0 offset:32768
	s_waitcnt lgkmcnt(0)
	v_mfma_f32_32x32x16_bf16 v[32:47], v[56:59], v[0:3], v[32:47]
	v_mfma_f32_32x32x16_bf16 v[16:31], v[60:63], v[4:7], v[16:31]
	ds_read_b128 v[0:3], v144 offset:32768
	ds_read_b128 v[4:7], v147 offset:32768
	v_mfma_f32_32x32x16_bf16 v[32:47], v[60:63], v[8:11], v[32:47]
	v_add_u32_e32 v8, 0x8000, v147
	ds_read_b128 v[8:11], v8 offset:32768
	s_waitcnt lgkmcnt(2)
	v_mfma_f32_32x32x16_bf16 v[16:31], v[64:67], v[0:3], v[16:31]
	v_add_u32_e32 v0, 0x8000, v144
	ds_read_b128 v[0:3], v0 offset:32768
	s_waitcnt lgkmcnt(0)
	v_mfma_f32_32x32x16_bf16 v[32:47], v[64:67], v[0:3], v[32:47]
	v_mfma_f32_32x32x16_bf16 v[16:31], v[68:71], v[4:7], v[16:31]
	ds_read_b128 v[0:3], v143 offset:32768
	ds_read_b128 v[4:7], v146 offset:32768
	v_mfma_f32_32x32x16_bf16 v[32:47], v[68:71], v[8:11], v[32:47]
	v_add_u32_e32 v8, 0x8000, v146
	ds_read_b128 v[8:11], v8 offset:32768
	s_waitcnt lgkmcnt(2)
	v_mfma_f32_32x32x16_bf16 v[16:31], v[72:75], v[0:3], v[16:31]
	v_add_u32_e32 v0, 0x8000, v143
	ds_read_b128 v[0:3], v0 offset:32768
	s_waitcnt lgkmcnt(0)
	v_mfma_f32_32x32x16_bf16 v[32:47], v[72:75], v[0:3], v[32:47]
	v_mfma_f32_32x32x16_bf16 v[16:31], v[76:79], v[4:7], v[16:31]
	v_mfma_f32_32x32x16_bf16 v[32:47], v[76:79], v[8:11], v[32:47]
	v_mfma_f32_32x32x16_bf16 v[0:15], v[64:67], v[80:83], 0
	v_mfma_f32_32x32x16_bf16 v[0:15], v[68:71], v[84:87], v[0:15]
	s_waitcnt vmcnt(16)
	ds_read_b32 v251, v167 offset:256
	v_mul_f32_e32 v151, 0xbfb8aa3b, v173
	v_mul_f32_e32 v93, 0xbfb8aa3b, v174
	s_nop 0
	v_fmamk_f32 v18, v18, 0xbfb8aa3b, v151
	v_fmamk_f32 v19, v19, 0xbfb8aa3b, v151
	v_fmamk_f32 v16, v16, 0xbfb8aa3b, v151
	v_fmamk_f32 v32, v32, 0xbfb8aa3b, v93
	v_fmamk_f32 v17, v17, 0xbfb8aa3b, v151
	v_exp_f32_e32 v18, v18
	v_fmamk_f32 v33, v33, 0xbfb8aa3b, v93
	v_exp_f32_e32 v161, v19
	v_exp_f32_e32 v91, v16
	v_exp_f32_e32 v32, v32
	v_exp_f32_e32 v152, v17
	v_exp_f32_e32 v33, v33
	v_add_f32_e32 v162, 1.0, v18
	v_add_f32_e32 v32, 1.0, v32
	v_add_f32_e32 v91, 1.0, v91
	v_add_f32_e32 v33, 1.0, v33
	v_rcp_f32_e32 v164, v32
	v_rcp_f32_e32 v163, v91
	v_rcp_f32_e32 v166, v33
	v_add_f32_e32 v152, 1.0, v152
	v_rcp_f32_e32 v165, v152
	v_fmamk_f32 v34, v34, 0xbfb8aa3b, v93
	v_exp_f32_e32 v34, v34
	v_fmamk_f32 v36, v36, 0xbfb8aa3b, v93
	v_add_f32_e32 v34, 1.0, v34
	v_exp_f32_e32 v36, v36
	s_nop 1
	s_nop 1
	s_waitcnt lgkmcnt(0)
	v_mul_f32_e32 v33, 0x3fb8aa3b, v251
	v_mul_f32_e32 v16, v163, v33
	v_exp_f32_e32 v32, v16
	v_rcp_f32_e32 v16, v162
	v_mul_f32_e32 v17, v165, v33
	v_fma_f32 v18, -v32, v32, 1.0
	v_sqrt_f32_e32 v18, v18
	v_mul_f32_e32 v16, v16, v33
	v_exp_f32_e32 v91, v17
	v_mul_f32_e32 v18, v164, v18
	v_mul_f32_e32 v18, v0, v18
	v_exp_f32_e32 v0, v16
	v_add_f32_e32 v16, 1.0, v161
	v_rcp_f32_e32 v16, v16
	v_fma_f32 v19, -v91, v91, 1.0
	v_sqrt_f32_e32 v19, v19
	v_rcp_f32_e32 v17, v34
	v_mul_f32_e32 v16, v16, v33
	v_exp_f32_e32 v152, v16
	v_fmamk_f32 v16, v20, 0xbfb8aa3b, v151
	v_mul_f32_e32 v34, v166, v19
	v_fmamk_f32 v19, v35, 0xbfb8aa3b, v93
	v_exp_f32_e32 v16, v16
	v_exp_f32_e32 v19, v19
	v_fma_f32 v20, -v152, v152, 1.0
	v_add_f32_e32 v16, 1.0, v16
	v_rcp_f32_e32 v16, v16
	v_add_f32_e32 v19, 1.0, v19
	v_rcp_f32_e32 v19, v19
	v_sqrt_f32_e32 v20, v20
	v_mul_f32_e32 v16, v16, v33
	v_fma_f32 v35, -v0, v0, 1.0
	v_mul_f32_e32 v153, v19, v20
	v_exp_f32_e32 v20, v16
	v_fmamk_f32 v16, v21, 0xbfb8aa3b, v151
	v_exp_f32_e32 v16, v16
	v_sqrt_f32_e32 v35, v35
	v_fma_f32 v19, -v20, v20, 1.0
	v_fmamk_f32 v21, v37, 0xbfb8aa3b, v93
	v_add_f32_e32 v16, 1.0, v16
	v_rcp_f32_e32 v16, v16
	v_mul_f32_e32 v35, v17, v35
	v_add_f32_e32 v17, 1.0, v36
	v_rcp_f32_e32 v17, v17
	v_mul_f32_e32 v16, v16, v33
	v_exp_f32_e32 v36, v16
	v_fmamk_f32 v16, v22, 0xbfb8aa3b, v151
	v_exp_f32_e32 v16, v16
	v_sqrt_f32_e32 v19, v19
	v_exp_f32_e32 v21, v21
	v_add_f32_e32 v16, 1.0, v16
	v_rcp_f32_e32 v16, v16
	v_mul_f32_e32 v17, v17, v19
	v_mul_f32_e32 v19, v4, v17
	v_add_f32_e32 v4, 1.0, v21
	v_fmamk_f32 v21, v38, 0xbfb8aa3b, v93
	v_mul_f32_e32 v16, v16, v33
	v_fma_f32 v17, -v36, v36, 1.0
	v_exp_f32_e32 v21, v21
	v_rcp_f32_e32 v4, v4
	v_sqrt_f32_e32 v17, v17
	v_exp_f32_e32 v37, v16
	v_add_f32_e32 v16, 1.0, v21
	v_fmamk_f32 v21, v23, 0xbfb8aa3b, v151
	v_mul_f32_e32 v4, v4, v17
	v_fma_f32 v17, -v37, v37, 1.0
	v_rcp_f32_e32 v16, v16
	v_sqrt_f32_e32 v17, v17
	v_exp_f32_e32 v21, v21
	v_fmamk_f32 v22, v39, 0xbfb8aa3b, v93
	v_mul_f32_e32 v23, v16, v17
	v_add_f32_e32 v16, 1.0, v21
	v_rcp_f32_e32 v16, v16
	v_fmamk_f32 v21, v24, 0xbfb8aa3b, v151
	v_exp_f32_e32 v21, v21
	v_mul_f32_e32 v16, v16, v33
	v_exp_f32_e32 v24, v16
	v_add_f32_e32 v16, 1.0, v21
	v_rcp_f32_e32 v16, v16
	v_exp_f32_e32 v22, v22
	v_fmamk_f32 v21, v40, 0xbfb8aa3b, v93
	v_mul_f32_e32 v16, v16, v33
	v_add_f32_e32 v17, 1.0, v22
	v_fma_f32 v22, -v24, v24, 1.0
	v_sqrt_f32_e32 v38, v22
	v_exp_f32_e32 v22, v16
	v_fmamk_f32 v16, v25, 0xbfb8aa3b, v151
	v_exp_f32_e32 v16, v16
	v_exp_f32_e32 v21, v21
	v_fmamk_f32 v39, v41, 0xbfb8aa3b, v93
	v_fma_f32 v25, -v22, v22, 1.0
	v_add_f32_e32 v16, 1.0, v16
	v_rcp_f32_e32 v16, v16
	v_add_f32_e32 v21, 1.0, v21
	v_rcp_f32_e32 v17, v17
	v_rcp_f32_e32 v21, v21
	v_sqrt_f32_e32 v25, v25
	v_exp_f32_e32 v39, v39
	v_mul_f32_e32 v16, v16, v33
	v_mul_f32_e32 v38, v17, v38
	v_mul_f32_e32 v17, v21, v25
	v_add_f32_e32 v21, 1.0, v39
	v_exp_f32_e32 v39, v16
	v_fmamk_f32 v16, v26, 0xbfb8aa3b, v151
	v_exp_f32_e32 v16, v16
	v_rcp_f32_e32 v25, v21
	v_fma_f32 v21, -v39, v39, 1.0
	v_sqrt_f32_e32 v26, v21
	v_add_f32_e32 v16, 1.0, v16
	v_fmamk_f32 v21, v42, 0xbfb8aa3b, v93
	v_rcp_f32_e32 v16, v16
	v_exp_f32_e32 v40, v21
	v_mul_f32_e32 v21, v8, v17
	v_mul_f32_e32 v16, v16, v33
	v_add_f32_e32 v17, 1.0, v40
	v_exp_f32_e32 v40, v16
	v_fmamk_f32 v16, v27, 0xbfb8aa3b, v151
	v_exp_f32_e32 v16, v16
	v_mul_f32_e32 v8, v25, v26
	v_fma_f32 v25, -v40, v40, 1.0
	v_fmamk_f32 v26, v43, 0xbfb8aa3b, v93
	v_add_f32_e32 v16, 1.0, v16
	v_rcp_f32_e32 v16, v16
	v_rcp_f32_e32 v17, v17
	v_sqrt_f32_e32 v25, v25
	v_mul_f32_e32 v16, v16, v33
	v_exp_f32_e32 v26, v26
	v_exp_f32_e32 v41, v16
	v_mul_f32_e32 v154, v17, v25
	v_fmamk_f32 v25, v28, 0xbfb8aa3b, v151
	v_add_f32_e32 v16, 1.0, v26
	v_fmamk_f32 v26, v44, 0xbfb8aa3b, v93
	v_fma_f32 v17, -v41, v41, 1.0
	v_exp_f32_e32 v25, v25
	v_rcp_f32_e32 v16, v16
	v_sqrt_f32_e32 v17, v17
	v_exp_f32_e32 v26, v26
	v_add_f32_e32 v25, 1.0, v25
	v_rcp_f32_e32 v25, v25
	v_mul_f32_e32 v155, v16, v17
	v_add_f32_e32 v16, 1.0, v26
	v_fmamk_f32 v26, v45, 0xbfb8aa3b, v93
	v_exp_f32_e32 v26, v26
	v_rcp_f32_e32 v17, v16
	v_mul_f32_e32 v16, v25, v33
	v_fmamk_f32 v25, v29, 0xbfb8aa3b, v151
	v_exp_f32_e32 v25, v25
	v_add_f32_e32 v26, 1.0, v26
	v_rcp_f32_e32 v42, v26
	v_fmamk_f32 v26, v30, 0xbfb8aa3b, v151
	v_exp_f32_e32 v26, v26
	v_add_f32_e32 v25, 1.0, v25
	v_rcp_f32_e32 v25, v25
	v_fmamk_f32 v27, v46, 0xbfb8aa3b, v93
	v_exp_f32_e32 v27, v27
	v_add_f32_e32 v26, 1.0, v26
	v_rcp_f32_e32 v26, v26
	v_mul_f32_e32 v25, v25, v33
	v_exp_f32_e32 v43, v25
	v_add_f32_e32 v25, 1.0, v27
	v_rcp_f32_e32 v44, v25
	v_mul_f32_e32 v25, v26, v33
	v_fmamk_f32 v26, v31, 0xbfb8aa3b, v151
	v_exp_f32_e32 v26, v26
	v_fmamk_f32 v27, v47, 0xbfb8aa3b, v93
	v_exp_f32_e32 v27, v27
	v_add_f32_e32 v26, 1.0, v26
	v_rcp_f32_e32 v26, v26
	v_exp_f32_e32 v16, v16
	v_fmac_f32_e32 v18, 0, v32
	v_exp_f32_e32 v45, v25
	v_add_f32_e32 v25, 1.0, v27
	v_mul_f32_e32 v31, v91, v18
	v_rcp_f32_e32 v46, v25
	v_mul_f32_e32 v25, v26, v33
	v_fmac_f32_e32 v31, v1, v34
	v_mul_f32_e32 v33, v32, v91
	v_fmac_f32_e32 v19, 0, v20
	v_mul_f32_e32 v30, v0, v31
	v_mul_f32_e32 v34, v0, v33
	v_mul_f32_e32 v28, v36, v19
	v_fma_f32 v0, -v16, v16, 1.0
	v_fmac_f32_e32 v28, v5, v4
	v_sqrt_f32_e32 v1, v0
	v_mul_f32_e32 v27, v37, v28
	v_fmac_f32_e32 v30, v2, v35
	v_fmac_f32_e32 v27, v6, v23
	v_fma_f32 v2, -v43, v43, 1.0
	v_mul_f32_e32 v26, v24, v27
	v_mov_b32_e32 v0, v89
	v_sqrt_f32_e32 v2, v2
	v_fmac_f32_e32 v26, v7, v38
	v_pk_mul_f32 v[6:7], v[16:17], v[0:1]
	v_mul_f32_e32 v29, v152, v30
	v_fmac_f32_e32 v6, v12, v7
	v_fmac_f32_e32 v29, v3, v153
	v_mov_b32_e32 v3, v6
	v_pk_mul_f32 v[4:5], v[42:43], v[2:3]
	v_fma_f32 v0, -v45, v45, 1.0
	v_exp_f32_e32 v47, v25
	v_fmac_f32_e32 v5, v13, v4
	v_sqrt_f32_e32 v4, v0
	v_fmac_f32_e32 v21, 0, v22
	v_mul_f32_e32 v25, v39, v21
	v_mul_f32_e32 v36, v20, v36
	v_fmac_f32_e32 v25, v9, v8
	v_pk_mul_f32 v[8:9], v[44:45], v[4:5]
	v_fma_f32 v0, -v47, v47, 1.0
	v_mul_f32_e32 v37, v37, v36
	v_fmac_f32_e32 v9, v14, v8
	v_sqrt_f32_e32 v8, v0
	ds_bpermute_b32 v0, v140, v29
	v_mul_f32_e32 v38, v24, v37
	v_mul_f32_e32 v24, v40, v25
	v_mul_f32_e32 v35, v152, v34
	v_fmac_f32_e32 v24, v10, v154
	v_mul_f32_e32 v23, v41, v24
	ds_bpermute_b32 v13, v140, v35
	v_fmac_f32_e32 v23, v11, v155
	v_pk_mul_f32 v[10:11], v[46:47], v[8:9]
	s_waitcnt lgkmcnt(1)
	v_cndmask_b32_e64 v14, v29, v0, s[0:1]
	v_fmac_f32_e32 v11, v15, v10
	v_cndmask_b32_e64 v10, v0, v29, s[0:1]
	ds_bpermute_b32 v0, v140, v38
	ds_bpermute_b32 v3, v140, v26
	v_mul_f32_e32 v39, v22, v39
	v_mul_f32_e32 v40, v40, v39
	s_waitcnt lgkmcnt(2)
	v_cndmask_b32_e64 v1, v13, v35, s[0:1]
	v_mul_f32_e32 v12, v41, v40
	v_mul_f32_e32 v7, v16, v43
	v_cndmask_b32_e64 v2, v35, v13, s[0:1]
	v_fmac_f32_e32 v10, 0, v1
	v_mul_f32_e32 v4, v45, v7
	v_mul_f32_e32 v15, v35, v13
	v_fmac_f32_e32 v14, v2, v10
	s_waitcnt lgkmcnt(1)
	v_cndmask_b32_e64 v1, v0, v38, s[0:1]
	s_waitcnt lgkmcnt(0)
	v_cndmask_b32_e64 v17, v3, v26, s[0:1]
	v_cndmask_b32_e64 v41, v26, v3, s[0:1]
	ds_bpermute_b32 v2, v140, v12
	ds_bpermute_b32 v3, v140, v23
	v_mul_f32_e32 v8, v47, v4
	v_cndmask_b32_e64 v0, v38, v0, s[0:1]
	v_mul_f32_e32 v42, v15, v1
	v_fmac_f32_e32 v17, v1, v14
	v_mul_f32_e32 v43, v0, v42
	v_fmac_f32_e32 v41, v0, v17
	ds_bpermute_b32 v1, v140, v8
	ds_bpermute_b32 v0, v140, v11
	s_waitcnt lgkmcnt(3)
	v_cndmask_b32_e64 v47, v2, v12, s[0:1]
	s_waitcnt lgkmcnt(2)
	v_cndmask_b32_e64 v44, v3, v23, s[0:1]
	v_cndmask_b32_e64 v2, v12, v2, s[0:1]
	v_cndmask_b32_e64 v45, v23, v3, s[0:1]
	v_mul_f32_e32 v46, v47, v43
	v_fmac_f32_e32 v44, v47, v41
	v_mul_f32_e32 v47, v2, v46
	v_fmac_f32_e32 v45, v2, v44
	s_waitcnt lgkmcnt(1)
	v_cndmask_b32_e64 v2, v1, v8, s[0:1]
	s_waitcnt lgkmcnt(0)
	v_cndmask_b32_e64 v91, v0, v11, s[0:1]
	v_mul_f32_e32 v93, v2, v47
	v_fmac_f32_e32 v91, v2, v45
	s_and_saveexec_b64 s[8:9], s[0:1]
	v_mul_f32_e32 v3, v91, v1
	v_mul_f32_e32 v2, v93, v1
	v_add_f32_e32 v3, v3, v0
	ds_write_b64 v139, v[2:3] offset:4096
	s_or_b64 exec, exec, s[8:9]
	s_and_b64 vcc, exec, s[6:7]
	s_waitcnt lgkmcnt(0)
	s_barrier
	s_cbranch_vccnz .LBB0_353
	s_cmp_lt_u32 s62, 8
	s_cbranch_scc1 .LBB0_354
	s_add_i32 s9, 16, 0x1000
	s_and_b32 s8, s62, 0x7ffffff8
	v_add3_u32 v151, v141, v138, s9
	v_mov_b32_e32 v0, 1.0
	v_mov_b32_e32 v3, 0
	s_mov_b32 s9, 0

.LBB0_359:
	s_or_b64 exec, exec, s[8:9]
	ds_read_b128 v[0:3], v148 offset:40960
	ds_read_b128 v[4:7], v150 offset:40960
	v_add_u32_e32 v8, 0xa000, v150
	s_waitcnt lgkmcnt(1)
	v_mfma_f32_32x32x16_bf16 v[16:31], v[48:51], v[0:3], 0
	v_add_u32_e32 v0, 0xa000, v148
	ds_read_b128 v[0:3], v0 offset:32768
	ds_read_b128 v[8:11], v8 offset:32768
	s_waitcnt lgkmcnt(1)
	v_mfma_f32_32x32x16_bf16 v[32:47], v[48:51], v[0:3], 0
	v_mfma_f32_32x32x16_bf16 v[16:31], v[52:55], v[4:7], v[16:31]
	ds_read_b128 v[0:3], v145 offset:40960
	ds_read_b128 v[4:7], v149 offset:40960
	s_waitcnt lgkmcnt(2)
	v_mfma_f32_32x32x16_bf16 v[32:47], v[52:55], v[8:11], v[32:47]
	v_add_u32_e32 v8, 0xa000, v149
	ds_read_b128 v[8:11], v8 offset:32768
	s_waitcnt lgkmcnt(2)
	v_mfma_f32_32x32x16_bf16 v[16:31], v[56:59], v[0:3], v[16:31]
	v_add_u32_e32 v0, 0xa000, v145
	ds_read_b128 v[0:3], v0 offset:32768
	s_waitcnt lgkmcnt(0)
	v_mfma_f32_32x32x16_bf16 v[32:47], v[56:59], v[0:3], v[32:47]
	v_mfma_f32_32x32x16_bf16 v[16:31], v[60:63], v[4:7], v[16:31]
	ds_read_b128 v[0:3], v144 offset:40960
	ds_read_b128 v[4:7], v147 offset:40960
	v_mfma_f32_32x32x16_bf16 v[32:47], v[60:63], v[8:11], v[32:47]
	v_add_u32_e32 v8, 0xa000, v147
	ds_read_b128 v[8:11], v8 offset:32768
	s_waitcnt lgkmcnt(2)
	v_mfma_f32_32x32x16_bf16 v[16:31], v[64:67], v[0:3], v[16:31]
	v_add_u32_e32 v0, 0xa000, v144
	ds_read_b128 v[0:3], v0 offset:32768
	s_waitcnt lgkmcnt(0)
	v_mfma_f32_32x32x16_bf16 v[32:47], v[64:67], v[0:3], v[32:47]
	v_mfma_f32_32x32x16_bf16 v[16:31], v[68:71], v[4:7], v[16:31]
	ds_read_b128 v[0:3], v143 offset:40960
	ds_read_b128 v[4:7], v146 offset:40960
	v_mfma_f32_32x32x16_bf16 v[32:47], v[68:71], v[8:11], v[32:47]
	v_add_u32_e32 v8, 0xa000, v146
	ds_read_b128 v[8:11], v8 offset:32768
	s_waitcnt lgkmcnt(2)
	v_mfma_f32_32x32x16_bf16 v[16:31], v[72:75], v[0:3], v[16:31]
	v_add_u32_e32 v0, 0xa000, v143
	ds_read_b128 v[0:3], v0 offset:32768
	s_waitcnt lgkmcnt(0)
	v_mfma_f32_32x32x16_bf16 v[32:47], v[72:75], v[0:3], v[32:47]
	v_mfma_f32_32x32x16_bf16 v[16:31], v[76:79], v[4:7], v[16:31]
	v_mfma_f32_32x32x16_bf16 v[32:47], v[76:79], v[8:11], v[32:47]
	v_mfma_f32_32x32x16_bf16 v[0:15], v[72:75], v[80:83], 0
	v_mfma_f32_32x32x16_bf16 v[0:15], v[76:79], v[84:87], v[0:15]
	s_waitcnt vmcnt(16)
	ds_read_b32 v251, v167 offset:384
	v_mul_f32_e32 v49, 0xbfb8aa3b, v173
	v_mul_f32_e32 v48, 0xbfb8aa3b, v174
	s_nop 0
	v_fmamk_f32 v18, v18, 0xbfb8aa3b, v49
	v_fmamk_f32 v19, v19, 0xbfb8aa3b, v49
	v_fmamk_f32 v16, v16, 0xbfb8aa3b, v49
	v_fmamk_f32 v32, v32, 0xbfb8aa3b, v48
	v_fmamk_f32 v17, v17, 0xbfb8aa3b, v49
	v_exp_f32_e32 v18, v18
	v_fmamk_f32 v33, v33, 0xbfb8aa3b, v48
	v_exp_f32_e32 v59, v19
	v_exp_f32_e32 v50, v16
	v_exp_f32_e32 v32, v32
	v_exp_f32_e32 v51, v17
	v_exp_f32_e32 v33, v33
	v_add_f32_e32 v60, 1.0, v18
	v_add_f32_e32 v32, 1.0, v32
	v_add_f32_e32 v50, 1.0, v50
	v_add_f32_e32 v33, 1.0, v33
	v_rcp_f32_e32 v62, v32
	v_rcp_f32_e32 v61, v50
	v_rcp_f32_e32 v64, v33
	v_add_f32_e32 v51, 1.0, v51
	v_rcp_f32_e32 v63, v51
	v_fmamk_f32 v34, v34, 0xbfb8aa3b, v48
	v_exp_f32_e32 v34, v34
	v_fmamk_f32 v36, v36, 0xbfb8aa3b, v48
	v_add_f32_e32 v34, 1.0, v34
	v_exp_f32_e32 v36, v36
	s_nop 1
	s_nop 1
	s_waitcnt lgkmcnt(0)
	v_mul_f32_e32 v33, 0x3fb8aa3b, v251
	v_mul_f32_e32 v16, v61, v33
	v_exp_f32_e32 v32, v16
	v_rcp_f32_e32 v16, v60
	v_mul_f32_e32 v17, v63, v33
	v_fma_f32 v18, -v32, v32, 1.0
	v_sqrt_f32_e32 v18, v18
	v_mul_f32_e32 v16, v16, v33
	v_exp_f32_e32 v50, v17
	v_mul_f32_e32 v18, v62, v18
	v_mul_f32_e32 v18, v0, v18
	v_exp_f32_e32 v0, v16
	v_add_f32_e32 v16, 1.0, v59
	v_rcp_f32_e32 v16, v16
	v_fma_f32 v19, -v50, v50, 1.0
	v_sqrt_f32_e32 v19, v19
	v_rcp_f32_e32 v17, v34
	v_mul_f32_e32 v16, v16, v33
	v_exp_f32_e32 v51, v16
	v_fmamk_f32 v16, v20, 0xbfb8aa3b, v49
	v_mul_f32_e32 v34, v64, v19
	v_fmamk_f32 v19, v35, 0xbfb8aa3b, v48
	v_exp_f32_e32 v16, v16
	v_exp_f32_e32 v19, v19
	v_fma_f32 v20, -v51, v51, 1.0
	v_add_f32_e32 v16, 1.0, v16
	v_rcp_f32_e32 v16, v16
	v_add_f32_e32 v19, 1.0, v19
	v_rcp_f32_e32 v19, v19
	v_sqrt_f32_e32 v20, v20
	v_mul_f32_e32 v16, v16, v33
	v_fma_f32 v35, -v0, v0, 1.0
	v_mul_f32_e32 v52, v19, v20
	v_exp_f32_e32 v20, v16
	v_fmamk_f32 v16, v21, 0xbfb8aa3b, v49
	v_exp_f32_e32 v16, v16
	v_sqrt_f32_e32 v35, v35
	v_fma_f32 v19, -v20, v20, 1.0
	v_fmamk_f32 v21, v37, 0xbfb8aa3b, v48
	v_add_f32_e32 v16, 1.0, v16
	v_rcp_f32_e32 v16, v16
	v_mul_f32_e32 v35, v17, v35
	v_add_f32_e32 v17, 1.0, v36
	v_rcp_f32_e32 v17, v17
	v_mul_f32_e32 v16, v16, v33
	v_exp_f32_e32 v36, v16
	v_fmamk_f32 v16, v22, 0xbfb8aa3b, v49
	v_exp_f32_e32 v16, v16
	v_sqrt_f32_e32 v19, v19
	v_exp_f32_e32 v21, v21
	v_add_f32_e32 v16, 1.0, v16
	v_rcp_f32_e32 v16, v16
	v_mul_f32_e32 v17, v17, v19
	v_mul_f32_e32 v19, v4, v17
	v_add_f32_e32 v4, 1.0, v21
	v_fmamk_f32 v21, v38, 0xbfb8aa3b, v48
	v_mul_f32_e32 v16, v16, v33
	v_fma_f32 v17, -v36, v36, 1.0
	v_exp_f32_e32 v21, v21
	v_rcp_f32_e32 v4, v4
	v_sqrt_f32_e32 v17, v17
	v_exp_f32_e32 v37, v16
	v_add_f32_e32 v16, 1.0, v21
	v_fmamk_f32 v21, v23, 0xbfb8aa3b, v49
	v_mul_f32_e32 v4, v4, v17
	v_fma_f32 v17, -v37, v37, 1.0
	v_rcp_f32_e32 v16, v16
	v_sqrt_f32_e32 v17, v17
	v_exp_f32_e32 v21, v21
	v_fmamk_f32 v22, v39, 0xbfb8aa3b, v48
	v_mul_f32_e32 v23, v16, v17
	v_add_f32_e32 v16, 1.0, v21
	v_rcp_f32_e32 v16, v16
	v_fmamk_f32 v21, v24, 0xbfb8aa3b, v49
	v_exp_f32_e32 v21, v21
	v_mul_f32_e32 v16, v16, v33
	v_exp_f32_e32 v24, v16
	v_add_f32_e32 v16, 1.0, v21
	v_rcp_f32_e32 v16, v16
	v_exp_f32_e32 v22, v22
	v_fmamk_f32 v21, v40, 0xbfb8aa3b, v48
	v_mul_f32_e32 v16, v16, v33
	v_add_f32_e32 v17, 1.0, v22
	v_fma_f32 v22, -v24, v24, 1.0
	v_sqrt_f32_e32 v38, v22
	v_exp_f32_e32 v22, v16
	v_fmamk_f32 v16, v25, 0xbfb8aa3b, v49
	v_exp_f32_e32 v16, v16
	v_exp_f32_e32 v21, v21
	v_fmamk_f32 v39, v41, 0xbfb8aa3b, v48
	v_fma_f32 v25, -v22, v22, 1.0
	v_add_f32_e32 v16, 1.0, v16
	v_rcp_f32_e32 v16, v16
	v_add_f32_e32 v21, 1.0, v21
	v_rcp_f32_e32 v17, v17
	v_rcp_f32_e32 v21, v21
	v_sqrt_f32_e32 v25, v25
	v_exp_f32_e32 v39, v39
	v_mul_f32_e32 v16, v16, v33
	v_mul_f32_e32 v38, v17, v38
	v_mul_f32_e32 v17, v21, v25
	v_add_f32_e32 v21, 1.0, v39
	v_exp_f32_e32 v39, v16
	v_fmamk_f32 v16, v26, 0xbfb8aa3b, v49
	v_exp_f32_e32 v16, v16
	v_rcp_f32_e32 v25, v21
	v_fma_f32 v21, -v39, v39, 1.0
	v_sqrt_f32_e32 v26, v21
	v_add_f32_e32 v16, 1.0, v16
	v_fmamk_f32 v21, v42, 0xbfb8aa3b, v48
	v_rcp_f32_e32 v16, v16
	v_exp_f32_e32 v40, v21
	v_mul_f32_e32 v21, v8, v17
	v_mul_f32_e32 v16, v16, v33
	v_add_f32_e32 v17, 1.0, v40
	v_exp_f32_e32 v40, v16
	v_fmamk_f32 v16, v27, 0xbfb8aa3b, v49
	v_exp_f32_e32 v16, v16
	v_mul_f32_e32 v8, v25, v26
	v_fma_f32 v25, -v40, v40, 1.0
	v_fmamk_f32 v26, v43, 0xbfb8aa3b, v48
	v_add_f32_e32 v16, 1.0, v16
	v_rcp_f32_e32 v16, v16
	v_rcp_f32_e32 v17, v17
	v_sqrt_f32_e32 v25, v25
	v_mul_f32_e32 v16, v16, v33
	v_exp_f32_e32 v26, v26
	v_exp_f32_e32 v41, v16
	v_mul_f32_e32 v53, v17, v25
	v_fmamk_f32 v25, v28, 0xbfb8aa3b, v49
	v_add_f32_e32 v16, 1.0, v26
	v_fmamk_f32 v26, v44, 0xbfb8aa3b, v48
	v_fma_f32 v17, -v41, v41, 1.0
	v_exp_f32_e32 v25, v25
	v_rcp_f32_e32 v16, v16
	v_sqrt_f32_e32 v17, v17
	v_exp_f32_e32 v26, v26
	v_add_f32_e32 v25, 1.0, v25
	v_rcp_f32_e32 v25, v25
	v_mul_f32_e32 v54, v16, v17
	v_add_f32_e32 v16, 1.0, v26
	v_fmamk_f32 v26, v45, 0xbfb8aa3b, v48
	v_exp_f32_e32 v26, v26
	v_rcp_f32_e32 v17, v16
	v_mul_f32_e32 v16, v25, v33
	v_fmamk_f32 v25, v29, 0xbfb8aa3b, v49
	v_exp_f32_e32 v25, v25
	v_add_f32_e32 v26, 1.0, v26
	v_rcp_f32_e32 v42, v26
	v_fmamk_f32 v26, v30, 0xbfb8aa3b, v49
	v_exp_f32_e32 v26, v26
	v_add_f32_e32 v25, 1.0, v25
	v_rcp_f32_e32 v25, v25
	v_fmamk_f32 v27, v46, 0xbfb8aa3b, v48
	v_exp_f32_e32 v27, v27
	v_add_f32_e32 v26, 1.0, v26
	v_rcp_f32_e32 v26, v26
	v_mul_f32_e32 v25, v25, v33
	v_exp_f32_e32 v43, v25
	v_add_f32_e32 v25, 1.0, v27
	v_rcp_f32_e32 v44, v25
	v_mul_f32_e32 v25, v26, v33
	v_fmamk_f32 v26, v31, 0xbfb8aa3b, v49
	v_exp_f32_e32 v26, v26
	v_fmamk_f32 v27, v47, 0xbfb8aa3b, v48
	v_exp_f32_e32 v27, v27
	v_add_f32_e32 v26, 1.0, v26
	v_rcp_f32_e32 v26, v26
	v_exp_f32_e32 v16, v16
	v_fmac_f32_e32 v18, 0, v32
	v_exp_f32_e32 v45, v25
	v_add_f32_e32 v25, 1.0, v27
	v_mul_f32_e32 v31, v50, v18
	v_rcp_f32_e32 v46, v25
	v_mul_f32_e32 v25, v26, v33
	v_fmac_f32_e32 v31, v1, v34
	v_mul_f32_e32 v33, v32, v50
	v_fmac_f32_e32 v19, 0, v20
	v_mul_f32_e32 v30, v0, v31
	v_mul_f32_e32 v34, v0, v33
	v_mul_f32_e32 v28, v36, v19
	v_fma_f32 v0, -v16, v16, 1.0
	v_fmac_f32_e32 v28, v5, v4
	v_sqrt_f32_e32 v1, v0
	v_mul_f32_e32 v27, v37, v28
	v_fmac_f32_e32 v30, v2, v35
	v_fmac_f32_e32 v27, v6, v23
	v_fma_f32 v2, -v43, v43, 1.0
	v_mul_f32_e32 v26, v24, v27
	v_mov_b32_e32 v0, v89
	v_sqrt_f32_e32 v2, v2
	v_fmac_f32_e32 v26, v7, v38
	v_pk_mul_f32 v[6:7], v[16:17], v[0:1]
	v_mul_f32_e32 v29, v51, v30
	v_fmac_f32_e32 v6, v12, v7
	v_fmac_f32_e32 v29, v3, v52
	v_mov_b32_e32 v3, v6
	v_pk_mul_f32 v[4:5], v[42:43], v[2:3]
	v_fma_f32 v0, -v45, v45, 1.0
	v_exp_f32_e32 v47, v25
	v_fmac_f32_e32 v5, v13, v4
	v_sqrt_f32_e32 v4, v0
	v_fmac_f32_e32 v21, 0, v22
	v_mul_f32_e32 v25, v39, v21
	v_mul_f32_e32 v36, v20, v36
	v_fmac_f32_e32 v25, v9, v8
	v_pk_mul_f32 v[8:9], v[44:45], v[4:5]
	v_fma_f32 v0, -v47, v47, 1.0
	v_mul_f32_e32 v37, v37, v36
	v_fmac_f32_e32 v9, v14, v8
	v_sqrt_f32_e32 v8, v0
	ds_bpermute_b32 v0, v140, v29
	v_mul_f32_e32 v38, v24, v37
	v_mul_f32_e32 v24, v40, v25
	v_mul_f32_e32 v35, v51, v34
	v_fmac_f32_e32 v24, v10, v53
	v_mul_f32_e32 v23, v41, v24
	ds_bpermute_b32 v13, v140, v35
	v_fmac_f32_e32 v23, v11, v54
	v_pk_mul_f32 v[10:11], v[46:47], v[8:9]
	s_waitcnt lgkmcnt(1)
	v_cndmask_b32_e64 v14, v29, v0, s[0:1]
	v_fmac_f32_e32 v11, v15, v10
	v_cndmask_b32_e64 v10, v0, v29, s[0:1]
	ds_bpermute_b32 v0, v140, v38
	ds_bpermute_b32 v3, v140, v26
	v_mul_f32_e32 v39, v22, v39
	v_mul_f32_e32 v40, v40, v39
	s_waitcnt lgkmcnt(2)
	v_cndmask_b32_e64 v1, v13, v35, s[0:1]
	v_mul_f32_e32 v12, v41, v40
	v_mul_f32_e32 v7, v16, v43
	v_cndmask_b32_e64 v2, v35, v13, s[0:1]
	v_fmac_f32_e32 v10, 0, v1
	v_mul_f32_e32 v4, v45, v7
	v_mul_f32_e32 v15, v35, v13
	v_fmac_f32_e32 v14, v2, v10
	s_waitcnt lgkmcnt(1)
	v_cndmask_b32_e64 v1, v0, v38, s[0:1]
	s_waitcnt lgkmcnt(0)
	v_cndmask_b32_e64 v17, v3, v26, s[0:1]
	v_cndmask_b32_e64 v41, v26, v3, s[0:1]
	ds_bpermute_b32 v2, v140, v12
	ds_bpermute_b32 v3, v140, v23
	v_mul_f32_e32 v8, v47, v4
	v_cndmask_b32_e64 v0, v38, v0, s[0:1]
	v_mul_f32_e32 v42, v15, v1
	v_fmac_f32_e32 v17, v1, v14
	v_mul_f32_e32 v43, v0, v42
	v_fmac_f32_e32 v41, v0, v17
	ds_bpermute_b32 v1, v140, v8
	ds_bpermute_b32 v0, v140, v11
	s_waitcnt lgkmcnt(3)
	v_cndmask_b32_e64 v47, v2, v12, s[0:1]
	s_waitcnt lgkmcnt(2)
	v_cndmask_b32_e64 v44, v3, v23, s[0:1]
	v_cndmask_b32_e64 v2, v12, v2, s[0:1]
	v_cndmask_b32_e64 v45, v23, v3, s[0:1]
	v_mul_f32_e32 v46, v47, v43
	v_fmac_f32_e32 v44, v47, v41
	v_mul_f32_e32 v47, v2, v46
	v_fmac_f32_e32 v45, v2, v44
	s_waitcnt lgkmcnt(1)
	v_cndmask_b32_e64 v2, v1, v8, s[0:1]
	s_waitcnt lgkmcnt(0)
	v_cndmask_b32_e64 v48, v0, v11, s[0:1]
	v_mul_f32_e32 v49, v2, v47
	v_fmac_f32_e32 v48, v2, v45
	s_and_saveexec_b64 s[8:9], s[0:1]
	v_mul_f32_e32 v3, v48, v1
	v_mul_f32_e32 v2, v49, v1
	v_add_f32_e32 v3, v3, v0
	ds_write_b64 v139, v[2:3] offset:6144
	s_or_b64 exec, exec, s[8:9]
	s_and_b64 vcc, exec, s[6:7]
	s_waitcnt lgkmcnt(0)
	s_barrier
	s_cbranch_vccnz .LBB0_366
	s_cmp_lt_u32 s62, 8
	s_cbranch_scc1 .LBB0_367
	s_and_b32 s6, s62, 0x7ffffff8
	v_add3_u32 v50, v141, v138, s88
	v_mov_b32_e32 v0, 1.0
	v_mov_b32_e32 v3, 0
	s_mov_b32 s7, 0
